# silu gate chains: removed a dead v_div_scale and its wait state per element (result was overwritten by v_rcp)
# speedup vs baseline: 1.0023x; 1.0009x over previous
; #define LAS __attribute__((address_space(3)))
; #define LDS_WAIT() asm volatile("s_waitcnt lgkmcnt(0)" ::: "memory")
; DI float bflo(unsigned w) { return __uint_as_float(w << 16); }
; DI float bfhi(unsigned w) { return __uint_as_float(w & 0xffff0000u); }
; DI void branch_fold(ASt& st, float gate, bool may_be_empty, LAS float* wsf, int lane) {
;     ...
;     LDS_WAIT();
; #pragma unroll
;     for (int g4 = 0; g4 < 4; ++g4) { const f32x4 f = *(const LAS f32x4*)(wsf + 8 * g4 + 4 * hi);
; #pragma unroll
;         for (int k = 0; k < 4; ++k) { st.o0[4 * g4 + k] *= f[k]; st.o1[4 * g4 + k] *= f[k]; } }
; DI void nsa_unit(const Ctx& c0, int b, int g, int i, LAS unsigned char* lds) {
;     ...
;         branch_fold(st, g_w2, false, wsf, lane);
; #pragma unroll
;         for (int rg = 0; rg < 16; ++rg) { const unsigned w = OC[rg * 64]; ca0[rg] = (OACC[rg * 64] + st.o0[rg]) + bflo(w); ca1[rg] = (OACC[(16 + rg) * 64] + st.o1[rg]) + bfhi(w); }
;         __syncthreads();
;     }
;     ...
;     { const size_t g0 = ((size_t)b * SEQ + i * 64 + 32 * qh) * 512 + head * 64;
;       const bf16* nzg = (const bf16*)(c.ws + O_NZ) + g0; bf16* ong = (bf16*)(c.ws + O_ONSA) + g0;
;       LAS unsigned char* S = lds + A_OC + wid * 4096;
; #pragma unroll
;       for (int it = 0; it < 4; ++it) { const int rw = 8 * it + (lane >> 3), ch = lane & 7;
;           *(LAS u32x4*)(S + rw * 128 + ch * 16) = *(const u32x4*)(nzg + (size_t)rw * 512 + ch * 8); }
.LBB0_540:
	s_or_b64 exec, exec, s[12:13]
	s_or_b32 s3, s24, s33
	s_add_u32 s12, s8, s3
	s_addc_u32 s13, s9, 0
	s_lshl_b64 s[12:13], s[12:13], 9
	s_add_u32 s12, s12, s20
	s_addc_u32 s13, s13, 0
	s_lshl_b64 s[12:13], s[12:13], 1
	s_add_u32 s0, s0, s12
	s_addc_u32 s1, s1, s13
	v_mov_b32_e32 v135, v3
	v_lshl_add_u64 v[246:247], s[0:1], 0, v[134:135]
	s_mov_b64 s[98:99], 0xb500000
	v_lshl_add_u64 v[246:247], v[246:247], 0, s[98:99]
	v_lshl_add_u64 v[248:249], v[246:247], 0, v[126:127]
	global_load_dwordx4 v[230:233], v[248:249], off
	v_lshl_add_u64 v[248:249], v[246:247], 0, v[128:129]
	global_load_dwordx4 v[234:237], v[248:249], off
	v_lshl_add_u64 v[248:249], v[246:247], 0, v[130:131]
	global_load_dwordx4 v[238:241], v[248:249], off
	v_lshl_add_u64 v[248:249], v[246:247], 0, v[132:133]
	global_load_dwordx4 v[242:245], v[248:249], off
	s_waitcnt lgkmcnt(0)
	ds_read_b128 v[48:51], v205 offset:32768
	ds_read_b128 v[44:47], v205 offset:32800
	ds_read_b128 v[40:43], v205 offset:32832
	ds_read_b128 v[36:39], v205 offset:32864
	ds_read2st64_b32 v[52:53], v203 offset1:1
	ds_read2st64_b32 v[54:55], v214 offset0:144 offset1:145
	ds_read2st64_b32 v[56:57], v214 offset0:160 offset1:161
	s_waitcnt lgkmcnt(0)
	v_lshlrev_b32_e32 v2, 16, v52
	v_fma_f32 v1, v20, v48, v54
	v_add_f32_e32 v60, v1, v2
	v_fma_f32 v1, v4, v48, v56
	v_fmac_f32_e32 v55, v21, v49
	v_fmac_f32_e32 v57, v5, v49
	ds_read2st64_b32 v[4:5], v203 offset0:2 offset1:3
	ds_read2st64_b32 v[20:21], v214 offset0:146 offset1:147
	ds_read2st64_b32 v[48:49], v214 offset0:162 offset1:163
	v_and_b32_e32 v2, 0xffff0000, v52
	v_add_f32_e32 v59, v1, v2
	v_lshlrev_b32_e32 v1, 16, v53
	v_add_f32_e32 v58, v55, v1
	v_and_b32_e32 v1, 0xffff0000, v53
	v_add_f32_e32 v57, v57, v1
	s_waitcnt lgkmcnt(0)
	v_fma_f32 v1, v22, v50, v20
	v_lshlrev_b32_e32 v2, 16, v4
	v_add_f32_e32 v56, v1, v2
	v_fma_f32 v1, v6, v50, v48
	v_and_b32_e32 v2, 0xffff0000, v4
	v_add_f32_e32 v55, v1, v2
	v_fmac_f32_e32 v21, v23, v51
	v_lshlrev_b32_e32 v1, 16, v5
	v_add_f32_e32 v54, v21, v1
	v_fmac_f32_e32 v49, v7, v51
	v_and_b32_e32 v1, 0xffff0000, v5
	ds_read2st64_b32 v[4:5], v203 offset0:4 offset1:5
	ds_read2st64_b32 v[6:7], v214 offset0:148 offset1:149
	ds_read2st64_b32 v[20:21], v214 offset0:164 offset1:165
	v_add_f32_e32 v53, v49, v1
	s_waitcnt lgkmcnt(0)
	v_lshlrev_b32_e32 v2, 16, v4
	v_fma_f32 v1, v24, v44, v6
	v_add_f32_e32 v52, v1, v2
	v_fma_f32 v1, v8, v44, v20
	v_and_b32_e32 v2, 0xffff0000, v4
	v_add_f32_e32 v51, v1, v2
	v_fmac_f32_e32 v7, v25, v45
	v_lshlrev_b32_e32 v1, 16, v5
	v_add_f32_e32 v50, v7, v1
	v_and_b32_e32 v1, 0xffff0000, v5
	ds_read2st64_b32 v[4:5], v203 offset0:6 offset1:7
	ds_read2st64_b32 v[6:7], v214 offset0:150 offset1:151
	v_fmac_f32_e32 v21, v9, v45
	ds_read2st64_b32 v[8:9], v214 offset0:166 offset1:167
	v_add_f32_e32 v49, v21, v1
	s_waitcnt lgkmcnt(0)
	v_lshlrev_b32_e32 v2, 16, v4
	v_fma_f32 v1, v26, v46, v6
	v_add_f32_e32 v48, v1, v2
	v_fma_f32 v1, v10, v46, v8
	v_and_b32_e32 v2, 0xffff0000, v4
	v_add_f32_e32 v46, v1, v2
	v_fmac_f32_e32 v7, v27, v47
	v_lshlrev_b32_e32 v1, 16, v5
	v_add_f32_e32 v45, v7, v1
	v_fmac_f32_e32 v9, v11, v47
	v_and_b32_e32 v1, 0xffff0000, v5
	ds_read2st64_b32 v[4:5], v203 offset0:8 offset1:9
	ds_read2st64_b32 v[6:7], v214 offset0:152 offset1:153
	v_add_f32_e32 v44, v9, v1
	ds_read2st64_b32 v[8:9], v214 offset0:168 offset1:169
	s_waitcnt lgkmcnt(0)
	v_lshlrev_b32_e32 v2, 16, v4
	v_fma_f32 v1, v28, v40, v6
	v_add_f32_e32 v27, v1, v2
	v_fma_f32 v1, v12, v40, v8
	v_and_b32_e32 v2, 0xffff0000, v4
	v_add_f32_e32 v26, v1, v2
	v_fmac_f32_e32 v7, v29, v41
	v_lshlrev_b32_e32 v1, 16, v5
	v_add_f32_e32 v25, v7, v1
	v_fmac_f32_e32 v9, v13, v41
	v_and_b32_e32 v1, 0xffff0000, v5
	ds_read2st64_b32 v[4:5], v203 offset0:10 offset1:11
	ds_read2st64_b32 v[6:7], v214 offset0:154 offset1:155
	v_add_f32_e32 v24, v9, v1
	ds_read2st64_b32 v[8:9], v214 offset0:170 offset1:171
	s_waitcnt lgkmcnt(0)
	v_lshlrev_b32_e32 v2, 16, v4
	v_fma_f32 v1, v30, v42, v6
	v_add_f32_e32 v23, v1, v2
	v_fma_f32 v1, v14, v42, v8
	v_and_b32_e32 v2, 0xffff0000, v4
	v_add_f32_e32 v22, v1, v2
	v_fmac_f32_e32 v7, v31, v43
	v_lshlrev_b32_e32 v1, 16, v5
	v_add_f32_e32 v21, v7, v1
	v_fmac_f32_e32 v9, v15, v43
	v_and_b32_e32 v1, 0xffff0000, v5
	ds_read2st64_b32 v[4:5], v203 offset0:12 offset1:13
	ds_read2st64_b32 v[6:7], v214 offset0:156 offset1:157
	v_add_f32_e32 v15, v9, v1
	ds_read2st64_b32 v[8:9], v214 offset0:172 offset1:173
	s_waitcnt lgkmcnt(0)
	v_lshlrev_b32_e32 v2, 16, v4
	v_fma_f32 v1, v32, v36, v6
	v_add_f32_e32 v20, v1, v2
	v_fma_f32 v1, v16, v36, v8
	v_and_b32_e32 v2, 0xffff0000, v4
	v_add_f32_e32 v14, v1, v2
	v_fmac_f32_e32 v7, v33, v37
	v_lshlrev_b32_e32 v1, 16, v5
	v_add_f32_e32 v13, v7, v1
	v_fmac_f32_e32 v9, v17, v37
	v_and_b32_e32 v1, 0xffff0000, v5
	ds_read2st64_b32 v[4:5], v203 offset0:14 offset1:15
	ds_read2st64_b32 v[6:7], v214 offset0:158 offset1:159
	v_add_f32_e32 v12, v9, v1
	ds_read2st64_b32 v[8:9], v214 offset0:174 offset1:175
	s_waitcnt lgkmcnt(0)
	v_lshlrev_b32_e32 v2, 16, v4
	v_fma_f32 v1, v34, v38, v6
	v_add_f32_e32 v10, v1, v2
	v_fma_f32 v1, v18, v38, v8
	v_and_b32_e32 v2, 0xffff0000, v4
	v_add_f32_e32 v11, v1, v2
	v_fmac_f32_e32 v7, v35, v39
	v_lshlrev_b32_e32 v1, 16, v5
	v_add_f32_e32 v2, v7, v1
	v_fmac_f32_e32 v9, v19, v39
	v_and_b32_e32 v1, 0xffff0000, v5
	v_mov_b32_e32 v135, v3
	v_add_f32_e32 v1, v9, v1
	v_lshl_add_u64 v[8:9], s[0:1], 0, v[134:135]
	s_mov_b64 s[0:1], 0xb500000
	v_lshl_add_u64 v[16:17], v[8:9], 0, s[0:1]
	v_lshl_add_u64 v[4:5], v[16:17], 0, v[126:127]
	s_barrier
; #define LAS __attribute__((address_space(3)))
; #define LDS_WAIT() asm volatile("s_waitcnt lgkmcnt(0)" ::: "memory")
; DI unsigned cvtpk(float lo, float hi) { f32x2 v = {lo, hi}; bf16x2_t b = __builtin_convertvector(v, bf16x2_t); return __builtin_bit_cast(unsigned, b); }
; DI float bf2f(bf16 b) { return __uint_as_float(((unsigned)b) << 16); }
; DI float siluf_(float x) { return x / (1.f + __expf(-x)); }
; DI void nsa_unit(const Ctx& c0, int b, int g, int i, LAS unsigned char* lds) {
;     ...
;       LDS_WAIT();
; #pragma unroll
;       for (int rg = 0; rg < 16; ++rg) { LAS bf16* e = (LAS bf16*)(S + ((rg & 3) + 8 * (rg >> 2) + 4 * hi) * 128 + r * 2);
;           const float z0 = bf2f(e[0]), z1 = bf2f(e[32]);
;           e[0] = (bf16)(cvtpk(ca0[rg] * siluf_(z0), 0.f) & 0xffffu);
;           e[32] = (bf16)(cvtpk(ca1[rg] * siluf_(z1), 0.f) & 0xffffu); }
;       LDS_WAIT();
	s_add_i32 s23, s23, 1
	s_cmp_eq_u32 s23, 4
	s_waitcnt vmcnt(0) lgkmcnt(0)
	ds_write_b128 v216, v[230:233]
	ds_write_b128 v217, v[234:237]
	ds_write_b128 v218, v[238:241]
	ds_write_b128 v219, v[242:245]
	s_waitcnt lgkmcnt(0)
	ds_read_u16 v4, v220
	ds_read_u16 v5, v220 offset:64
	s_waitcnt lgkmcnt(1)
	v_lshlrev_b32_e32 v4, 16, v4
	v_mul_f32_e32 v6, 0xbfb8aa3b, v4
	v_exp_f32_e32 v6, v6
	s_waitcnt lgkmcnt(0)
	v_lshlrev_b32_e32 v5, 16, v5
	v_add_f32_e32 v6, 1.0, v6
	v_rcp_f32_e32 v7, v6
	s_nop 0
	v_mul_f32_e32 v4, v4, v7
	v_mul_f32_e32 v4, v60, v4
	v_cvt_pk_bf16_f32 v4, v4, v4
	ds_write_b16 v220, v4
	v_mul_f32_e32 v4, 0xbfb8aa3b, v5
	v_exp_f32_e32 v4, v4
	s_nop 0
	v_add_f32_e32 v4, 1.0, v4
	v_div_scale_f32 v6, s[0:1], v4, v4, v5
	s_nop 0
	v_rcp_f32_e32 v4, v4
	s_nop 0
	v_mul_f32_e32 v4, v5, v4
	v_mul_f32_e32 v4, v59, v4
	v_cvt_pk_bf16_f32 v4, v4, s0
	ds_write_b16 v220, v4 offset:64
	ds_read_u16 v4, v220 offset:128
	ds_read_u16 v5, v220 offset:192
	s_waitcnt lgkmcnt(1)
	v_lshlrev_b32_e32 v4, 16, v4
	v_mul_f32_e32 v6, 0xbfb8aa3b, v4
	v_exp_f32_e32 v6, v6
	s_waitcnt lgkmcnt(0)
	v_lshlrev_b32_e32 v5, 16, v5
	v_add_f32_e32 v6, 1.0, v6
	v_rcp_f32_e32 v7, v6
	s_nop 0
	v_mul_f32_e32 v4, v4, v7
	v_mul_f32_e32 v4, v58, v4
	v_cvt_pk_bf16_f32 v4, v4, v4
	ds_write_b16 v220, v4 offset:128
	v_mul_f32_e32 v4, 0xbfb8aa3b, v5
	v_exp_f32_e32 v4, v4
	s_nop 0
	v_add_f32_e32 v4, 1.0, v4
	v_div_scale_f32 v6, s[0:1], v4, v4, v5
	s_nop 0
	v_rcp_f32_e32 v4, v4
	s_nop 0
	v_mul_f32_e32 v4, v5, v4
	v_mul_f32_e32 v4, v57, v4
	v_cvt_pk_bf16_f32 v4, v4, s0
	ds_write_b16 v220, v4 offset:192
	ds_read_u16 v4, v220 offset:256
	ds_read_u16 v5, v220 offset:320
	s_waitcnt lgkmcnt(1)
	v_lshlrev_b32_e32 v4, 16, v4
	v_mul_f32_e32 v6, 0xbfb8aa3b, v4
	v_exp_f32_e32 v6, v6
	s_waitcnt lgkmcnt(0)
	v_lshlrev_b32_e32 v5, 16, v5
	v_add_f32_e32 v6, 1.0, v6
	v_rcp_f32_e32 v7, v6
	s_nop 0
	v_mul_f32_e32 v4, v4, v7
	v_mul_f32_e32 v4, v56, v4
	v_cvt_pk_bf16_f32 v4, v4, v4
	ds_write_b16 v220, v4 offset:256
	v_mul_f32_e32 v4, 0xbfb8aa3b, v5
	v_exp_f32_e32 v4, v4
	s_nop 0
	v_add_f32_e32 v4, 1.0, v4
	v_div_scale_f32 v6, s[0:1], v4, v4, v5
	s_nop 0
	v_rcp_f32_e32 v4, v4
	s_nop 0
	v_mul_f32_e32 v4, v5, v4
	v_mul_f32_e32 v4, v55, v4
	v_cvt_pk_bf16_f32 v4, v4, s0
	ds_write_b16 v220, v4 offset:320
	ds_read_u16 v4, v220 offset:384
	ds_read_u16 v5, v220 offset:448
	s_waitcnt lgkmcnt(1)
	v_lshlrev_b32_e32 v4, 16, v4
	v_mul_f32_e32 v6, 0xbfb8aa3b, v4
	v_exp_f32_e32 v6, v6
	s_waitcnt lgkmcnt(0)
	v_lshlrev_b32_e32 v5, 16, v5
	v_add_f32_e32 v6, 1.0, v6
	v_rcp_f32_e32 v7, v6
	s_nop 0
	v_mul_f32_e32 v4, v4, v7
	v_mul_f32_e32 v4, v54, v4
	v_cvt_pk_bf16_f32 v4, v4, v4
	ds_write_b16 v220, v4 offset:384
	v_mul_f32_e32 v4, 0xbfb8aa3b, v5
	v_exp_f32_e32 v4, v4
	s_nop 0
	v_add_f32_e32 v4, 1.0, v4
	v_div_scale_f32 v6, s[0:1], v4, v4, v5
	s_nop 0
	v_rcp_f32_e32 v4, v4
	s_nop 0
	v_mul_f32_e32 v4, v5, v4
	v_mul_f32_e32 v4, v53, v4
	v_cvt_pk_bf16_f32 v4, v4, s0
	ds_write_b16 v220, v4 offset:448
	ds_read_u16 v4, v220 offset:1024
	ds_read_u16 v5, v220 offset:1088
	s_waitcnt lgkmcnt(1)
	v_lshlrev_b32_e32 v4, 16, v4
	v_mul_f32_e32 v6, 0xbfb8aa3b, v4
	v_exp_f32_e32 v6, v6
	s_waitcnt lgkmcnt(0)
	v_lshlrev_b32_e32 v5, 16, v5
	v_add_f32_e32 v6, 1.0, v6
	v_rcp_f32_e32 v7, v6
	s_nop 0
	v_mul_f32_e32 v4, v4, v7
	v_mul_f32_e32 v4, v52, v4
	v_cvt_pk_bf16_f32 v4, v4, v4
	ds_write_b16 v220, v4 offset:1024
	v_mul_f32_e32 v4, 0xbfb8aa3b, v5
	v_exp_f32_e32 v4, v4
	s_nop 0
	v_add_f32_e32 v4, 1.0, v4
	v_div_scale_f32 v6, s[0:1], v4, v4, v5
	s_nop 0
	v_rcp_f32_e32 v4, v4
	s_nop 0
	v_mul_f32_e32 v4, v5, v4
	v_mul_f32_e32 v4, v51, v4
	v_cvt_pk_bf16_f32 v4, v4, s0
	ds_write_b16 v220, v4 offset:1088
	ds_read_u16 v4, v220 offset:1152
	ds_read_u16 v5, v220 offset:1216
	s_waitcnt lgkmcnt(1)
	v_lshlrev_b32_e32 v4, 16, v4
	v_mul_f32_e32 v6, 0xbfb8aa3b, v4
	v_exp_f32_e32 v6, v6
	s_waitcnt lgkmcnt(0)
	v_lshlrev_b32_e32 v5, 16, v5
	v_add_f32_e32 v6, 1.0, v6
	v_rcp_f32_e32 v7, v6
	s_nop 0
	v_mul_f32_e32 v4, v4, v7
	v_mul_f32_e32 v4, v50, v4
	v_cvt_pk_bf16_f32 v4, v4, v4
	ds_write_b16 v220, v4 offset:1152
	v_mul_f32_e32 v4, 0xbfb8aa3b, v5
	v_exp_f32_e32 v4, v4
	s_nop 0
	v_add_f32_e32 v4, 1.0, v4
	v_div_scale_f32 v6, s[0:1], v4, v4, v5
	s_nop 0
	v_rcp_f32_e32 v4, v4
	s_nop 0
	v_mul_f32_e32 v4, v5, v4
	v_mul_f32_e32 v4, v49, v4
	v_cvt_pk_bf16_f32 v4, v4, s0
	ds_write_b16 v220, v4 offset:1216
	ds_read_u16 v4, v220 offset:1280
	ds_read_u16 v5, v220 offset:1344
	s_waitcnt lgkmcnt(1)
	v_lshlrev_b32_e32 v4, 16, v4
	v_mul_f32_e32 v6, 0xbfb8aa3b, v4
	v_exp_f32_e32 v6, v6
	s_waitcnt lgkmcnt(0)
	v_lshlrev_b32_e32 v5, 16, v5
	v_add_f32_e32 v6, 1.0, v6
	v_rcp_f32_e32 v7, v6
	s_nop 0
	v_mul_f32_e32 v4, v4, v7
	v_mul_f32_e32 v4, v48, v4
	v_cvt_pk_bf16_f32 v4, v4, v4
	ds_write_b16 v220, v4 offset:1280
	v_mul_f32_e32 v4, 0xbfb8aa3b, v5
	v_exp_f32_e32 v4, v4
	s_nop 0
	v_add_f32_e32 v4, 1.0, v4
	v_div_scale_f32 v6, s[0:1], v4, v4, v5
	s_nop 0
	v_rcp_f32_e32 v4, v4
	s_nop 0
	v_mul_f32_e32 v4, v5, v4
	v_mul_f32_e32 v4, v46, v4
	v_cvt_pk_bf16_f32 v4, v4, s0
	ds_write_b16 v220, v4 offset:1344
	ds_read_u16 v4, v220 offset:1408
	s_waitcnt lgkmcnt(0)
	v_lshlrev_b32_e32 v5, 16, v4
	v_mul_f32_e32 v6, 0xbfb8aa3b, v5
	v_exp_f32_e32 v6, v6
	ds_read_u16 v4, v220 offset:1472
	v_add_f32_e32 v6, 1.0, v6
	v_div_scale_f32 v7, s[0:1], v6, v6, v5
	s_waitcnt lgkmcnt(0)
	v_lshlrev_b32_e32 v4, 16, v4
	v_rcp_f32_e32 v7, v6
	s_nop 0
	v_mul_f32_e32 v5, v5, v7
	v_mul_f32_e32 v5, v45, v5
	v_cvt_pk_bf16_f32 v5, v5, s0
	ds_write_b16 v220, v5 offset:1408
	v_mul_f32_e32 v5, 0xbfb8aa3b, v4
	v_exp_f32_e32 v5, v5
	s_nop 0
	v_add_f32_e32 v5, 1.0, v5
	v_rcp_f32_e32 v6, v5
	s_nop 0
	v_mul_f32_e32 v4, v4, v6
	v_mul_f32_e32 v4, v44, v4
	v_cvt_pk_bf16_f32 v4, v4, v4
	ds_write_b16 v220, v4 offset:1472
	ds_read_u16 v4, v220 offset:2048
	ds_read_u16 v5, v220 offset:2112
	s_waitcnt lgkmcnt(1)
; #define LAS __attribute__((address_space(3)))
; #define LDS_WAIT() asm volatile("s_waitcnt lgkmcnt(0)" ::: "memory")
; DI unsigned cvtpk(float lo, float hi) { f32x2 v = {lo, hi}; bf16x2_t b = __builtin_convertvector(v, bf16x2_t); return __builtin_bit_cast(unsigned, b); }
; DI float bf2f(bf16 b) { return __uint_as_float(((unsigned)b) << 16); }
; DI float siluf_(float x) { return x / (1.f + __expf(-x)); }
; DI void nsa_unit(const Ctx& c0, int b, int g, int i, LAS unsigned char* lds) {
;     ...
;       for (int rg = 0; rg < 16; ++rg) { LAS bf16* e = (LAS bf16*)(S + ((rg & 3) + 8 * (rg >> 2) + 4 * hi) * 128 + r * 2);
;           const float z0 = bf2f(e[0]), z1 = bf2f(e[32]);
;           e[0] = (bf16)(cvtpk(ca0[rg] * siluf_(z0), 0.f) & 0xffffu);
;           e[32] = (bf16)(cvtpk(ca1[rg] * siluf_(z1), 0.f) & 0xffffu); }
;       LDS_WAIT();
; #pragma unroll
;       for (int it = 0; it < 4; ++it) { const int rw = 8 * it + (lane >> 3), ch = lane & 7;
;           *(u32x4*)(ong + (size_t)rw * 512 + ch * 8) = *(const LAS u32x4*)(S + rw * 128 + ch * 16); }
;       LDS_WAIT(); }
	v_lshlrev_b32_e32 v4, 16, v4
	v_mul_f32_e32 v6, 0xbfb8aa3b, v4
	v_exp_f32_e32 v6, v6
	s_waitcnt lgkmcnt(0)
	v_lshlrev_b32_e32 v5, 16, v5
	v_add_f32_e32 v6, 1.0, v6
	v_rcp_f32_e32 v7, v6
	s_nop 0
	v_mul_f32_e32 v4, v4, v7
	v_mul_f32_e32 v4, v27, v4
	v_cvt_pk_bf16_f32 v4, v4, v4
	ds_write_b16 v220, v4 offset:2048
	v_mul_f32_e32 v4, 0xbfb8aa3b, v5
	v_exp_f32_e32 v4, v4
	s_nop 0
	v_add_f32_e32 v4, 1.0, v4
	v_div_scale_f32 v6, s[0:1], v4, v4, v5
	s_nop 0
	v_rcp_f32_e32 v4, v4
	s_nop 0
	v_mul_f32_e32 v4, v5, v4
	v_mul_f32_e32 v4, v26, v4
	v_cvt_pk_bf16_f32 v4, v4, s0
	ds_write_b16 v220, v4 offset:2112
	ds_read_u16 v4, v220 offset:2176
	ds_read_u16 v5, v220 offset:2240
	s_waitcnt lgkmcnt(1)
	v_lshlrev_b32_e32 v4, 16, v4
	v_mul_f32_e32 v6, 0xbfb8aa3b, v4
	v_exp_f32_e32 v6, v6
	s_waitcnt lgkmcnt(0)
	v_lshlrev_b32_e32 v5, 16, v5
	v_add_f32_e32 v6, 1.0, v6
	v_rcp_f32_e32 v7, v6
	s_nop 0
	v_mul_f32_e32 v4, v4, v7
	v_mul_f32_e32 v4, v25, v4
	v_cvt_pk_bf16_f32 v4, v4, v4
	ds_write_b16 v220, v4 offset:2176
	v_mul_f32_e32 v4, 0xbfb8aa3b, v5
	v_exp_f32_e32 v4, v4
	s_nop 0
	v_add_f32_e32 v4, 1.0, v4
	v_div_scale_f32 v6, s[0:1], v4, v4, v5
	s_nop 0
	v_rcp_f32_e32 v4, v4
	s_nop 0
	v_mul_f32_e32 v4, v5, v4
	v_mul_f32_e32 v4, v24, v4
	v_cvt_pk_bf16_f32 v4, v4, s0
	ds_write_b16 v220, v4 offset:2240
	ds_read_u16 v4, v220 offset:2304
	ds_read_u16 v5, v220 offset:2368
	s_waitcnt lgkmcnt(1)
	v_lshlrev_b32_e32 v4, 16, v4
	v_mul_f32_e32 v6, 0xbfb8aa3b, v4
	v_exp_f32_e32 v6, v6
	s_waitcnt lgkmcnt(0)
	v_lshlrev_b32_e32 v5, 16, v5
	v_add_f32_e32 v6, 1.0, v6
	v_rcp_f32_e32 v7, v6
	s_nop 0
	v_mul_f32_e32 v4, v4, v7
	v_mul_f32_e32 v4, v23, v4
	v_cvt_pk_bf16_f32 v4, v4, v4
	ds_write_b16 v220, v4 offset:2304
	v_mul_f32_e32 v4, 0xbfb8aa3b, v5
	v_exp_f32_e32 v4, v4
	s_nop 0
	v_add_f32_e32 v4, 1.0, v4
	v_div_scale_f32 v6, s[0:1], v4, v4, v5
	s_nop 0
	v_rcp_f32_e32 v4, v4
	s_nop 0
	v_mul_f32_e32 v4, v5, v4
	v_mul_f32_e32 v4, v22, v4
	v_cvt_pk_bf16_f32 v4, v4, s0
	ds_write_b16 v220, v4 offset:2368
	ds_read_u16 v4, v220 offset:2432
	ds_read_u16 v5, v220 offset:2496
	s_waitcnt lgkmcnt(1)
	v_lshlrev_b32_e32 v4, 16, v4
	v_mul_f32_e32 v6, 0xbfb8aa3b, v4
	v_exp_f32_e32 v6, v6
	s_waitcnt lgkmcnt(0)
	v_lshlrev_b32_e32 v5, 16, v5
	v_add_f32_e32 v6, 1.0, v6
	v_rcp_f32_e32 v7, v6
	s_nop 0
	v_mul_f32_e32 v4, v4, v7
	v_mul_f32_e32 v4, v21, v4
	v_cvt_pk_bf16_f32 v4, v4, v4
	ds_write_b16 v220, v4 offset:2432
	v_mul_f32_e32 v4, 0xbfb8aa3b, v5
	v_exp_f32_e32 v4, v4
	s_nop 0
	v_add_f32_e32 v4, 1.0, v4
	v_div_scale_f32 v6, s[0:1], v4, v4, v5
	s_nop 0
	v_rcp_f32_e32 v4, v4
	s_nop 0
	v_mul_f32_e32 v4, v5, v4
	v_mul_f32_e32 v4, v15, v4
	v_cvt_pk_bf16_f32 v4, v4, s0
	ds_write_b16 v220, v4 offset:2496
	ds_read_u16 v4, v220 offset:3072
	ds_read_u16 v5, v220 offset:3136
	s_waitcnt lgkmcnt(1)
	v_lshlrev_b32_e32 v4, 16, v4
	v_mul_f32_e32 v6, 0xbfb8aa3b, v4
	v_exp_f32_e32 v6, v6
	s_waitcnt lgkmcnt(0)
	v_lshlrev_b32_e32 v5, 16, v5
	v_add_f32_e32 v6, 1.0, v6
	v_rcp_f32_e32 v7, v6
	s_nop 0
	v_mul_f32_e32 v4, v4, v7
	v_mul_f32_e32 v4, v20, v4
	v_cvt_pk_bf16_f32 v4, v4, v4
	ds_write_b16 v220, v4 offset:3072
	v_mul_f32_e32 v4, 0xbfb8aa3b, v5
	v_exp_f32_e32 v4, v4
	s_nop 0
	v_add_f32_e32 v4, 1.0, v4
	v_div_scale_f32 v6, s[0:1], v4, v4, v5
	s_nop 0
	v_rcp_f32_e32 v4, v4
	s_nop 0
	v_mul_f32_e32 v4, v5, v4
	v_mul_f32_e32 v4, v14, v4
	v_cvt_pk_bf16_f32 v4, v4, s0
	ds_write_b16 v220, v4 offset:3136
	ds_read_u16 v4, v220 offset:3200
	ds_read_u16 v5, v220 offset:3264
	s_waitcnt lgkmcnt(1)
	v_lshlrev_b32_e32 v4, 16, v4
	v_mul_f32_e32 v6, 0xbfb8aa3b, v4
	v_exp_f32_e32 v6, v6
	s_waitcnt lgkmcnt(0)
	v_lshlrev_b32_e32 v5, 16, v5
	v_add_f32_e32 v6, 1.0, v6
	v_rcp_f32_e32 v7, v6
	s_nop 0
	v_mul_f32_e32 v4, v4, v7
	v_mul_f32_e32 v4, v13, v4
	v_cvt_pk_bf16_f32 v4, v4, v4
	ds_write_b16 v220, v4 offset:3200
	v_mul_f32_e32 v4, 0xbfb8aa3b, v5
	v_exp_f32_e32 v4, v4
	s_nop 0
	v_add_f32_e32 v4, 1.0, v4
	v_div_scale_f32 v6, s[0:1], v4, v4, v5
	s_nop 0
	v_rcp_f32_e32 v4, v4
	s_nop 0
	v_mul_f32_e32 v4, v5, v4
	v_mul_f32_e32 v4, v12, v4
	v_cvt_pk_bf16_f32 v4, v4, s0
	ds_write_b16 v220, v4 offset:3264
	ds_read_u16 v4, v220 offset:3328
	ds_read_u16 v5, v220 offset:3392
	s_waitcnt lgkmcnt(1)
	v_lshlrev_b32_e32 v4, 16, v4
	v_mul_f32_e32 v6, 0xbfb8aa3b, v4
	v_exp_f32_e32 v6, v6
	s_waitcnt lgkmcnt(0)
	v_lshlrev_b32_e32 v5, 16, v5
	v_add_f32_e32 v6, 1.0, v6
	v_rcp_f32_e32 v7, v6
	s_nop 0
	v_mul_f32_e32 v4, v4, v7
	v_mul_f32_e32 v4, v10, v4
	v_cvt_pk_bf16_f32 v4, v4, v4
	ds_write_b16 v220, v4 offset:3328
	v_mul_f32_e32 v4, 0xbfb8aa3b, v5
	v_exp_f32_e32 v4, v4
	s_nop 0
	v_add_f32_e32 v4, 1.0, v4
	v_div_scale_f32 v6, s[0:1], v4, v4, v5
	s_nop 0
	v_rcp_f32_e32 v4, v4
	s_nop 0
	v_mul_f32_e32 v4, v5, v4
	v_mul_f32_e32 v4, v11, v4
	v_cvt_pk_bf16_f32 v4, v4, s0
	ds_write_b16 v220, v4 offset:3392
	ds_read_u16 v4, v220 offset:3456
	ds_read_u16 v5, v220 offset:3520
	s_waitcnt lgkmcnt(1)
	v_lshlrev_b32_e32 v4, 16, v4
	v_mul_f32_e32 v6, 0xbfb8aa3b, v4
	v_exp_f32_e32 v6, v6
	s_waitcnt lgkmcnt(0)
	v_lshlrev_b32_e32 v5, 16, v5
	v_add_f32_e32 v6, 1.0, v6
	v_div_scale_f32 v7, s[0:1], v6, v6, v4
	s_nop 0
	v_rcp_f32_e32 v7, v6
	s_nop 0
	v_mul_f32_e32 v4, v4, v7
	v_mul_f32_e32 v2, v2, v4
	v_cvt_pk_bf16_f32 v2, v2, s0
	ds_write_b16 v220, v2 offset:3456
	v_mul_f32_e32 v2, 0xbfb8aa3b, v5
	v_exp_f32_e32 v2, v2
	s_nop 0
	v_add_f32_e32 v2, 1.0, v2
	v_div_scale_f32 v4, s[0:1], v2, v2, v5
	s_nop 0
	v_rcp_f32_e32 v2, v2
	s_nop 0
	v_mul_f32_e32 v2, v5, v2
	v_mul_f32_e32 v1, v1, v2
	v_cvt_pk_bf16_f32 v1, v1, s0
	ds_write_b16 v220, v1 offset:3520
	s_waitcnt lgkmcnt(0)
	ds_read_b128 v[4:7], v216
	s_mov_b64 s[0:1], 0xd500000
	v_lshl_add_u64 v[8:9], v[8:9], 0, s[0:1]
	v_lshl_add_u64 v[10:11], v[8:9], 0, v[126:127]
	s_waitcnt lgkmcnt(0)
	global_store_dwordx4 v[10:11], v[4:7], off
	ds_read_b128 v[4:7], v217
	v_lshl_add_u64 v[10:11], v[8:9], 0, v[128:129]
	s_waitcnt lgkmcnt(0)
	global_store_dwordx4 v[10:11], v[4:7], off
	ds_read_b128 v[4:7], v218
	v_lshl_add_u64 v[10:11], v[8:9], 0, v[130:131]
	v_lshl_add_u64 v[8:9], v[8:9], 0, v[132:133]
	s_waitcnt lgkmcnt(0)
	global_store_dwordx4 v[10:11], v[4:7], off
	ds_read_b128 v[4:7], v219
	s_waitcnt lgkmcnt(0)
	global_store_dwordx4 v[8:9], v[4:7], off
	s_waitcnt lgkmcnt(0)
	s_cbranch_scc1 .LBB0_538

; #define MFMA32(a, b, c) __builtin_amdgcn_mfma_f32_32x32x16_bf16((a), (b), (c), 0, 0, 0)
; DI void gla_stage3(const Ctx& c0, int layer, int unit, int cb, LAS unsigned char* lds) {
;     ...
;     const bf16* qgp = (const bf16*)(c.ws + O_QG) + (row0 + r) * 256 + h * 64 + 8 * hi;
;     const float* sp = (const float*)(c.ws + O_UPD) + (size_t)unit * 8192;
;     const float* gn = c.a->in[I_GNORM] + (size_t)layer * 128;
;     bf16x8 qf[4];
; #pragma unroll
;     for (int s = 0; s < 4; ++s) qf[s] = *(const bf16x8*)(qgp + 16 * s);
;     f32x16 o[4];
; #pragma unroll
;     for (int vb = 0; vb < 4; ++vb) {
;         o[vb] = f32x16{};
; #pragma unroll
;         for (int s = 0; s < 4; ++s) { const float* s0 = sp + (size_t)(16 * s + 8 * hi) * 128 + 32 * vb + r;
;             const bf16x8 bfv = pack8(s0[0], s0[128], s0[256], s0[384], s0[512], s0[640], s0[768], s0[896]);
;             o[vb] = MFMA32(qf[s], bfv, o[vb]); }
;         asm volatile("" ::: "memory");
;     }
;     g3_tile_in((const bf16*)(c.ws + O_OINTRA) + row0 * 512 + h * 128, R, lane);
.LBB0_604:
	s_mov_b64 s[2:3], s[84:85]
	s_mov_b64 s[0:1], s[86:87]
	s_ashr_i32 s2, s35, 8
	s_ashr_i32 s3, s2, 31
	s_lshl_b64 s[2:3], s[2:3], 12
	s_and_b32 s5, s8, 0xfc0
	s_or_b32 s2, s2, s5
	s_or_b64 s[2:3], s[2:3], s[6:7]
	v_mov_b32_e32 v3, s3
	v_or_b32_e32 v2, s2, v152
	s_bfe_u32 s4, s35, 0x20006
	v_lshlrev_b64 v[2:3], 9, v[2:3]
	v_lshl_add_u64 v[2:3], s[0:1], 0, v[2:3]
	s_lshl_b32 s10, s4, 7
	v_lshl_add_u64 v[2:3], v[2:3], 0, s[10:11]
	v_lshl_add_u64 v[2:3], v[2:3], 0, v[86:87]
	v_lshl_add_u64 v[4:5], v[2:3], 0, s[16:17]
	v_add_co_u32_e32 v2, vcc, s13, v2
	v_lshl_add_u64 v[90:91], s[0:1], 0, v[84:85]
	s_nop 0
	v_addc_co_u32_e32 v3, vcc, 0, v3, vcc
	global_load_dwordx4 v[50:53], v[2:3], off
	global_load_dwordx4 v[110:113], v[4:5], off offset:96
	global_load_dwordx4 v[106:109], v[4:5], off offset:64
	global_load_dwordx4 v[102:105], v[4:5], off offset:32
	v_add_co_u32_e32 v2, vcc, s24, v90
	s_lshl_b64 s[2:3], s[2:3], 10
	s_nop 0
	v_addc_co_u32_e32 v3, vcc, -1, v91, vcc
	v_add_co_u32_e32 v58, vcc, s28, v90
	global_load_dword v2, v[2:3], off
	s_nop 0
	v_addc_co_u32_e32 v59, vcc, -1, v91, vcc
	global_load_dword v3, v[58:59], off offset:384
	global_load_dword v4, v[58:59], off offset:896
	global_load_dword v5, v[58:59], off offset:1408
	global_load_dword v6, v[58:59], off offset:1920
	global_load_dword v7, v[58:59], off offset:2432
	global_load_dword v8, v[58:59], off offset:2944
	global_load_dword v9, v[58:59], off offset:3456
	v_add_co_u32_e32 v18, vcc, s25, v90
	s_lshl_b32 s4, s4, 8
	s_nop 0
	v_addc_co_u32_e32 v19, vcc, -1, v91, vcc
	v_add_co_u32_e32 v114, vcc, s29, v90
	global_load_dword v18, v[18:19], off
	s_nop 0
	v_addc_co_u32_e32 v115, vcc, -1, v91, vcc
	global_load_dword v19, v[114:115], off offset:384
	global_load_dword v20, v[114:115], off offset:896
	global_load_dword v21, v[114:115], off offset:1408
	global_load_dword v22, v[114:115], off offset:1920
	global_load_dword v23, v[114:115], off offset:2432
	global_load_dword v24, v[114:115], off offset:2944
	global_load_dword v25, v[114:115], off offset:3456
	s_add_u32 s0, s0, s2
	s_addc_u32 s1, s1, s3
	s_add_u32 s0, s0, s4
	s_addc_u32 s1, s1, 0
	s_add_i32 s35, s35, s12
	s_add_i32 s8, s8, s9
	v_lshl_add_u64 v[84:85], v[84:85], 0, s[14:15]
	s_cmpk_lt_i32 s35, 0x800
	s_waitcnt vmcnt(0) lgkmcnt(0)
	global_load_dword v41, v[114:115], off offset:3584
	global_load_dword v40, v[114:115], off offset:3072
	global_load_dword v39, v[114:115], off offset:2560
	global_load_dword v38, v[114:115], off offset:2048
	global_load_dword v37, v[114:115], off offset:1536
	global_load_dword v36, v[114:115], off offset:1024
	global_load_dword v35, v[114:115], off offset:512
	global_load_dword v34, v[114:115], off
	global_load_dword v145, v[58:59], off offset:3584
	global_load_dword v146, v[58:59], off offset:3072
	global_load_dword v143, v[58:59], off offset:2560
	global_load_dword v144, v[58:59], off offset:2048
	global_load_dword v141, v[58:59], off offset:1536
	global_load_dword v142, v[58:59], off offset:1024
	global_load_dword v139, v[58:59], off offset:512
	global_load_dword v140, v[58:59], off
	v_cvt_pk_bf16_f32 v2, v2, v3
	v_cvt_pk_bf16_f32 v3, v4, v5
	v_cvt_pk_bf16_f32 v4, v6, v7
	v_cvt_pk_bf16_f32 v5, v8, v9
	v_cvt_pk_bf16_f32 v18, v18, v19
	s_nop 0
	v_mfma_f32_32x32x16_bf16 v[2:17], v[50:53], v[2:5], 0
	v_cvt_pk_bf16_f32 v19, v20, v21
	v_cvt_pk_bf16_f32 v20, v22, v23
	v_cvt_pk_bf16_f32 v21, v24, v25
	s_nop 1
	v_mfma_f32_32x32x16_bf16 v[2:17], v[102:105], v[18:21], v[2:17]
	v_add_co_u32_e32 v18, vcc, s26, v90
	s_nop 1
	v_addc_co_u32_e32 v19, vcc, -1, v91, vcc
	v_add_co_u32_e32 v118, vcc, s30, v90
	global_load_dword v18, v[18:19], off
	s_nop 0
	v_addc_co_u32_e32 v119, vcc, -1, v91, vcc
	global_load_dword v19, v[118:119], off offset:384
	global_load_dword v20, v[118:119], off offset:896
	global_load_dword v21, v[118:119], off offset:1408
	global_load_dword v22, v[118:119], off offset:1920
	global_load_dword v23, v[118:119], off offset:2432
	global_load_dword v24, v[118:119], off offset:2944
	global_load_dword v25, v[118:119], off offset:3456
	s_waitcnt vmcnt(0) lgkmcnt(0)
	global_load_dword v63, v[114:115], off offset:3712
	global_load_dword v62, v[114:115], off offset:3200
	global_load_dword v61, v[114:115], off offset:2688
	global_load_dword v60, v[114:115], off offset:2176
	global_load_dword v57, v[114:115], off offset:1664
	global_load_dword v56, v[114:115], off offset:1152
	global_load_dword v55, v[114:115], off offset:640
	global_load_dword v54, v[114:115], off offset:128
	global_load_dword v173, v[58:59], off offset:3712
	global_load_dword v176, v[58:59], off offset:3200
	global_load_dword v171, v[58:59], off offset:2688
	global_load_dword v174, v[58:59], off offset:2176
	global_load_dword v169, v[58:59], off offset:1664
	global_load_dword v172, v[58:59], off offset:1152
	global_load_dword v167, v[58:59], off offset:640
	global_load_dword v170, v[58:59], off offset:128
	global_load_dword v157, v[118:119], off offset:3584
	global_load_dword v160, v[118:119], off offset:3072
	global_load_dword v155, v[118:119], off offset:2560
	global_load_dword v158, v[118:119], off offset:2048
	global_load_dword v149, v[118:119], off offset:1536
	global_load_dword v156, v[118:119], off offset:1024
	global_load_dword v147, v[118:119], off offset:512
	global_load_dword v148, v[118:119], off
	v_cvt_pk_bf16_f32 v18, v18, v19
	v_cvt_pk_bf16_f32 v19, v20, v21
	v_cvt_pk_bf16_f32 v20, v22, v23
	v_cvt_pk_bf16_f32 v21, v24, v25
	s_nop 1
	v_mfma_f32_32x32x16_bf16 v[2:17], v[106:109], v[18:21], v[2:17]
	v_add_co_u32_e32 v18, vcc, s27, v90
	s_nop 1
	v_addc_co_u32_e32 v19, vcc, -1, v91, vcc
	v_add_co_u32_e32 v120, vcc, s31, v90
	global_load_dword v18, v[18:19], off
	s_nop 0
	v_addc_co_u32_e32 v121, vcc, -1, v91, vcc
	global_load_dword v19, v[120:121], off offset:384
	global_load_dword v20, v[120:121], off offset:896
	global_load_dword v21, v[120:121], off offset:1408
	global_load_dword v22, v[120:121], off offset:1920
	global_load_dword v23, v[120:121], off offset:2432
	global_load_dword v24, v[120:121], off offset:2944
	global_load_dword v25, v[120:121], off offset:3456
	v_cmp_lt_i32_e32 vcc, v94, v95
	s_waitcnt vmcnt(0) lgkmcnt(0)
; #define MFMA32(a, b, c) __builtin_amdgcn_mfma_f32_32x32x16_bf16((a), (b), (c), 0, 0, 0)
; DI void gla_stage3(const Ctx& c0, int layer, int unit, int cb, LAS unsigned char* lds) {
;     ...
;     f32x16 o[4];
; #pragma unroll
;     for (int vb = 0; vb < 4; ++vb) {
;         o[vb] = f32x16{};
; #pragma unroll
;         for (int s = 0; s < 4; ++s) { const float* s0 = sp + (size_t)(16 * s + 8 * hi) * 128 + 32 * vb + r;
;             const bf16x8 bfv = pack8(s0[0], s0[128], s0[256], s0[384], s0[512], s0[640], s0[768], s0[896]);
;             o[vb] = MFMA32(qf[s], bfv, o[vb]); }
;         asm volatile("" ::: "memory");
;     }
;     g3_tile_in((const bf16*)(c.ws + O_OINTRA) + row0 * 512 + h * 128, R, lane);
	global_load_dword v127, v[114:115], off offset:3840
	global_load_dword v126, v[114:115], off offset:3328
	global_load_dword v125, v[114:115], off offset:2816
	global_load_dword v124, v[114:115], off offset:2304
	global_load_dword v123, v[114:115], off offset:1792
	global_load_dword v122, v[114:115], off offset:1280
	global_load_dword v117, v[114:115], off offset:768
	global_load_dword v116, v[114:115], off offset:256
	global_load_dword v214, v[58:59], off offset:3840
	global_load_dword v212, v[58:59], off offset:3328
	global_load_dword v205, v[58:59], off offset:2816
	global_load_dword v210, v[58:59], off offset:2304
	global_load_dword v203, v[58:59], off offset:1792
	global_load_dword v208, v[58:59], off offset:1280
	global_load_dword v201, v[58:59], off offset:768
	global_load_dword v206, v[58:59], off offset:256
	global_load_dword v199, v[120:121], off offset:3712
	global_load_dword v204, v[120:121], off offset:3200
	global_load_dword v197, v[120:121], off offset:2688
	global_load_dword v202, v[120:121], off offset:2176
	global_load_dword v195, v[120:121], off offset:1664
	global_load_dword v200, v[120:121], off offset:1152
	global_load_dword v183, v[120:121], off offset:640
	global_load_dword v198, v[120:121], off offset:128
	global_load_dword v181, v[118:119], off offset:3712
	global_load_dword v196, v[118:119], off offset:3200
	global_load_dword v179, v[118:119], off offset:2688
	global_load_dword v182, v[118:119], off offset:2176
	global_load_dword v177, v[118:119], off offset:1664
	global_load_dword v180, v[118:119], off offset:1152
	global_load_dword v175, v[118:119], off offset:640
	global_load_dword v178, v[118:119], off offset:128
	global_load_dword v165, v[120:121], off offset:3584
	global_load_dword v168, v[120:121], off offset:3072
	global_load_dword v163, v[120:121], off offset:2560
	global_load_dword v166, v[120:121], off offset:2048
	global_load_dword v161, v[120:121], off offset:1536
	global_load_dword v164, v[120:121], off offset:1024
	global_load_dword v159, v[120:121], off offset:512
	global_load_dword v162, v[120:121], off
	v_cvt_pk_bf16_f32 v18, v18, v19
	v_cvt_pk_bf16_f32 v19, v20, v21
	v_cvt_pk_bf16_f32 v20, v22, v23
	v_cvt_pk_bf16_f32 v21, v24, v25
	s_nop 1
	v_mfma_f32_32x32x16_bf16 v[2:17], v[110:113], v[18:21], v[2:17]
	s_waitcnt vmcnt(40) lgkmcnt(0)
	global_load_dword v238, v[82:83], off offset:384
	global_load_dword v236, v[82:83], off offset:256
	global_load_dword v234, v[82:83], off offset:128
	global_load_dword v232, v[82:83], off
	global_load_dword v90, v[90:91], off
	global_load_dword v230, v[120:121], off offset:3328
	global_load_dword v219, v[120:121], off offset:2816
	global_load_dword v228, v[120:121], off offset:2304
	global_load_dword v217, v[120:121], off offset:1792
	global_load_dword v226, v[120:121], off offset:1280
	global_load_dword v215, v[120:121], off offset:768
	global_load_dword v224, v[120:121], off offset:256
	global_load_dword v213, v[118:119], off offset:3840
	global_load_dword v222, v[118:119], off offset:3328
	global_load_dword v211, v[118:119], off offset:2816
	global_load_dword v220, v[118:119], off offset:2304
	global_load_dword v209, v[118:119], off offset:1792
	global_load_dword v218, v[118:119], off offset:1280
	global_load_dword v207, v[118:119], off offset:768
	global_load_dword v216, v[118:119], off offset:256
	v_cvt_pk_bf16_f32 v18, v140, v139
	v_cvt_pk_bf16_f32 v34, v34, v35
	v_cvt_pk_bf16_f32 v19, v142, v141
	v_cvt_pk_bf16_f32 v35, v36, v37
	v_cvt_pk_bf16_f32 v20, v144, v143
	v_cvt_pk_bf16_f32 v36, v38, v39
	v_cvt_pk_bf16_f32 v21, v146, v145
	v_cvt_pk_bf16_f32 v37, v40, v41
	s_nop 0
	v_mfma_f32_32x32x16_bf16 v[18:33], v[50:53], v[18:21], 0
	v_mfma_f32_32x32x16_bf16 v[18:33], v[102:105], v[34:37], v[18:33]
	s_waitcnt vmcnt(60) lgkmcnt(0)
	v_cvt_pk_bf16_f32 v34, v148, v147
	v_cvt_pk_bf16_f32 v35, v156, v149
	v_cvt_pk_bf16_f32 v36, v158, v155
	v_cvt_pk_bf16_f32 v37, v160, v157
	s_nop 1
	v_mfma_f32_32x32x16_bf16 v[18:33], v[106:109], v[34:37], v[18:33]
	s_waitcnt vmcnt(20) lgkmcnt(0)
	v_cvt_pk_bf16_f32 v34, v162, v159
	v_cvt_pk_bf16_f32 v35, v164, v161
	v_cvt_pk_bf16_f32 v36, v166, v163
	v_cvt_pk_bf16_f32 v37, v168, v165
	s_nop 1
	v_mfma_f32_32x32x16_bf16 v[18:33], v[110:113], v[34:37], v[18:33]
	s_waitcnt vmcnt(62) lgkmcnt(0)
	v_cvt_pk_bf16_f32 v34, v170, v167
	v_cvt_pk_bf16_f32 v54, v54, v55
	v_cvt_pk_bf16_f32 v35, v172, v169
	v_cvt_pk_bf16_f32 v55, v56, v57
	v_cvt_pk_bf16_f32 v36, v174, v171
	v_cvt_pk_bf16_f32 v56, v60, v61
	v_cvt_pk_bf16_f32 v37, v176, v173
	v_cvt_pk_bf16_f32 v57, v62, v63
	s_nop 0
	v_mfma_f32_32x32x16_bf16 v[34:49], v[50:53], v[34:37], 0
	v_mfma_f32_32x32x16_bf16 v[34:49], v[102:105], v[54:57], v[34:49]
	s_waitcnt vmcnt(28) lgkmcnt(0)
	v_cvt_pk_bf16_f32 v54, v178, v175
	v_cvt_pk_bf16_f32 v55, v180, v177
	v_cvt_pk_bf16_f32 v56, v182, v179
	v_cvt_pk_bf16_f32 v57, v196, v181
	s_nop 1
	v_mfma_f32_32x32x16_bf16 v[34:49], v[106:109], v[54:57], v[34:49]
	s_waitcnt vmcnt(36) lgkmcnt(0)
	v_cvt_pk_bf16_f32 v54, v198, v183
	v_cvt_pk_bf16_f32 v55, v200, v195
	v_cvt_pk_bf16_f32 v56, v202, v197
	v_cvt_pk_bf16_f32 v57, v204, v199
	s_nop 1
	v_mfma_f32_32x32x16_bf16 v[34:49], v[110:113], v[54:57], v[34:49]
	s_nop 0
	s_nop 0
	s_waitcnt vmcnt(44) lgkmcnt(0)
	v_cvt_pk_bf16_f32 v54, v206, v201
	v_cvt_pk_bf16_f32 v114, v116, v117
	v_cvt_pk_bf16_f32 v55, v208, v203
	v_cvt_pk_bf16_f32 v115, v122, v123
	v_cvt_pk_bf16_f32 v56, v210, v205
	v_cvt_pk_bf16_f32 v116, v124, v125
	v_cvt_pk_bf16_f32 v57, v212, v214
	v_cvt_pk_bf16_f32 v117, v126, v127
	s_nop 0
	v_mfma_f32_32x32x16_bf16 v[50:65], v[50:53], v[54:57], 0
	v_mfma_f32_32x32x16_bf16 v[50:65], v[102:105], v[114:117], v[50:65]
	s_waitcnt vmcnt(0) lgkmcnt(0)
; #define LAS __attribute__((address_space(3)))
; #define LDS_WAIT() asm volatile("s_waitcnt lgkmcnt(0)" ::: "memory")
; DI float bf2f(bf16 b) { return __uint_as_float(((unsigned)b) << 16); }
; DI void g3_tile_in(const bf16* g, LAS unsigned char* R, int lane) {
; #pragma unroll
;     for (int it = 0; it < 8; ++it) { const int row = 4 * it + (lane >> 4), ch = lane & 15;
;         *(LAS u32x4*)(R + row * G3_PITCH + ch * 16) = *(const u32x4*)(g + (size_t)row * 512 + ch * 8); }
;     LDS_WAIT();
; DI void gla_stage3(const Ctx& c0, int layer, int unit, int cb, LAS unsigned char* lds) {
;     ...
;     g3_tile_in((const bf16*)(c.ws + O_OINTRA) + row0 * 512 + h * 128, R, lane);
; #pragma unroll
;     for (int vb = 0; vb < 4; ++vb) {
; #pragma unroll
;         for (int rg = 0; rg < 16; ++rg) o[vb][rg] += bf2f(*(const LAS bf16*)(Re + ((rg & 3) + 8 * (rg >> 2)) * G3_PITCH + 64 * vb));
;         asm volatile("" ::: "memory");
;     }
	v_cvt_pk_bf16_f32 v102, v216, v207
	v_cvt_pk_bf16_f32 v103, v218, v209
	v_cvt_pk_bf16_f32 v104, v220, v211
	v_cvt_pk_bf16_f32 v105, v222, v213
	s_nop 1
	v_mfma_f32_32x32x16_bf16 v[50:65], v[106:109], v[102:105], v[50:65]
	s_nop 0
	s_waitcnt vmcnt(8) lgkmcnt(0)
	v_cvt_pk_bf16_f32 v102, v224, v215
	v_cvt_pk_bf16_f32 v103, v226, v217
	v_cvt_pk_bf16_f32 v104, v228, v219
	v_cvt_pk_bf16_f32 v105, v230, v90
	v_lshl_add_u64 v[90:91], s[0:1], 0, v[88:89]
	v_lshl_add_u64 v[106:107], v[90:91], 0, s[18:19]
	v_mfma_f32_32x32x16_bf16 v[50:65], v[110:113], v[102:105], v[50:65]
	v_lshl_add_u64 v[102:103], v[106:107], 0, v[66:67]
	global_load_dwordx4 v[102:105], v[102:103], off
	s_waitcnt vmcnt(0) lgkmcnt(0)
	v_lshl_add_u64 v[168:169], v[90:91], 0, s[20:21]
	v_lshl_add_u64 v[140:141], v[168:169], 0, v[70:71]
	global_load_dwordx4 v[174:177], v[140:141], off
	v_lshl_add_u64 v[140:141], v[106:107], 0, v[70:71]
	global_load_dwordx4 v[146:149], v[140:141], off
	v_lshl_add_u64 v[144:145], v[106:107], 0, v[68:69]
	global_load_dwordx4 v[140:143], v[144:145], off
	ds_write_b128 v92, v[102:105]
	s_waitcnt vmcnt(0) lgkmcnt(0)
	v_lshl_add_u64 v[144:145], v[168:169], 0, v[76:77]
	global_load_dwordx4 v[200:203], v[144:145], off
	v_lshl_add_u64 v[144:145], v[168:169], 0, v[74:75]
	global_load_dwordx4 v[196:199], v[144:145], off
	v_lshl_add_u64 v[144:145], v[168:169], 0, v[72:73]
	global_load_dwordx4 v[178:181], v[144:145], off
	v_lshl_add_u64 v[144:145], v[106:107], 0, v[74:75]
	global_load_dwordx4 v[156:159], v[144:145], off
	v_lshl_add_u64 v[102:103], v[106:107], 0, v[72:73]
	global_load_dwordx4 v[102:105], v[102:103], off
	ds_write_b128 v92, v[140:143] offset:1088
	s_waitcnt vmcnt(5) lgkmcnt(0)
	v_lshl_add_u64 v[140:141], v[168:169], 0, v[78:79]
	global_load_dwordx4 v[204:207], v[140:141], off
	v_lshl_add_u64 v[140:141], v[106:107], 0, v[78:79]
	global_load_dwordx4 v[160:163], v[140:141], off
	v_lshl_add_u64 v[144:145], v[106:107], 0, v[76:77]
	global_load_dwordx4 v[140:143], v[144:145], off
	ds_write_b128 v92, v[146:149] offset:2176
	s_waitcnt vmcnt(3) lgkmcnt(0)
	v_lshl_add_u64 v[144:145], v[168:169], 0, v[66:67]
	global_load_dwordx4 v[164:167], v[144:145], off
	v_lshl_add_u64 v[148:149], v[106:107], 0, v[80:81]
	global_load_dwordx4 v[144:147], v[148:149], off
	ds_write_b128 v92, v[102:105] offset:3264
	s_waitcnt vmcnt(6) lgkmcnt(0)
	v_lshl_add_u64 v[148:149], v[168:169], 0, v[68:69]
	global_load_dwordx4 v[170:173], v[148:149], off
	ds_write_b128 v92, v[156:159] offset:4352
	s_waitcnt vmcnt(3) lgkmcnt(0)
	ds_write_b128 v92, v[140:143] offset:5440
	s_waitcnt vmcnt(4) lgkmcnt(0)
	ds_write_b128 v92, v[160:163] offset:6528
	s_waitcnt vmcnt(1) lgkmcnt(0)
	ds_write_b128 v92, v[144:147] offset:7616
	s_waitcnt lgkmcnt(0)
	ds_read_u16 v102, v1
	s_waitcnt lgkmcnt(0)
	v_lshlrev_b32_e32 v102, 16, v102
	v_add_f32_e32 v138, v2, v102
	ds_read_u16 v2, v1 offset:272
	s_waitcnt lgkmcnt(0)
	v_lshlrev_b32_e32 v2, 16, v2
	v_add_f32_e32 v137, v3, v2
	ds_read_u16 v2, v1 offset:544
	s_waitcnt lgkmcnt(0)
	v_lshlrev_b32_e32 v2, 16, v2
	v_add_f32_e32 v136, v4, v2
	ds_read_u16 v2, v1 offset:816
	s_waitcnt lgkmcnt(0)
	v_lshlrev_b32_e32 v2, 16, v2
	v_add_f32_e32 v135, v5, v2
	ds_read_u16 v2, v1 offset:2176
	s_waitcnt lgkmcnt(0)
	v_lshlrev_b32_e32 v2, 16, v2
	v_add_f32_e32 v134, v6, v2
	ds_read_u16 v2, v1 offset:2448
	s_waitcnt lgkmcnt(0)
	v_lshlrev_b32_e32 v2, 16, v2
	v_add_f32_e32 v133, v7, v2
	ds_read_u16 v2, v1 offset:2720
	s_waitcnt lgkmcnt(0)
	v_lshlrev_b32_e32 v2, 16, v2
	v_add_f32_e32 v132, v8, v2
	ds_read_u16 v2, v1 offset:2992
	s_waitcnt lgkmcnt(0)
	v_lshlrev_b32_e32 v2, 16, v2
	v_add_f32_e32 v131, v9, v2
	ds_read_u16 v2, v1 offset:4352
	s_waitcnt lgkmcnt(0)
	v_lshlrev_b32_e32 v2, 16, v2
	v_add_f32_e32 v130, v10, v2
	ds_read_u16 v2, v1 offset:4624
	s_waitcnt lgkmcnt(0)
	v_lshlrev_b32_e32 v2, 16, v2
	v_add_f32_e32 v129, v11, v2
	ds_read_u16 v2, v1 offset:4896
	s_waitcnt lgkmcnt(0)
	v_lshlrev_b32_e32 v2, 16, v2
	v_add_f32_e32 v128, v12, v2
	ds_read_u16 v2, v1 offset:5168
	s_waitcnt lgkmcnt(0)
	v_lshlrev_b32_e32 v2, 16, v2
	v_add_f32_e32 v127, v13, v2
	ds_read_u16 v2, v1 offset:6528
	s_waitcnt lgkmcnt(0)
	v_lshlrev_b32_e32 v2, 16, v2
	v_add_f32_e32 v126, v14, v2
	ds_read_u16 v2, v1 offset:6800
	s_waitcnt lgkmcnt(0)
	v_lshlrev_b32_e32 v2, 16, v2
	v_add_f32_e32 v125, v15, v2
	ds_read_u16 v2, v1 offset:7072
	s_waitcnt lgkmcnt(0)
	v_lshlrev_b32_e32 v2, 16, v2
	v_add_f32_e32 v124, v16, v2
	ds_read_u16 v2, v1 offset:7344
	s_waitcnt lgkmcnt(0)
	v_lshlrev_b32_e32 v2, 16, v2
	v_add_f32_e32 v123, v17, v2
	ds_read_u16 v2, v1 offset:64
	s_waitcnt lgkmcnt(0)
	v_lshlrev_b32_e32 v2, 16, v2
	v_add_f32_e32 v122, v18, v2
	ds_read_u16 v2, v1 offset:336
	s_waitcnt lgkmcnt(0)
	v_lshlrev_b32_e32 v2, 16, v2
	v_add_f32_e32 v121, v19, v2
	ds_read_u16 v2, v1 offset:608
	s_waitcnt lgkmcnt(0)
	v_lshlrev_b32_e32 v2, 16, v2
	v_add_f32_e32 v120, v20, v2
	ds_read_u16 v2, v1 offset:880
	s_waitcnt lgkmcnt(0)
	v_lshlrev_b32_e32 v2, 16, v2
	v_add_f32_e32 v119, v21, v2
	ds_read_u16 v2, v1 offset:2240
	s_waitcnt lgkmcnt(0)
	v_lshlrev_b32_e32 v2, 16, v2
	v_add_f32_e32 v118, v22, v2
	ds_read_u16 v2, v1 offset:2512
	s_waitcnt lgkmcnt(0)
	v_lshlrev_b32_e32 v2, 16, v2
	v_add_f32_e32 v117, v23, v2
	ds_read_u16 v2, v1 offset:2784
	s_waitcnt lgkmcnt(0)
	v_lshlrev_b32_e32 v2, 16, v2
	v_add_f32_e32 v116, v24, v2
	ds_read_u16 v2, v1 offset:3056
	s_waitcnt lgkmcnt(0)
	v_lshlrev_b32_e32 v2, 16, v2
	v_add_f32_e32 v115, v25, v2
	ds_read_u16 v2, v1 offset:4416
	s_waitcnt lgkmcnt(0)
	v_lshlrev_b32_e32 v2, 16, v2
	v_add_f32_e32 v114, v26, v2
	ds_read_u16 v2, v1 offset:4688
	s_waitcnt lgkmcnt(0)
; #define LAS __attribute__((address_space(3)))
; DI float bf2f(bf16 b) { return __uint_as_float(((unsigned)b) << 16); }
; DI void gla_stage3(const Ctx& c0, int layer, int unit, int cb, LAS unsigned char* lds) {
;     ...
;     for (int vb = 0; vb < 4; ++vb) {
; #pragma unroll
;         for (int rg = 0; rg < 16; ++rg) o[vb][rg] += bf2f(*(const LAS bf16*)(Re + ((rg & 3) + 8 * (rg >> 2)) * G3_PITCH + 64 * vb));
;         asm volatile("" ::: "memory");
;     }
	v_lshlrev_b32_e32 v2, 16, v2
	v_add_f32_e32 v113, v27, v2
	ds_read_u16 v2, v1 offset:4960
	s_waitcnt lgkmcnt(0)
	v_lshlrev_b32_e32 v2, 16, v2
	v_add_f32_e32 v112, v28, v2
	ds_read_u16 v2, v1 offset:5232
	s_waitcnt lgkmcnt(0)
	v_lshlrev_b32_e32 v2, 16, v2
	v_add_f32_e32 v111, v29, v2
	ds_read_u16 v2, v1 offset:6592
	s_waitcnt lgkmcnt(0)
	v_lshlrev_b32_e32 v2, 16, v2
	v_add_f32_e32 v110, v30, v2
	ds_read_u16 v2, v1 offset:6864
	s_waitcnt lgkmcnt(0)
	v_lshlrev_b32_e32 v2, 16, v2
	v_add_f32_e32 v109, v31, v2
	ds_read_u16 v2, v1 offset:7136
	s_waitcnt lgkmcnt(0)
	v_lshlrev_b32_e32 v2, 16, v2
	v_add_f32_e32 v108, v32, v2
	ds_read_u16 v2, v1 offset:7408
	s_waitcnt lgkmcnt(0)
	v_lshlrev_b32_e32 v2, 16, v2
	v_add_f32_e32 v107, v33, v2
	ds_read_u16 v2, v1 offset:128
	s_waitcnt lgkmcnt(0)
	v_lshlrev_b32_e32 v2, 16, v2
	v_add_f32_e32 v106, v34, v2
	ds_read_u16 v2, v1 offset:400
	s_waitcnt lgkmcnt(0)
	v_lshlrev_b32_e32 v2, 16, v2
	v_add_f32_e32 v105, v35, v2
	ds_read_u16 v2, v1 offset:672
	s_waitcnt lgkmcnt(0)
	v_lshlrev_b32_e32 v2, 16, v2
	v_add_f32_e32 v104, v36, v2
	ds_read_u16 v2, v1 offset:944
	s_waitcnt lgkmcnt(0)
	v_lshlrev_b32_e32 v2, 16, v2
	v_add_f32_e32 v103, v37, v2
	ds_read_u16 v2, v1 offset:2304
	s_waitcnt lgkmcnt(0)
	v_lshlrev_b32_e32 v2, 16, v2
	v_add_f32_e32 v102, v38, v2
	ds_read_u16 v2, v1 offset:2576
	s_waitcnt lgkmcnt(0)
	v_lshlrev_b32_e32 v2, 16, v2
	v_add_f32_e32 v39, v39, v2
	ds_read_u16 v2, v1 offset:2848
	s_waitcnt lgkmcnt(0)
	v_lshlrev_b32_e32 v2, 16, v2
	v_add_f32_e32 v38, v40, v2
	ds_read_u16 v2, v1 offset:3120
	s_waitcnt lgkmcnt(0)
	v_lshlrev_b32_e32 v2, 16, v2
	v_add_f32_e32 v37, v41, v2
	ds_read_u16 v2, v1 offset:4480
	s_waitcnt lgkmcnt(0)
	v_lshlrev_b32_e32 v2, 16, v2
	v_add_f32_e32 v36, v42, v2
	ds_read_u16 v2, v1 offset:4752
	s_waitcnt lgkmcnt(0)
	v_lshlrev_b32_e32 v2, 16, v2
	v_add_f32_e32 v34, v43, v2
	ds_read_u16 v2, v1 offset:5024
	s_waitcnt lgkmcnt(0)
	v_lshlrev_b32_e32 v2, 16, v2
	v_add_f32_e32 v33, v44, v2
	ds_read_u16 v2, v1 offset:5296
	s_waitcnt lgkmcnt(0)
	v_lshlrev_b32_e32 v2, 16, v2
	v_add_f32_e32 v32, v45, v2
	ds_read_u16 v2, v1 offset:6656
	s_waitcnt lgkmcnt(0)
	v_lshlrev_b32_e32 v2, 16, v2
	v_add_f32_e32 v30, v46, v2
	ds_read_u16 v2, v1 offset:6928
	s_waitcnt lgkmcnt(0)
	v_lshlrev_b32_e32 v2, 16, v2
	v_add_f32_e32 v29, v47, v2
	ds_read_u16 v2, v1 offset:7200
	s_waitcnt lgkmcnt(0)
	v_lshlrev_b32_e32 v2, 16, v2
	v_add_f32_e32 v28, v48, v2
	ds_read_u16 v2, v1 offset:7472
	s_waitcnt lgkmcnt(0)
	v_lshlrev_b32_e32 v2, 16, v2
	v_add_f32_e32 v26, v49, v2
	ds_read_u16 v2, v1 offset:192
	s_waitcnt lgkmcnt(0)
	v_lshlrev_b32_e32 v2, 16, v2
	v_add_f32_e32 v19, v50, v2
	ds_read_u16 v2, v1 offset:464
	s_waitcnt lgkmcnt(0)
	v_lshlrev_b32_e32 v2, 16, v2
	v_add_f32_e32 v18, v51, v2
	ds_read_u16 v2, v1 offset:736
	s_waitcnt lgkmcnt(0)
	v_lshlrev_b32_e32 v2, 16, v2
	v_add_f32_e32 v17, v52, v2
	ds_read_u16 v2, v1 offset:1008
	s_waitcnt lgkmcnt(0)
	v_lshlrev_b32_e32 v2, 16, v2
	v_add_f32_e32 v16, v53, v2
	ds_read_u16 v2, v1 offset:2368
	s_waitcnt lgkmcnt(0)
	v_lshlrev_b32_e32 v2, 16, v2
	v_add_f32_e32 v15, v54, v2
	ds_read_u16 v2, v1 offset:2640
	s_waitcnt lgkmcnt(0)
	v_lshlrev_b32_e32 v2, 16, v2
	v_add_f32_e32 v14, v55, v2
	ds_read_u16 v2, v1 offset:2912
	s_waitcnt lgkmcnt(0)
	v_lshlrev_b32_e32 v2, 16, v2
	v_add_f32_e32 v13, v56, v2
	ds_read_u16 v2, v1 offset:3184
	s_waitcnt lgkmcnt(0)
	v_lshlrev_b32_e32 v2, 16, v2
	v_add_f32_e32 v12, v57, v2
	ds_read_u16 v2, v1 offset:4544
	s_waitcnt lgkmcnt(0)
	v_lshlrev_b32_e32 v2, 16, v2
	v_add_f32_e32 v11, v58, v2
	ds_read_u16 v2, v1 offset:4816
	s_waitcnt lgkmcnt(0)
	v_lshlrev_b32_e32 v2, 16, v2
	v_add_f32_e32 v10, v59, v2
	ds_read_u16 v2, v1 offset:5088
	s_waitcnt lgkmcnt(0)
	v_lshlrev_b32_e32 v2, 16, v2
	v_add_f32_e32 v9, v60, v2
	ds_read_u16 v2, v1 offset:5360
	s_waitcnt lgkmcnt(0)
	v_lshlrev_b32_e32 v2, 16, v2
	v_add_f32_e32 v8, v61, v2
	ds_read_u16 v2, v1 offset:6720
	s_waitcnt lgkmcnt(0)
	v_lshlrev_b32_e32 v2, 16, v2
	v_add_f32_e32 v7, v62, v2
	ds_read_u16 v2, v1 offset:6992
	s_waitcnt lgkmcnt(0)
	v_lshlrev_b32_e32 v2, 16, v2
	v_add_f32_e32 v6, v63, v2
	ds_read_u16 v2, v1 offset:7264
	s_waitcnt lgkmcnt(0)
	v_lshlrev_b32_e32 v2, 16, v2
	v_add_f32_e32 v5, v64, v2
	ds_read_u16 v2, v1 offset:7536
	s_waitcnt lgkmcnt(0)
	s_waitcnt lgkmcnt(0)
; DI void gla_stage3(const Ctx& c0, int layer, int unit, int cb, LAS unsigned char* lds) {
;     ...
;     float rs[16];
; #pragma unroll
;     for (int rg = 0; rg < 16; ++rg) { float ss = o[0][rg] * o[0][rg] + o[1][rg] * o[1][rg] + o[2][rg] * o[2][rg] + o[3][rg] * o[3][rg];
;         ss += __shfl_xor(ss, 1); ss += __shfl_xor(ss, 2); ss += __shfl_xor(ss, 4); ss += __shfl_xor(ss, 8); ss += __shfl_xor(ss, 16);
;         rs[rg] = 1.f / sqrtf(ss * (1.f / 128.f) + EPS); }
	v_lshlrev_b32_e32 v2, 16, v2
	v_add_f32_e32 v4, v65, v2
	v_cndmask_b32_e32 v2, v93, v94, vcc
	v_cmp_lt_i32_e32 vcc, v96, v95
	v_lshlrev_b32_e32 v2, 2, v2
	s_nop 0
	v_cndmask_b32_e32 v3, v93, v96, vcc
	v_cmp_lt_i32_e32 vcc, v97, v95
	v_lshlrev_b32_e32 v3, 2, v3
	s_nop 0
	v_cndmask_b32_e32 v20, v93, v97, vcc
	v_cmp_lt_i32_e32 vcc, v98, v95
	v_lshlrev_b32_e32 v20, 2, v20
	s_nop 0
	v_cndmask_b32_e32 v21, v93, v98, vcc
	v_cmp_lt_i32_e32 vcc, v99, v95
	v_lshlrev_b32_e32 v47, 2, v21
	s_nop 0
	v_cndmask_b32_e32 v21, v93, v99, vcc
	v_lshlrev_b32_e32 v48, 2, v21
	v_mul_f32_e32 v21, v122, v122
	v_fmac_f32_e32 v21, v138, v138
	v_fmac_f32_e32 v21, v106, v106
	v_fmac_f32_e32 v21, v19, v19
	s_nop 1
	v_add_f32_dpp v21, v21, v21 quad_perm:[1,0,3,2] row_mask:0xf bank_mask:0xf
	s_nop 1
	v_add_f32_dpp v21, v21, v21 quad_perm:[2,3,0,1] row_mask:0xf bank_mask:0xf
	s_nop 1
	v_add_f32_dpp v21, v21, v21 row_half_mirror row_mask:0xf bank_mask:0xf
	s_nop 1
	v_add_f32_dpp v21, v21, v21 row_mirror row_mask:0xf bank_mask:0xf
	v_mov_b32_e32 v22, v21
	v_mov_b32_e32 v23, v21
	s_nop 1
	v_permlane16_swap_b32_e32 v22, v23
	v_add_f32_e32 v21, v22, v23
	v_fmamk_f32 v21, v21, 0x3c000000, v100
	v_cmp_gt_f32_e32 vcc, s34, v21
	v_mul_f32_e32 v22, 0x4f800000, v21
	s_nop 0
	v_cndmask_b32_e32 v21, v21, v22, vcc
	v_sqrt_f32_e32 v22, v21
	s_nop 0
	v_add_u32_e32 v23, -1, v22
	v_fma_f32 v24, -v23, v22, v21
	v_cmp_ge_f32_e64 s[4:5], 0, v24
	v_add_u32_e32 v24, 1, v22
	s_nop 0
	v_cndmask_b32_e64 v23, v22, v23, s[4:5]
	v_fma_f32 v22, -v24, v22, v21
	v_cmp_lt_f32_e64 s[4:5], 0, v22
	s_nop 1
	v_cndmask_b32_e64 v22, v23, v24, s[4:5]
	v_mul_f32_e32 v23, 0x37800000, v22
	v_cndmask_b32_e32 v22, v22, v23, vcc
	v_cmp_class_f32_e32 vcc, v21, v101
	s_nop 1
	v_cndmask_b32_e32 v21, v22, v21, vcc
	s_nop 0
	v_div_scale_f32 v24, vcc, 1.0, v21, 1.0
	v_rcp_f32_e32 v46, v21
	v_mul_f32_e32 v21, v121, v121
	v_fmac_f32_e32 v21, v137, v137
	v_fmac_f32_e32 v21, v105, v105
	v_fmac_f32_e32 v21, v18, v18
	s_nop 1
	v_add_f32_dpp v21, v21, v21 quad_perm:[1,0,3,2] row_mask:0xf bank_mask:0xf
	v_mul_f32_e32 v19, v19, v46
	s_nop 1
	v_add_f32_dpp v21, v21, v21 quad_perm:[2,3,0,1] row_mask:0xf bank_mask:0xf
	s_nop 1
	v_add_f32_dpp v21, v21, v21 row_half_mirror row_mask:0xf bank_mask:0xf
	s_nop 1
	v_add_f32_dpp v21, v21, v21 row_mirror row_mask:0xf bank_mask:0xf
	v_mov_b32_e32 v22, v21
	v_mov_b32_e32 v23, v21
	s_nop 1
	v_permlane16_swap_b32_e32 v22, v23
	v_add_f32_e32 v21, v22, v23
	v_fmamk_f32 v21, v21, 0x3c000000, v100
	v_cmp_gt_f32_e32 vcc, s34, v21
	v_mul_f32_e32 v22, 0x4f800000, v21
	s_nop 0
	v_cndmask_b32_e32 v21, v21, v22, vcc
	v_sqrt_f32_e32 v22, v21
	s_nop 0
	v_add_u32_e32 v23, -1, v22
	v_fma_f32 v24, -v23, v22, v21
	v_cmp_ge_f32_e64 s[4:5], 0, v24
	v_add_u32_e32 v24, 1, v22
	s_nop 0
	v_cndmask_b32_e64 v23, v22, v23, s[4:5]
	v_fma_f32 v22, -v24, v22, v21
	v_cmp_lt_f32_e64 s[4:5], 0, v22
	s_nop 1
	v_cndmask_b32_e64 v22, v23, v24, s[4:5]
	v_mul_f32_e32 v23, 0x37800000, v22
	v_cndmask_b32_e32 v22, v22, v23, vcc
	v_cmp_class_f32_e32 vcc, v21, v101
	s_nop 1
	v_cndmask_b32_e32 v21, v22, v21, vcc
	s_nop 0
	v_div_scale_f32 v24, vcc, 1.0, v21, 1.0
	v_rcp_f32_e32 v45, v21
	v_mul_f32_e32 v21, v120, v120
	v_fmac_f32_e32 v21, v136, v136
	v_fmac_f32_e32 v21, v104, v104
	v_fmac_f32_e32 v21, v17, v17
	s_nop 1
	v_add_f32_dpp v21, v21, v21 quad_perm:[1,0,3,2] row_mask:0xf bank_mask:0xf
	v_mul_f32_e32 v18, v18, v45
	s_nop 1
	v_add_f32_dpp v21, v21, v21 quad_perm:[2,3,0,1] row_mask:0xf bank_mask:0xf
	s_nop 1
	v_add_f32_dpp v21, v21, v21 row_half_mirror row_mask:0xf bank_mask:0xf
	s_nop 1
	v_add_f32_dpp v21, v21, v21 row_mirror row_mask:0xf bank_mask:0xf
	v_mov_b32_e32 v22, v21
	v_mov_b32_e32 v23, v21
	s_nop 1
	v_permlane16_swap_b32_e32 v22, v23
	v_add_f32_e32 v21, v22, v23
	v_fmamk_f32 v21, v21, 0x3c000000, v100
	v_cmp_gt_f32_e32 vcc, s34, v21
	v_mul_f32_e32 v22, 0x4f800000, v21
	s_nop 0
	v_cndmask_b32_e32 v21, v21, v22, vcc
	v_sqrt_f32_e32 v22, v21
	s_nop 0
	v_add_u32_e32 v23, -1, v22
	v_fma_f32 v24, -v23, v22, v21
	v_cmp_ge_f32_e64 s[4:5], 0, v24
	v_add_u32_e32 v24, 1, v22
	s_nop 0
	v_cndmask_b32_e64 v23, v22, v23, s[4:5]
	v_fma_f32 v22, -v24, v22, v21
	v_cmp_lt_f32_e64 s[4:5], 0, v22
	s_nop 1
	v_cndmask_b32_e64 v22, v23, v24, s[4:5]
	v_mul_f32_e32 v23, 0x37800000, v22
	v_cndmask_b32_e32 v22, v22, v23, vcc
	v_cmp_class_f32_e32 vcc, v21, v101
	s_nop 1
	v_cndmask_b32_e32 v21, v22, v21, vcc
	s_nop 0
	v_div_scale_f32 v24, vcc, 1.0, v21, 1.0
	v_rcp_f32_e32 v44, v21
	v_mul_f32_e32 v21, v119, v119
	v_fmac_f32_e32 v21, v135, v135
	v_fmac_f32_e32 v21, v103, v103
	v_fmac_f32_e32 v21, v16, v16
	s_nop 1
	v_add_f32_dpp v21, v21, v21 quad_perm:[1,0,3,2] row_mask:0xf bank_mask:0xf
	v_mul_f32_e32 v17, v17, v44
	s_nop 1
	v_add_f32_dpp v21, v21, v21 quad_perm:[2,3,0,1] row_mask:0xf bank_mask:0xf
	s_nop 1
	v_add_f32_dpp v21, v21, v21 row_half_mirror row_mask:0xf bank_mask:0xf
	s_nop 1
	v_add_f32_dpp v21, v21, v21 row_mirror row_mask:0xf bank_mask:0xf
	v_mov_b32_e32 v22, v21
	v_mov_b32_e32 v23, v21
	s_nop 1
	v_permlane16_swap_b32_e32 v22, v23
	v_add_f32_e32 v21, v22, v23
	v_fmamk_f32 v21, v21, 0x3c000000, v100
	v_cmp_gt_f32_e32 vcc, s34, v21
	v_mul_f32_e32 v22, 0x4f800000, v21
	s_nop 0
	v_cndmask_b32_e32 v21, v21, v22, vcc
	v_sqrt_f32_e32 v22, v21
	s_nop 0
	v_add_u32_e32 v23, -1, v22
	v_fma_f32 v24, -v23, v22, v21
	v_cmp_ge_f32_e64 s[4:5], 0, v24
	v_add_u32_e32 v24, 1, v22
	s_nop 0
	v_cndmask_b32_e64 v23, v22, v23, s[4:5]
	v_fma_f32 v22, -v24, v22, v21
	v_cmp_lt_f32_e64 s[4:5], 0, v22
	s_nop 1
	v_cndmask_b32_e64 v22, v23, v24, s[4:5]
	v_mul_f32_e32 v23, 0x37800000, v22
	v_cndmask_b32_e32 v22, v22, v23, vcc
	v_cmp_class_f32_e32 vcc, v21, v101
	s_nop 1
; DI void gla_stage3(const Ctx& c0, int layer, int unit, int cb, LAS unsigned char* lds) {
;     ...
;     float rs[16];
; #pragma unroll
;     for (int rg = 0; rg < 16; ++rg) { float ss = o[0][rg] * o[0][rg] + o[1][rg] * o[1][rg] + o[2][rg] * o[2][rg] + o[3][rg] * o[3][rg];
;         ss += __shfl_xor(ss, 1); ss += __shfl_xor(ss, 2); ss += __shfl_xor(ss, 4); ss += __shfl_xor(ss, 8); ss += __shfl_xor(ss, 16);
;         rs[rg] = 1.f / sqrtf(ss * (1.f / 128.f) + EPS); }
	v_cndmask_b32_e32 v21, v22, v21, vcc
	s_nop 0
	v_div_scale_f32 v24, vcc, 1.0, v21, 1.0
	v_rcp_f32_e32 v43, v21
	v_mul_f32_e32 v21, v118, v118
	v_fmac_f32_e32 v21, v134, v134
	v_fmac_f32_e32 v21, v102, v102
	v_fmac_f32_e32 v21, v15, v15
	s_nop 1
	v_add_f32_dpp v21, v21, v21 quad_perm:[1,0,3,2] row_mask:0xf bank_mask:0xf
	v_mul_f32_e32 v16, v16, v43
	s_nop 1
	v_add_f32_dpp v21, v21, v21 quad_perm:[2,3,0,1] row_mask:0xf bank_mask:0xf
	s_nop 1
	v_add_f32_dpp v21, v21, v21 row_half_mirror row_mask:0xf bank_mask:0xf
	s_nop 1
	v_add_f32_dpp v21, v21, v21 row_mirror row_mask:0xf bank_mask:0xf
	v_mov_b32_e32 v22, v21
	v_mov_b32_e32 v23, v21
	s_nop 1
	v_permlane16_swap_b32_e32 v22, v23
	v_add_f32_e32 v21, v22, v23
	v_fmamk_f32 v21, v21, 0x3c000000, v100
	v_cmp_gt_f32_e32 vcc, s34, v21
	v_mul_f32_e32 v22, 0x4f800000, v21
	s_nop 0
	v_cndmask_b32_e32 v21, v21, v22, vcc
	v_sqrt_f32_e32 v22, v21
	s_nop 0
	v_add_u32_e32 v23, -1, v22
	v_fma_f32 v24, -v23, v22, v21
	v_cmp_ge_f32_e64 s[4:5], 0, v24
	v_add_u32_e32 v24, 1, v22
	s_nop 0
	v_cndmask_b32_e64 v23, v22, v23, s[4:5]
	v_fma_f32 v22, -v24, v22, v21
	v_cmp_lt_f32_e64 s[4:5], 0, v22
	s_nop 1
	v_cndmask_b32_e64 v22, v23, v24, s[4:5]
	v_mul_f32_e32 v23, 0x37800000, v22
	v_cndmask_b32_e32 v22, v22, v23, vcc
	v_cmp_class_f32_e32 vcc, v21, v101
	s_nop 1
	v_cndmask_b32_e32 v21, v22, v21, vcc
	s_nop 0
	v_div_scale_f32 v24, vcc, 1.0, v21, 1.0
	v_rcp_f32_e32 v42, v21
	v_mul_f32_e32 v21, v117, v117
	v_fmac_f32_e32 v21, v133, v133
	v_fmac_f32_e32 v21, v39, v39
	v_fmac_f32_e32 v21, v14, v14
	s_nop 1
	v_add_f32_dpp v21, v21, v21 quad_perm:[1,0,3,2] row_mask:0xf bank_mask:0xf
	v_mul_f32_e32 v15, v15, v42
	s_nop 1
	v_add_f32_dpp v21, v21, v21 quad_perm:[2,3,0,1] row_mask:0xf bank_mask:0xf
	s_nop 1
	v_add_f32_dpp v21, v21, v21 row_half_mirror row_mask:0xf bank_mask:0xf
	s_nop 1
	v_add_f32_dpp v21, v21, v21 row_mirror row_mask:0xf bank_mask:0xf
	v_mov_b32_e32 v22, v21
	v_mov_b32_e32 v23, v21
	s_nop 1
	v_permlane16_swap_b32_e32 v22, v23
	v_add_f32_e32 v21, v22, v23
	v_fmamk_f32 v21, v21, 0x3c000000, v100
	v_cmp_gt_f32_e32 vcc, s34, v21
	v_mul_f32_e32 v22, 0x4f800000, v21
	s_nop 0
	v_cndmask_b32_e32 v21, v21, v22, vcc
	v_sqrt_f32_e32 v22, v21
	s_nop 0
	v_add_u32_e32 v23, -1, v22
	v_fma_f32 v24, -v23, v22, v21
	v_cmp_ge_f32_e64 s[4:5], 0, v24
	v_add_u32_e32 v24, 1, v22
	s_nop 0
	v_cndmask_b32_e64 v23, v22, v23, s[4:5]
	v_fma_f32 v22, -v24, v22, v21
	v_cmp_lt_f32_e64 s[4:5], 0, v22
	s_nop 1
	v_cndmask_b32_e64 v22, v23, v24, s[4:5]
	v_mul_f32_e32 v23, 0x37800000, v22
	v_cndmask_b32_e32 v22, v22, v23, vcc
	v_cmp_class_f32_e32 vcc, v21, v101
	s_nop 1
	v_cndmask_b32_e32 v21, v22, v21, vcc
	s_nop 0
	v_div_scale_f32 v24, vcc, 1.0, v21, 1.0
	v_rcp_f32_e32 v41, v21
	v_mul_f32_e32 v21, v116, v116
	v_fmac_f32_e32 v21, v132, v132
	v_fmac_f32_e32 v21, v38, v38
	v_fmac_f32_e32 v21, v13, v13
	s_nop 1
	v_add_f32_dpp v21, v21, v21 quad_perm:[1,0,3,2] row_mask:0xf bank_mask:0xf
	v_mul_f32_e32 v39, v39, v41
	v_mul_f32_e32 v14, v14, v41
	s_nop 1
	v_add_f32_dpp v21, v21, v21 quad_perm:[2,3,0,1] row_mask:0xf bank_mask:0xf
	s_nop 1
	v_add_f32_dpp v21, v21, v21 row_half_mirror row_mask:0xf bank_mask:0xf
	s_nop 1
	v_add_f32_dpp v21, v21, v21 row_mirror row_mask:0xf bank_mask:0xf
	v_mov_b32_e32 v22, v21
	v_mov_b32_e32 v23, v21
	s_nop 1
	v_permlane16_swap_b32_e32 v22, v23
	v_add_f32_e32 v21, v22, v23
	v_fmamk_f32 v21, v21, 0x3c000000, v100
	v_cmp_gt_f32_e32 vcc, s34, v21
	v_mul_f32_e32 v22, 0x4f800000, v21
	s_nop 0
	v_cndmask_b32_e32 v21, v21, v22, vcc
	v_sqrt_f32_e32 v22, v21
	s_nop 0
	v_add_u32_e32 v23, -1, v22
	v_fma_f32 v24, -v23, v22, v21
	v_cmp_ge_f32_e64 s[4:5], 0, v24
	v_add_u32_e32 v24, 1, v22
	s_nop 0
	v_cndmask_b32_e64 v23, v22, v23, s[4:5]
	v_fma_f32 v22, -v24, v22, v21
	v_cmp_lt_f32_e64 s[4:5], 0, v22
	s_nop 1
	v_cndmask_b32_e64 v22, v23, v24, s[4:5]
	v_mul_f32_e32 v23, 0x37800000, v22
	v_cndmask_b32_e32 v22, v22, v23, vcc
	v_cmp_class_f32_e32 vcc, v21, v101
	s_nop 1
	v_cndmask_b32_e32 v21, v22, v21, vcc
	s_nop 0
	v_div_scale_f32 v24, vcc, 1.0, v21, 1.0
	v_rcp_f32_e32 v40, v21
	v_mul_f32_e32 v21, v115, v115
	v_fmac_f32_e32 v21, v131, v131
	v_fmac_f32_e32 v21, v37, v37
	v_fmac_f32_e32 v21, v12, v12
	s_nop 1
	v_add_f32_dpp v21, v21, v21 quad_perm:[1,0,3,2] row_mask:0xf bank_mask:0xf
	v_mul_f32_e32 v38, v38, v40
	v_mul_f32_e32 v13, v13, v40
	s_nop 1
	v_add_f32_dpp v21, v21, v21 quad_perm:[2,3,0,1] row_mask:0xf bank_mask:0xf
	s_nop 1
	v_add_f32_dpp v21, v21, v21 row_half_mirror row_mask:0xf bank_mask:0xf
	s_nop 1
	v_add_f32_dpp v21, v21, v21 row_mirror row_mask:0xf bank_mask:0xf
	v_mov_b32_e32 v22, v21
	v_mov_b32_e32 v23, v21
	s_nop 1
	v_permlane16_swap_b32_e32 v22, v23
	v_add_f32_e32 v21, v22, v23
	v_fmamk_f32 v21, v21, 0x3c000000, v100
	v_cmp_gt_f32_e32 vcc, s34, v21
	v_mul_f32_e32 v22, 0x4f800000, v21
	s_nop 0
	v_cndmask_b32_e32 v21, v21, v22, vcc
	v_sqrt_f32_e32 v22, v21
	s_nop 0
	v_add_u32_e32 v23, -1, v22
	v_fma_f32 v24, -v23, v22, v21
	v_cmp_ge_f32_e64 s[4:5], 0, v24
	v_add_u32_e32 v24, 1, v22
	s_nop 0
	v_cndmask_b32_e64 v23, v22, v23, s[4:5]
	v_fma_f32 v22, -v24, v22, v21
	v_cmp_lt_f32_e64 s[4:5], 0, v22
	s_nop 1
	v_cndmask_b32_e64 v22, v23, v24, s[4:5]
	v_mul_f32_e32 v23, 0x37800000, v22
	v_cndmask_b32_e32 v22, v22, v23, vcc
	v_cmp_class_f32_e32 vcc, v21, v101
	s_nop 1
	v_cndmask_b32_e32 v21, v22, v21, vcc
	s_nop 0
	v_div_scale_f32 v24, vcc, 1.0, v21, 1.0
	v_rcp_f32_e32 v35, v21
	v_mul_f32_e32 v21, v114, v114
	v_fmac_f32_e32 v21, v130, v130
	v_fmac_f32_e32 v21, v36, v36
	v_fmac_f32_e32 v21, v11, v11
	s_nop 1
	v_add_f32_dpp v21, v21, v21 quad_perm:[1,0,3,2] row_mask:0xf bank_mask:0xf
	v_mul_f32_e32 v37, v37, v35
	v_mul_f32_e32 v12, v12, v35
; DI void gla_stage3(const Ctx& c0, int layer, int unit, int cb, LAS unsigned char* lds) {
;     ...
;     for (int rg = 0; rg < 16; ++rg) { float ss = o[0][rg] * o[0][rg] + o[1][rg] * o[1][rg] + o[2][rg] * o[2][rg] + o[3][rg] * o[3][rg];
;         ss += __shfl_xor(ss, 1); ss += __shfl_xor(ss, 2); ss += __shfl_xor(ss, 4); ss += __shfl_xor(ss, 8); ss += __shfl_xor(ss, 16);
;         rs[rg] = 1.f / sqrtf(ss * (1.f / 128.f) + EPS); }
	s_nop 1
	v_add_f32_dpp v21, v21, v21 quad_perm:[2,3,0,1] row_mask:0xf bank_mask:0xf
	s_nop 1
	v_add_f32_dpp v21, v21, v21 row_half_mirror row_mask:0xf bank_mask:0xf
	s_nop 1
	v_add_f32_dpp v21, v21, v21 row_mirror row_mask:0xf bank_mask:0xf
	v_mov_b32_e32 v22, v21
	v_mov_b32_e32 v23, v21
	s_nop 1
	v_permlane16_swap_b32_e32 v22, v23
	v_add_f32_e32 v21, v22, v23
	v_fmamk_f32 v21, v21, 0x3c000000, v100
	v_cmp_gt_f32_e32 vcc, s34, v21
	v_mul_f32_e32 v22, 0x4f800000, v21
	s_nop 0
	v_cndmask_b32_e32 v21, v21, v22, vcc
	v_sqrt_f32_e32 v22, v21
	s_nop 0
	v_add_u32_e32 v23, -1, v22
	v_fma_f32 v24, -v23, v22, v21
	v_cmp_ge_f32_e64 s[4:5], 0, v24
	v_add_u32_e32 v24, 1, v22
	s_nop 0
	v_cndmask_b32_e64 v23, v22, v23, s[4:5]
	v_fma_f32 v22, -v24, v22, v21
	v_cmp_lt_f32_e64 s[4:5], 0, v22
	s_nop 1
	v_cndmask_b32_e64 v22, v23, v24, s[4:5]
	v_mul_f32_e32 v23, 0x37800000, v22
	v_cndmask_b32_e32 v22, v22, v23, vcc
	v_cmp_class_f32_e32 vcc, v21, v101
	s_nop 1
	v_cndmask_b32_e32 v21, v22, v21, vcc
	s_nop 0
	v_div_scale_f32 v24, vcc, 1.0, v21, 1.0
	v_rcp_f32_e32 v31, v21
	v_mul_f32_e32 v21, v113, v113
	v_fmac_f32_e32 v21, v129, v129
	v_fmac_f32_e32 v21, v34, v34
	v_fmac_f32_e32 v21, v10, v10
	s_nop 1
	v_add_f32_dpp v21, v21, v21 quad_perm:[1,0,3,2] row_mask:0xf bank_mask:0xf
	v_mul_f32_e32 v36, v36, v31
	v_mul_f32_e32 v11, v11, v31
	s_nop 1
	v_add_f32_dpp v21, v21, v21 quad_perm:[2,3,0,1] row_mask:0xf bank_mask:0xf
	s_nop 1
	v_add_f32_dpp v21, v21, v21 row_half_mirror row_mask:0xf bank_mask:0xf
	s_nop 1
	v_add_f32_dpp v21, v21, v21 row_mirror row_mask:0xf bank_mask:0xf
	v_mov_b32_e32 v22, v21
	v_mov_b32_e32 v23, v21
	s_nop 1
	v_permlane16_swap_b32_e32 v22, v23
	v_add_f32_e32 v21, v22, v23
	v_fmamk_f32 v21, v21, 0x3c000000, v100
	v_cmp_gt_f32_e32 vcc, s34, v21
	v_mul_f32_e32 v22, 0x4f800000, v21
	s_nop 0
	v_cndmask_b32_e32 v21, v21, v22, vcc
	v_sqrt_f32_e32 v22, v21
	s_nop 0
	v_add_u32_e32 v23, -1, v22
	v_fma_f32 v24, -v23, v22, v21
	v_cmp_ge_f32_e64 s[4:5], 0, v24
	v_add_u32_e32 v24, 1, v22
	s_nop 0
	v_cndmask_b32_e64 v23, v22, v23, s[4:5]
	v_fma_f32 v22, -v24, v22, v21
	v_cmp_lt_f32_e64 s[4:5], 0, v22
	s_nop 1
	v_cndmask_b32_e64 v22, v23, v24, s[4:5]
	v_mul_f32_e32 v23, 0x37800000, v22
	v_cndmask_b32_e32 v22, v22, v23, vcc
	v_cmp_class_f32_e32 vcc, v21, v101
	s_nop 1
	v_cndmask_b32_e32 v21, v22, v21, vcc
	s_nop 0
	v_div_scale_f32 v24, vcc, 1.0, v21, 1.0
	v_rcp_f32_e32 v27, v21
	v_mul_f32_e32 v21, v112, v112
	v_fmac_f32_e32 v21, v128, v128
	v_fmac_f32_e32 v21, v33, v33
	v_fmac_f32_e32 v21, v9, v9
	s_nop 1
	v_add_f32_dpp v21, v21, v21 quad_perm:[1,0,3,2] row_mask:0xf bank_mask:0xf
	v_mul_f32_e32 v34, v34, v27
	v_mul_f32_e32 v10, v10, v27
	s_nop 1
	v_add_f32_dpp v21, v21, v21 quad_perm:[2,3,0,1] row_mask:0xf bank_mask:0xf
	s_nop 1
	v_add_f32_dpp v21, v21, v21 row_half_mirror row_mask:0xf bank_mask:0xf
	s_nop 1
	v_add_f32_dpp v21, v21, v21 row_mirror row_mask:0xf bank_mask:0xf
	v_mov_b32_e32 v22, v21
	v_mov_b32_e32 v23, v21
	s_nop 1
	v_permlane16_swap_b32_e32 v22, v23
	v_add_f32_e32 v21, v22, v23
	v_fmamk_f32 v21, v21, 0x3c000000, v100
	v_cmp_gt_f32_e32 vcc, s34, v21
	v_mul_f32_e32 v22, 0x4f800000, v21
	s_nop 0
	v_cndmask_b32_e32 v21, v21, v22, vcc
	v_sqrt_f32_e32 v22, v21
	s_nop 0
	v_add_u32_e32 v23, -1, v22
	v_fma_f32 v24, -v23, v22, v21
	v_cmp_ge_f32_e64 s[4:5], 0, v24
	v_add_u32_e32 v24, 1, v22
	s_nop 0
	v_cndmask_b32_e64 v23, v22, v23, s[4:5]
	v_fma_f32 v22, -v24, v22, v21
	v_cmp_lt_f32_e64 s[4:5], 0, v22
	s_nop 1
	v_cndmask_b32_e64 v22, v23, v24, s[4:5]
	v_mul_f32_e32 v23, 0x37800000, v22
	v_cndmask_b32_e32 v22, v22, v23, vcc
	v_cmp_class_f32_e32 vcc, v21, v101
	s_nop 1
	v_cndmask_b32_e32 v21, v22, v21, vcc
	s_nop 0
	v_div_scale_f32 v24, vcc, 1.0, v21, 1.0
	v_rcp_f32_e32 v25, v21
	v_mul_f32_e32 v21, v111, v111
	v_fmac_f32_e32 v21, v127, v127
	v_fmac_f32_e32 v21, v32, v32
	v_fmac_f32_e32 v21, v8, v8
	s_nop 1
	v_add_f32_dpp v21, v21, v21 quad_perm:[1,0,3,2] row_mask:0xf bank_mask:0xf
	v_mul_f32_e32 v33, v33, v25
	v_mul_f32_e32 v9, v9, v25
	s_nop 1
	v_add_f32_dpp v21, v21, v21 quad_perm:[2,3,0,1] row_mask:0xf bank_mask:0xf
	s_nop 1
	v_add_f32_dpp v21, v21, v21 row_half_mirror row_mask:0xf bank_mask:0xf
	s_nop 1
	v_add_f32_dpp v21, v21, v21 row_mirror row_mask:0xf bank_mask:0xf
	v_mov_b32_e32 v22, v21
	v_mov_b32_e32 v23, v21
	s_nop 1
	v_permlane16_swap_b32_e32 v22, v23
	v_add_f32_e32 v21, v22, v23
	v_fmamk_f32 v21, v21, 0x3c000000, v100
	v_cmp_gt_f32_e32 vcc, s34, v21
	v_mul_f32_e32 v22, 0x4f800000, v21
	s_nop 0
	v_cndmask_b32_e32 v21, v21, v22, vcc
	v_sqrt_f32_e32 v22, v21
	s_nop 0
	v_add_u32_e32 v23, -1, v22
	v_fma_f32 v24, -v23, v22, v21
	v_cmp_ge_f32_e64 s[4:5], 0, v24
	v_add_u32_e32 v24, 1, v22
	s_nop 0
	v_cndmask_b32_e64 v23, v22, v23, s[4:5]
	v_fma_f32 v22, -v24, v22, v21
	v_cmp_lt_f32_e64 s[4:5], 0, v22
	s_nop 1
	v_cndmask_b32_e64 v22, v23, v24, s[4:5]
	v_mul_f32_e32 v23, 0x37800000, v22
	v_cndmask_b32_e32 v22, v22, v23, vcc
	v_cmp_class_f32_e32 vcc, v21, v101
	s_nop 1
	v_cndmask_b32_e32 v21, v22, v21, vcc
	s_nop 0
	v_div_scale_f32 v24, vcc, 1.0, v21, 1.0
	v_rcp_f32_e32 v24, v21
	v_mul_f32_e32 v21, v110, v110
	v_fmac_f32_e32 v21, v126, v126
	v_fmac_f32_e32 v21, v30, v30
	v_fmac_f32_e32 v21, v7, v7
	s_nop 1
	v_add_f32_dpp v21, v21, v21 quad_perm:[1,0,3,2] row_mask:0xf bank_mask:0xf
	v_mul_f32_e32 v32, v32, v24
	v_mul_f32_e32 v8, v8, v24
	s_nop 1
	v_add_f32_dpp v21, v21, v21 quad_perm:[2,3,0,1] row_mask:0xf bank_mask:0xf
	s_nop 1
	v_add_f32_dpp v21, v21, v21 row_half_mirror row_mask:0xf bank_mask:0xf
	s_nop 1
	v_add_f32_dpp v21, v21, v21 row_mirror row_mask:0xf bank_mask:0xf
	v_mov_b32_e32 v22, v21
	v_mov_b32_e32 v23, v21
	s_nop 1
	v_permlane16_swap_b32_e32 v22, v23
; #define LAS __attribute__((address_space(3)))
; #define LDS_WAIT() asm volatile("s_waitcnt lgkmcnt(0)" ::: "memory")
; DI unsigned cvtpk(float lo, float hi) { f32x2 v = {lo, hi}; bf16x2_t b = __builtin_convertvector(v, bf16x2_t); return __builtin_bit_cast(unsigned, b); }
; DI float bf2f(bf16 b) { return __uint_as_float(((unsigned)b) << 16); }
; DI float siluf_(float x) { return x / (1.f + __expf(-x)); }
; DI void gla_stage3(const Ctx& c0, int layer, int unit, int cb, LAS unsigned char* lds) {
;     ...
;     for (int rg = 0; rg < 16; ++rg) { float ss = o[0][rg] * o[0][rg] + o[1][rg] * o[1][rg] + o[2][rg] * o[2][rg] + o[3][rg] * o[3][rg];
;         ss += __shfl_xor(ss, 1); ss += __shfl_xor(ss, 2); ss += __shfl_xor(ss, 4); ss += __shfl_xor(ss, 8); ss += __shfl_xor(ss, 16);
;         rs[rg] = 1.f / sqrtf(ss * (1.f / 128.f) + EPS); }
;     LDS_WAIT();
;     g3_tile_in((const bf16*)(c.ws + O_GR) + row0 * 512 + h * 128, R, lane);
; #pragma unroll
;     for (int vb = 0; vb < 4; ++vb) { const float g = gn[32 * vb + r];
; #pragma unroll
;         for (int rg = 0; rg < 16; ++rg) { LAS bf16* e = (LAS bf16*)(R + (4 * hi) * G3_PITCH + r * 2 + ((rg & 3) + 8 * (rg >> 2)) * G3_PITCH + 64 * vb);
;             const float z = bf2f(*e);
;             *e = (bf16)(cvtpk(o[vb][rg] * rs[rg] * g * siluf_(z), 0.f) & 0xffffu); }
	v_add_f32_e32 v21, v22, v23
	v_fmamk_f32 v21, v21, 0x3c000000, v100
	v_cmp_gt_f32_e32 vcc, s34, v21
	v_mul_f32_e32 v22, 0x4f800000, v21
	s_nop 0
	v_cndmask_b32_e32 v21, v21, v22, vcc
	v_sqrt_f32_e32 v22, v21
	s_nop 0
	v_add_u32_e32 v23, -1, v22
	v_fma_f32 v49, -v23, v22, v21
	v_cmp_ge_f32_e64 s[4:5], 0, v49
	v_add_u32_e32 v49, 1, v22
	s_nop 0
	v_cndmask_b32_e64 v23, v22, v23, s[4:5]
	v_fma_f32 v22, -v49, v22, v21
	v_cmp_lt_f32_e64 s[4:5], 0, v22
	s_nop 1
	v_cndmask_b32_e64 v22, v23, v49, s[4:5]
	v_mul_f32_e32 v23, 0x37800000, v22
	v_cndmask_b32_e32 v22, v22, v23, vcc
	v_cmp_class_f32_e32 vcc, v21, v101
	s_nop 1
	v_cndmask_b32_e32 v21, v22, v21, vcc
	s_nop 0
	v_div_scale_f32 v49, vcc, 1.0, v21, 1.0
	v_rcp_f32_e32 v23, v21
	v_mul_f32_e32 v21, v109, v109
	v_fmac_f32_e32 v21, v125, v125
	v_fmac_f32_e32 v21, v29, v29
	v_fmac_f32_e32 v21, v6, v6
	s_nop 1
	v_add_f32_dpp v21, v21, v21 quad_perm:[1,0,3,2] row_mask:0xf bank_mask:0xf
	v_mul_f32_e32 v30, v30, v23
	v_mul_f32_e32 v7, v7, v23
	s_nop 1
	v_add_f32_dpp v21, v21, v21 quad_perm:[2,3,0,1] row_mask:0xf bank_mask:0xf
	s_nop 1
	v_add_f32_dpp v21, v21, v21 row_half_mirror row_mask:0xf bank_mask:0xf
	s_nop 1
	v_add_f32_dpp v21, v21, v21 row_mirror row_mask:0xf bank_mask:0xf
	v_mov_b32_e32 v22, v21
	v_mov_b32_e32 v49, v21
	s_nop 1
	v_permlane16_swap_b32_e32 v22, v49
	v_add_f32_e32 v21, v22, v49
	v_fmamk_f32 v21, v21, 0x3c000000, v100
	v_cmp_gt_f32_e32 vcc, s34, v21
	v_mul_f32_e32 v22, 0x4f800000, v21
	s_nop 0
	v_cndmask_b32_e32 v21, v21, v22, vcc
	v_sqrt_f32_e32 v22, v21
	s_nop 0
	v_add_u32_e32 v49, -1, v22
	v_fma_f32 v50, -v49, v22, v21
	v_cmp_ge_f32_e64 s[4:5], 0, v50
	v_add_u32_e32 v50, 1, v22
	s_nop 0
	v_cndmask_b32_e64 v49, v22, v49, s[4:5]
	v_fma_f32 v22, -v50, v22, v21
	v_cmp_lt_f32_e64 s[4:5], 0, v22
	s_nop 1
	v_cndmask_b32_e64 v22, v49, v50, s[4:5]
	v_mul_f32_e32 v49, 0x37800000, v22
	v_cndmask_b32_e32 v22, v22, v49, vcc
	v_cmp_class_f32_e32 vcc, v21, v101
	s_nop 1
	v_cndmask_b32_e32 v21, v22, v21, vcc
	s_nop 0
	v_div_scale_f32 v50, vcc, 1.0, v21, 1.0
	v_rcp_f32_e32 v22, v21
	v_mul_f32_e32 v21, v108, v108
	v_fmac_f32_e32 v21, v124, v124
	v_fmac_f32_e32 v21, v28, v28
	v_fmac_f32_e32 v21, v5, v5
	s_nop 1
	v_add_f32_dpp v21, v21, v21 quad_perm:[1,0,3,2] row_mask:0xf bank_mask:0xf
	v_mul_f32_e32 v29, v29, v22
	v_mul_f32_e32 v6, v6, v22
	s_nop 1
	v_add_f32_dpp v21, v21, v21 quad_perm:[2,3,0,1] row_mask:0xf bank_mask:0xf
	s_nop 1
	v_add_f32_dpp v21, v21, v21 row_half_mirror row_mask:0xf bank_mask:0xf
	s_nop 1
	v_add_f32_dpp v21, v21, v21 row_mirror row_mask:0xf bank_mask:0xf
	v_mov_b32_e32 v49, v21
	v_mov_b32_e32 v50, v21
	s_nop 1
	v_permlane16_swap_b32_e32 v49, v50
	v_add_f32_e32 v21, v49, v50
	v_fmamk_f32 v21, v21, 0x3c000000, v100
	v_cmp_gt_f32_e32 vcc, s34, v21
	v_mul_f32_e32 v49, 0x4f800000, v21
	s_nop 0
	v_cndmask_b32_e32 v21, v21, v49, vcc
	v_sqrt_f32_e32 v49, v21
	s_nop 0
	v_add_u32_e32 v50, -1, v49
	v_fma_f32 v51, -v50, v49, v21
	v_cmp_ge_f32_e64 s[4:5], 0, v51
	v_add_u32_e32 v51, 1, v49
	s_nop 0
	v_cndmask_b32_e64 v50, v49, v50, s[4:5]
	v_fma_f32 v49, -v51, v49, v21
	v_cmp_lt_f32_e64 s[4:5], 0, v49
	s_nop 1
	v_cndmask_b32_e64 v49, v50, v51, s[4:5]
	v_mul_f32_e32 v50, 0x37800000, v49
	v_cndmask_b32_e32 v49, v49, v50, vcc
	v_cmp_class_f32_e32 vcc, v21, v101
	s_nop 1
	v_cndmask_b32_e32 v21, v49, v21, vcc
	s_nop 0
	v_div_scale_f32 v51, vcc, 1.0, v21, 1.0
	v_rcp_f32_e32 v21, v21
	v_mul_f32_e32 v49, v107, v107
	v_fmac_f32_e32 v49, v123, v123
	v_fmac_f32_e32 v49, v26, v26
	v_fmac_f32_e32 v49, v4, v4
	ds_bpermute_b32 v2, v2, v49
	v_mul_f32_e32 v28, v28, v21
	v_mul_f32_e32 v5, v5, v21
	s_waitcnt lgkmcnt(0)
	v_add_f32_e32 v2, v49, v2
	ds_bpermute_b32 v3, v3, v2
	s_waitcnt lgkmcnt(0)
	v_add_f32_e32 v2, v2, v3
	ds_bpermute_b32 v3, v20, v2
	s_waitcnt lgkmcnt(0)
	v_add_f32_e32 v2, v2, v3
	ds_bpermute_b32 v3, v47, v2
	s_waitcnt lgkmcnt(0)
	v_add_f32_e32 v2, v2, v3
	ds_bpermute_b32 v3, v48, v2
	s_waitcnt lgkmcnt(0)
	v_add_f32_e32 v2, v2, v3
	v_fmamk_f32 v2, v2, 0x3c000000, v100
	v_cmp_gt_f32_e32 vcc, s34, v2
	v_mul_f32_e32 v3, 0x4f800000, v2
	s_nop 0
	v_cndmask_b32_e32 v2, v2, v3, vcc
	v_sqrt_f32_e32 v3, v2
	s_nop 0
	v_add_u32_e32 v20, -1, v3
	v_fma_f32 v47, -v20, v3, v2
	v_cmp_ge_f32_e64 s[4:5], 0, v47
	v_add_u32_e32 v47, 1, v3
	s_nop 0
	v_cndmask_b32_e64 v20, v3, v20, s[4:5]
	v_fma_f32 v3, -v47, v3, v2
	v_cmp_lt_f32_e64 s[4:5], 0, v3
	s_nop 1
	v_cndmask_b32_e64 v3, v20, v47, s[4:5]
	v_mul_f32_e32 v20, 0x37800000, v3
	v_cndmask_b32_e32 v3, v3, v20, vcc
	v_cmp_class_f32_e32 vcc, v2, v101
	s_nop 1
	v_cndmask_b32_e32 v2, v3, v2, vcc
	s_nop 0
	v_rcp_f32_e32 v20, v2
	v_mul_f32_e32 v47, v138, v46
	v_mul_f32_e32 v26, v26, v20
	v_mul_f32_e32 v4, v4, v20
	s_waitcnt vmcnt(2) lgkmcnt(0)
	ds_write_b128 v92, v[164:167]
	s_waitcnt vmcnt(0) lgkmcnt(0)
	ds_write_b128 v92, v[170:173] offset:1088
	s_waitcnt vmcnt(13) lgkmcnt(0)
	ds_write_b128 v92, v[174:177] offset:2176
	s_waitcnt vmcnt(8) lgkmcnt(0)
	ds_write_b128 v92, v[178:181] offset:3264
	s_waitcnt vmcnt(9) lgkmcnt(0)
	ds_write_b128 v92, v[196:199] offset:4352
	s_waitcnt vmcnt(10) lgkmcnt(0)
	ds_write_b128 v92, v[200:203] offset:5440
	v_lshl_add_u64 v[2:3], v[168:169], 0, v[80:81]
	s_waitcnt vmcnt(5) lgkmcnt(0)
	ds_write_b128 v92, v[204:207] offset:6528
	global_load_dwordx4 v[48:51], v[2:3], off
	s_waitcnt vmcnt(0) lgkmcnt(0)
	ds_write_b128 v92, v[48:51] offset:7616
	s_waitcnt lgkmcnt(0)
	ds_read_u16 v3, v1
	s_waitcnt lgkmcnt(0)
	v_lshlrev_b32_e32 v3, 16, v3
	v_mul_f32_e32 v48, 0xbfb8aa3b, v3
	v_exp_f32_e32 v48, v48
	s_waitcnt vmcnt(0)
; #define LAS __attribute__((address_space(3)))
; DI unsigned cvtpk(float lo, float hi) { f32x2 v = {lo, hi}; bf16x2_t b = __builtin_convertvector(v, bf16x2_t); return __builtin_bit_cast(unsigned, b); }
; DI float bf2f(bf16 b) { return __uint_as_float(((unsigned)b) << 16); }
; DI float siluf_(float x) { return x / (1.f + __expf(-x)); }
; DI void gla_stage3(const Ctx& c0, int layer, int unit, int cb, LAS unsigned char* lds) {
;     ...
;     for (int vb = 0; vb < 4; ++vb) { const float g = gn[32 * vb + r];
; #pragma unroll
;         for (int rg = 0; rg < 16; ++rg) { LAS bf16* e = (LAS bf16*)(R + (4 * hi) * G3_PITCH + r * 2 + ((rg & 3) + 8 * (rg >> 2)) * G3_PITCH + 64 * vb);
;             const float z = bf2f(*e);
;             *e = (bf16)(cvtpk(o[vb][rg] * rs[rg] * g * siluf_(z), 0.f) & 0xffffu); }
	v_mul_f32_e32 v47, v47, v232
	v_add_f32_e32 v48, 1.0, v48
	v_rcp_f32_e32 v49, v48
	s_nop 0
	v_mul_f32_e32 v3, v3, v49
	v_mul_f32_e32 v3, v47, v3
	v_cvt_pk_bf16_f32 v3, v3, v3
	ds_write_b16 v1, v3
	ds_read_u16 v3, v1 offset:272
	v_mul_f32_e32 v47, v137, v45
	v_mul_f32_e32 v47, v47, v232
	s_waitcnt lgkmcnt(0)
	v_lshlrev_b32_e32 v3, 16, v3
	v_mul_f32_e32 v48, 0xbfb8aa3b, v3
	v_exp_f32_e32 v48, v48
	s_nop 0
	v_add_f32_e32 v48, 1.0, v48
	v_rcp_f32_e32 v49, v48
	s_nop 0
	v_mul_f32_e32 v3, v3, v49
	v_mul_f32_e32 v3, v47, v3
	v_cvt_pk_bf16_f32 v3, v3, v3
	ds_write_b16 v1, v3 offset:272
	ds_read_u16 v3, v1 offset:544
	v_mul_f32_e32 v47, v136, v44
	v_mul_f32_e32 v47, v47, v232
	s_waitcnt lgkmcnt(0)
	v_lshlrev_b32_e32 v3, 16, v3
	v_mul_f32_e32 v48, 0xbfb8aa3b, v3
	v_exp_f32_e32 v48, v48
	s_nop 0
	v_add_f32_e32 v48, 1.0, v48
	v_rcp_f32_e32 v49, v48
	s_nop 0
	v_mul_f32_e32 v3, v3, v49
	v_mul_f32_e32 v3, v47, v3
	v_cvt_pk_bf16_f32 v3, v3, v3
	ds_write_b16 v1, v3 offset:544
	ds_read_u16 v3, v1 offset:816
	v_mul_f32_e32 v47, v135, v43
	v_mul_f32_e32 v47, v47, v232
	s_waitcnt lgkmcnt(0)
	v_lshlrev_b32_e32 v3, 16, v3
	v_mul_f32_e32 v48, 0xbfb8aa3b, v3
	v_exp_f32_e32 v48, v48
	s_nop 0
	v_add_f32_e32 v48, 1.0, v48
	v_rcp_f32_e32 v49, v48
	s_nop 0
	v_mul_f32_e32 v3, v3, v49
	v_mul_f32_e32 v3, v47, v3
	v_cvt_pk_bf16_f32 v3, v3, v3
	ds_write_b16 v1, v3 offset:816
	ds_read_u16 v3, v1 offset:2176
	v_mul_f32_e32 v47, v134, v42
	v_mul_f32_e32 v47, v47, v232
	s_waitcnt lgkmcnt(0)
	v_lshlrev_b32_e32 v3, 16, v3
	v_mul_f32_e32 v48, 0xbfb8aa3b, v3
	v_exp_f32_e32 v48, v48
	s_nop 0
	v_add_f32_e32 v48, 1.0, v48
	v_rcp_f32_e32 v49, v48
	s_nop 0
	v_mul_f32_e32 v3, v3, v49
	v_mul_f32_e32 v3, v47, v3
	v_cvt_pk_bf16_f32 v3, v3, v3
	ds_write_b16 v1, v3 offset:2176
	ds_read_u16 v3, v1 offset:2448
	v_mul_f32_e32 v47, v133, v41
	v_mul_f32_e32 v47, v47, v232
	s_waitcnt lgkmcnt(0)
	v_lshlrev_b32_e32 v3, 16, v3
	v_mul_f32_e32 v48, 0xbfb8aa3b, v3
	v_exp_f32_e32 v48, v48
	s_nop 0
	v_add_f32_e32 v48, 1.0, v48
	v_rcp_f32_e32 v49, v48
	s_nop 0
	v_mul_f32_e32 v3, v3, v49
	v_mul_f32_e32 v3, v47, v3
	v_cvt_pk_bf16_f32 v3, v3, v3
	ds_write_b16 v1, v3 offset:2448
	ds_read_u16 v3, v1 offset:2720
	v_mul_f32_e32 v47, v132, v40
	v_mul_f32_e32 v47, v47, v232
	s_waitcnt lgkmcnt(0)
	v_lshlrev_b32_e32 v3, 16, v3
	v_mul_f32_e32 v48, 0xbfb8aa3b, v3
	v_exp_f32_e32 v48, v48
	s_nop 0
	v_add_f32_e32 v48, 1.0, v48
	v_rcp_f32_e32 v49, v48
	s_nop 0
	v_mul_f32_e32 v3, v3, v49
	v_mul_f32_e32 v3, v47, v3
	v_cvt_pk_bf16_f32 v3, v3, v3
	ds_write_b16 v1, v3 offset:2720
	ds_read_u16 v3, v1 offset:2992
	v_mul_f32_e32 v47, v131, v35
	v_mul_f32_e32 v47, v47, v232
	s_waitcnt lgkmcnt(0)
	v_lshlrev_b32_e32 v3, 16, v3
	v_mul_f32_e32 v48, 0xbfb8aa3b, v3
	v_exp_f32_e32 v48, v48
	s_nop 0
	v_add_f32_e32 v48, 1.0, v48
	v_rcp_f32_e32 v49, v48
	s_nop 0
	v_mul_f32_e32 v3, v3, v49
	v_mul_f32_e32 v3, v47, v3
	v_cvt_pk_bf16_f32 v3, v3, v3
	ds_write_b16 v1, v3 offset:2992
	ds_read_u16 v3, v1 offset:4352
	v_mul_f32_e32 v47, v130, v31
	v_mul_f32_e32 v47, v47, v232
	s_waitcnt lgkmcnt(0)
	v_lshlrev_b32_e32 v3, 16, v3
	v_mul_f32_e32 v48, 0xbfb8aa3b, v3
	v_exp_f32_e32 v48, v48
	s_nop 0
	v_add_f32_e32 v48, 1.0, v48
	v_rcp_f32_e32 v49, v48
	s_nop 0
	v_mul_f32_e32 v3, v3, v49
	v_mul_f32_e32 v3, v47, v3
	v_cvt_pk_bf16_f32 v3, v3, v3
	ds_write_b16 v1, v3 offset:4352
	ds_read_u16 v3, v1 offset:4624
	v_mul_f32_e32 v47, v129, v27
	v_mul_f32_e32 v47, v47, v232
	s_waitcnt lgkmcnt(0)
	v_lshlrev_b32_e32 v3, 16, v3
	v_mul_f32_e32 v48, 0xbfb8aa3b, v3
	v_exp_f32_e32 v48, v48
	s_nop 0
	v_add_f32_e32 v48, 1.0, v48
	v_rcp_f32_e32 v49, v48
	s_nop 0
	v_mul_f32_e32 v3, v3, v49
	v_mul_f32_e32 v3, v47, v3
	v_cvt_pk_bf16_f32 v3, v3, v3
	ds_write_b16 v1, v3 offset:4624
	ds_read_u16 v3, v1 offset:4896
	v_mul_f32_e32 v47, v128, v25
	v_mul_f32_e32 v47, v47, v232
	s_waitcnt lgkmcnt(0)
	v_lshlrev_b32_e32 v3, 16, v3
	v_mul_f32_e32 v48, 0xbfb8aa3b, v3
	v_exp_f32_e32 v48, v48
	s_nop 0
	v_add_f32_e32 v48, 1.0, v48
	v_rcp_f32_e32 v49, v48
	s_nop 0
	v_mul_f32_e32 v3, v3, v49
	v_mul_f32_e32 v3, v47, v3
	v_cvt_pk_bf16_f32 v3, v3, v3
	ds_write_b16 v1, v3 offset:4896
	ds_read_u16 v3, v1 offset:5168
	v_mul_f32_e32 v47, v127, v24
	v_mul_f32_e32 v47, v47, v232
	s_waitcnt lgkmcnt(0)
	v_lshlrev_b32_e32 v3, 16, v3
	v_mul_f32_e32 v48, 0xbfb8aa3b, v3
	v_exp_f32_e32 v48, v48
	s_nop 0
	v_add_f32_e32 v48, 1.0, v48
	v_rcp_f32_e32 v49, v48
	s_nop 0
	v_mul_f32_e32 v3, v3, v49
	v_mul_f32_e32 v3, v47, v3
	v_cvt_pk_bf16_f32 v3, v3, v3
	ds_write_b16 v1, v3 offset:5168
	ds_read_u16 v3, v1 offset:6528
	v_mul_f32_e32 v47, v126, v23
	v_mul_f32_e32 v47, v47, v232
	s_waitcnt lgkmcnt(0)
	v_lshlrev_b32_e32 v3, 16, v3
	v_mul_f32_e32 v48, 0xbfb8aa3b, v3
	v_exp_f32_e32 v48, v48
	s_nop 0
	v_add_f32_e32 v48, 1.0, v48
	v_rcp_f32_e32 v49, v48
	s_nop 0
	v_mul_f32_e32 v3, v3, v49
	v_mul_f32_e32 v3, v47, v3
	v_cvt_pk_bf16_f32 v3, v3, v3
	ds_write_b16 v1, v3 offset:6528
	ds_read_u16 v3, v1 offset:6800
	v_mul_f32_e32 v47, v125, v22
	v_mul_f32_e32 v47, v47, v232
	s_waitcnt lgkmcnt(0)
	v_lshlrev_b32_e32 v3, 16, v3
	v_mul_f32_e32 v48, 0xbfb8aa3b, v3
	v_exp_f32_e32 v48, v48
	s_nop 0
	v_add_f32_e32 v48, 1.0, v48
	v_rcp_f32_e32 v49, v48
	s_nop 0
	v_mul_f32_e32 v3, v3, v49
	v_mul_f32_e32 v3, v47, v3
	v_cvt_pk_bf16_f32 v3, v3, v3
	ds_write_b16 v1, v3 offset:6800
	ds_read_u16 v3, v1 offset:7072
	v_mul_f32_e32 v47, v124, v21
	v_mul_f32_e32 v47, v47, v232
	s_waitcnt lgkmcnt(0)
	v_lshlrev_b32_e32 v3, 16, v3
	v_mul_f32_e32 v48, 0xbfb8aa3b, v3
	v_exp_f32_e32 v48, v48
	s_nop 0
	v_add_f32_e32 v48, 1.0, v48
	v_rcp_f32_e32 v49, v48
	s_nop 0
	v_mul_f32_e32 v3, v3, v49
	v_mul_f32_e32 v3, v47, v3
	v_cvt_pk_bf16_f32 v3, v3, v3
	ds_write_b16 v1, v3 offset:7072
	ds_read_u16 v3, v1 offset:7344
	v_mul_f32_e32 v47, v123, v20
	v_mul_f32_e32 v2, v47, v232
	s_waitcnt lgkmcnt(0)
; #define LAS __attribute__((address_space(3)))
; DI unsigned cvtpk(float lo, float hi) { f32x2 v = {lo, hi}; bf16x2_t b = __builtin_convertvector(v, bf16x2_t); return __builtin_bit_cast(unsigned, b); }
; DI float bf2f(bf16 b) { return __uint_as_float(((unsigned)b) << 16); }
; DI float siluf_(float x) { return x / (1.f + __expf(-x)); }
; DI void gla_stage3(const Ctx& c0, int layer, int unit, int cb, LAS unsigned char* lds) {
;     ...
;     for (int vb = 0; vb < 4; ++vb) { const float g = gn[32 * vb + r];
; #pragma unroll
;         for (int rg = 0; rg < 16; ++rg) { LAS bf16* e = (LAS bf16*)(R + (4 * hi) * G3_PITCH + r * 2 + ((rg & 3) + 8 * (rg >> 2)) * G3_PITCH + 64 * vb);
;             const float z = bf2f(*e);
;             *e = (bf16)(cvtpk(o[vb][rg] * rs[rg] * g * siluf_(z), 0.f) & 0xffffu); }
	v_lshlrev_b32_e32 v3, 16, v3
	v_mul_f32_e32 v47, 0xbfb8aa3b, v3
	v_exp_f32_e32 v47, v47
	s_nop 0
	v_add_f32_e32 v47, 1.0, v47
	v_div_scale_f32 v48, s[0:1], v47, v47, v3
	s_nop 0
	v_rcp_f32_e32 v48, v47
	s_nop 0
	v_mul_f32_e32 v3, v3, v48
	v_mul_f32_e32 v2, v2, v3
	v_cvt_pk_bf16_f32 v2, v2, s0
	ds_write_b16 v1, v2 offset:7344
	ds_read_u16 v3, v1 offset:64
	v_mul_f32_e32 v47, v122, v46
	s_waitcnt lgkmcnt(0)
	v_lshlrev_b32_e32 v3, 16, v3
	v_mul_f32_e32 v48, 0xbfb8aa3b, v3
	v_exp_f32_e32 v48, v48
	s_waitcnt vmcnt(0)
	v_mul_f32_e32 v47, v47, v234
	v_add_f32_e32 v48, 1.0, v48
	v_rcp_f32_e32 v49, v48
	s_nop 0
	v_mul_f32_e32 v3, v3, v49
	v_mul_f32_e32 v3, v47, v3
	v_cvt_pk_bf16_f32 v3, v3, v3
	ds_write_b16 v1, v3 offset:64
	ds_read_u16 v3, v1 offset:336
	v_mul_f32_e32 v47, v121, v45
	v_mul_f32_e32 v47, v47, v234
	s_waitcnt lgkmcnt(0)
	v_lshlrev_b32_e32 v3, 16, v3
	v_mul_f32_e32 v48, 0xbfb8aa3b, v3
	v_exp_f32_e32 v48, v48
	s_nop 0
	v_add_f32_e32 v48, 1.0, v48
	v_rcp_f32_e32 v49, v48
	s_nop 0
	v_mul_f32_e32 v3, v3, v49
	v_mul_f32_e32 v3, v47, v3
	v_cvt_pk_bf16_f32 v3, v3, v3
	ds_write_b16 v1, v3 offset:336
	ds_read_u16 v3, v1 offset:608
	v_mul_f32_e32 v47, v120, v44
	v_mul_f32_e32 v47, v47, v234
	s_waitcnt lgkmcnt(0)
	v_lshlrev_b32_e32 v3, 16, v3
	v_mul_f32_e32 v48, 0xbfb8aa3b, v3
	v_exp_f32_e32 v48, v48
	s_nop 0
	v_add_f32_e32 v48, 1.0, v48
	v_rcp_f32_e32 v49, v48
	s_nop 0
	v_mul_f32_e32 v3, v3, v49
	v_mul_f32_e32 v3, v47, v3
	v_cvt_pk_bf16_f32 v3, v3, v3
	ds_write_b16 v1, v3 offset:608
	ds_read_u16 v3, v1 offset:880
	v_mul_f32_e32 v47, v119, v43
	v_mul_f32_e32 v47, v47, v234
	s_waitcnt lgkmcnt(0)
	v_lshlrev_b32_e32 v3, 16, v3
	v_mul_f32_e32 v48, 0xbfb8aa3b, v3
	v_exp_f32_e32 v48, v48
	s_nop 0
	v_add_f32_e32 v48, 1.0, v48
	v_rcp_f32_e32 v49, v48
	s_nop 0
	v_mul_f32_e32 v3, v3, v49
	v_mul_f32_e32 v3, v47, v3
	v_cvt_pk_bf16_f32 v3, v3, v3
	ds_write_b16 v1, v3 offset:880
	ds_read_u16 v3, v1 offset:2240
	v_mul_f32_e32 v47, v118, v42
	v_mul_f32_e32 v47, v47, v234
	s_waitcnt lgkmcnt(0)
	v_lshlrev_b32_e32 v3, 16, v3
	v_mul_f32_e32 v48, 0xbfb8aa3b, v3
	v_exp_f32_e32 v48, v48
	s_nop 0
	v_add_f32_e32 v48, 1.0, v48
	v_rcp_f32_e32 v49, v48
	s_nop 0
	v_mul_f32_e32 v3, v3, v49
	v_mul_f32_e32 v3, v47, v3
	v_cvt_pk_bf16_f32 v3, v3, v3
	ds_write_b16 v1, v3 offset:2240
	ds_read_u16 v3, v1 offset:2512
	v_mul_f32_e32 v47, v117, v41
	v_mul_f32_e32 v47, v47, v234
	s_waitcnt lgkmcnt(0)
	v_lshlrev_b32_e32 v3, 16, v3
	v_mul_f32_e32 v48, 0xbfb8aa3b, v3
	v_exp_f32_e32 v48, v48
	s_nop 0
	v_add_f32_e32 v48, 1.0, v48
	v_rcp_f32_e32 v49, v48
	s_nop 0
	v_mul_f32_e32 v3, v3, v49
	v_mul_f32_e32 v3, v47, v3
	v_cvt_pk_bf16_f32 v3, v3, v3
	ds_write_b16 v1, v3 offset:2512
	ds_read_u16 v3, v1 offset:2784
	v_mul_f32_e32 v47, v116, v40
	v_mul_f32_e32 v47, v47, v234
	s_waitcnt lgkmcnt(0)
	v_lshlrev_b32_e32 v3, 16, v3
	v_mul_f32_e32 v48, 0xbfb8aa3b, v3
	v_exp_f32_e32 v48, v48
	s_nop 0
	v_add_f32_e32 v48, 1.0, v48
	v_rcp_f32_e32 v49, v48
	s_nop 0
	v_mul_f32_e32 v3, v3, v49
	v_mul_f32_e32 v3, v47, v3
	v_cvt_pk_bf16_f32 v3, v3, v3
	ds_write_b16 v1, v3 offset:2784
	ds_read_u16 v3, v1 offset:3056
	v_mul_f32_e32 v47, v115, v35
	v_mul_f32_e32 v47, v47, v234
	s_waitcnt lgkmcnt(0)
	v_lshlrev_b32_e32 v3, 16, v3
	v_mul_f32_e32 v48, 0xbfb8aa3b, v3
	v_exp_f32_e32 v48, v48
	s_nop 0
	v_add_f32_e32 v48, 1.0, v48
	v_rcp_f32_e32 v49, v48
	s_nop 0
	v_mul_f32_e32 v3, v3, v49
	v_mul_f32_e32 v3, v47, v3
	v_cvt_pk_bf16_f32 v3, v3, v3
	ds_write_b16 v1, v3 offset:3056
	ds_read_u16 v3, v1 offset:4416
	v_mul_f32_e32 v47, v114, v31
	v_mul_f32_e32 v47, v47, v234
	s_waitcnt lgkmcnt(0)
	v_lshlrev_b32_e32 v3, 16, v3
	v_mul_f32_e32 v48, 0xbfb8aa3b, v3
	v_exp_f32_e32 v48, v48
	s_nop 0
	v_add_f32_e32 v48, 1.0, v48
	v_rcp_f32_e32 v49, v48
	s_nop 0
	v_mul_f32_e32 v3, v3, v49
	v_mul_f32_e32 v3, v47, v3
	v_cvt_pk_bf16_f32 v3, v3, v3
	ds_write_b16 v1, v3 offset:4416
	ds_read_u16 v3, v1 offset:4688
	v_mul_f32_e32 v47, v113, v27
	v_mul_f32_e32 v47, v47, v234
	s_waitcnt lgkmcnt(0)
	v_lshlrev_b32_e32 v3, 16, v3
	v_mul_f32_e32 v48, 0xbfb8aa3b, v3
	v_exp_f32_e32 v48, v48
	s_nop 0
	v_add_f32_e32 v48, 1.0, v48
	v_rcp_f32_e32 v49, v48
	s_nop 0
	v_mul_f32_e32 v3, v3, v49
	v_mul_f32_e32 v3, v47, v3
	v_cvt_pk_bf16_f32 v3, v3, v3
	ds_write_b16 v1, v3 offset:4688
	ds_read_u16 v3, v1 offset:4960
	v_mul_f32_e32 v47, v112, v25
	v_mul_f32_e32 v47, v47, v234
	s_waitcnt lgkmcnt(0)
	v_lshlrev_b32_e32 v3, 16, v3
	v_mul_f32_e32 v48, 0xbfb8aa3b, v3
	v_exp_f32_e32 v48, v48
	s_nop 0
	v_add_f32_e32 v48, 1.0, v48
	v_rcp_f32_e32 v49, v48
	s_nop 0
	v_mul_f32_e32 v3, v3, v49
	v_mul_f32_e32 v3, v47, v3
	v_cvt_pk_bf16_f32 v3, v3, v3
	ds_write_b16 v1, v3 offset:4960
	ds_read_u16 v3, v1 offset:5232
	v_mul_f32_e32 v47, v111, v24
	v_mul_f32_e32 v47, v47, v234
	s_waitcnt lgkmcnt(0)
	v_lshlrev_b32_e32 v3, 16, v3
	v_mul_f32_e32 v48, 0xbfb8aa3b, v3
	v_exp_f32_e32 v48, v48
	s_nop 0
	v_add_f32_e32 v48, 1.0, v48
	v_rcp_f32_e32 v49, v48
	s_nop 0
	v_mul_f32_e32 v3, v3, v49
	v_mul_f32_e32 v3, v47, v3
	v_cvt_pk_bf16_f32 v3, v3, v3
	ds_write_b16 v1, v3 offset:5232
	ds_read_u16 v3, v1 offset:6592
	v_mul_f32_e32 v47, v110, v23
	v_mul_f32_e32 v47, v47, v234
	s_waitcnt lgkmcnt(0)
	v_lshlrev_b32_e32 v3, 16, v3
	v_mul_f32_e32 v48, 0xbfb8aa3b, v3
	v_exp_f32_e32 v48, v48
	s_nop 0
	v_add_f32_e32 v48, 1.0, v48
	v_rcp_f32_e32 v49, v48
	s_nop 0
	v_mul_f32_e32 v3, v3, v49
	v_mul_f32_e32 v3, v47, v3
	v_cvt_pk_bf16_f32 v3, v3, v3
	ds_write_b16 v1, v3 offset:6592
	ds_read_u16 v3, v1 offset:6864
	v_mul_f32_e32 v47, v109, v22
	v_mul_f32_e32 v47, v47, v234
	s_waitcnt lgkmcnt(0)
; #define LAS __attribute__((address_space(3)))
; DI unsigned cvtpk(float lo, float hi) { f32x2 v = {lo, hi}; bf16x2_t b = __builtin_convertvector(v, bf16x2_t); return __builtin_bit_cast(unsigned, b); }
; DI float bf2f(bf16 b) { return __uint_as_float(((unsigned)b) << 16); }
; DI float siluf_(float x) { return x / (1.f + __expf(-x)); }
; DI void gla_stage3(const Ctx& c0, int layer, int unit, int cb, LAS unsigned char* lds) {
;     ...
;     for (int vb = 0; vb < 4; ++vb) { const float g = gn[32 * vb + r];
; #pragma unroll
;         for (int rg = 0; rg < 16; ++rg) { LAS bf16* e = (LAS bf16*)(R + (4 * hi) * G3_PITCH + r * 2 + ((rg & 3) + 8 * (rg >> 2)) * G3_PITCH + 64 * vb);
;             const float z = bf2f(*e);
;             *e = (bf16)(cvtpk(o[vb][rg] * rs[rg] * g * siluf_(z), 0.f) & 0xffffu); }
	v_lshlrev_b32_e32 v3, 16, v3
	v_mul_f32_e32 v48, 0xbfb8aa3b, v3
	v_exp_f32_e32 v48, v48
	s_nop 0
	v_add_f32_e32 v48, 1.0, v48
	v_rcp_f32_e32 v49, v48
	s_nop 0
	v_mul_f32_e32 v3, v3, v49
	v_mul_f32_e32 v3, v47, v3
	v_cvt_pk_bf16_f32 v3, v3, v3
	ds_write_b16 v1, v3 offset:6864
	ds_read_u16 v3, v1 offset:7136
	v_mul_f32_e32 v47, v108, v21
	v_mul_f32_e32 v47, v47, v234
	s_waitcnt lgkmcnt(0)
	v_lshlrev_b32_e32 v3, 16, v3
	v_mul_f32_e32 v48, 0xbfb8aa3b, v3
	v_exp_f32_e32 v48, v48
	s_nop 0
	v_add_f32_e32 v48, 1.0, v48
	v_rcp_f32_e32 v49, v48
	s_nop 0
	v_mul_f32_e32 v3, v3, v49
	v_mul_f32_e32 v3, v47, v3
	v_cvt_pk_bf16_f32 v3, v3, v3
	ds_write_b16 v1, v3 offset:7136
	ds_read_u16 v3, v1 offset:7408
	v_mul_f32_e32 v47, v107, v20
	v_mul_f32_e32 v2, v47, v234
	s_waitcnt lgkmcnt(0)
	v_lshlrev_b32_e32 v3, 16, v3
	v_mul_f32_e32 v47, 0xbfb8aa3b, v3
	v_exp_f32_e32 v47, v47
	s_nop 0
	v_add_f32_e32 v47, 1.0, v47
	v_div_scale_f32 v48, s[0:1], v47, v47, v3
	s_nop 0
	v_rcp_f32_e32 v48, v47
	s_nop 0
	v_mul_f32_e32 v3, v3, v48
	v_mul_f32_e32 v2, v2, v3
	v_cvt_pk_bf16_f32 v2, v2, s0
	ds_write_b16 v1, v2 offset:7408
	ds_read_u16 v3, v1 offset:128
	v_mul_f32_e32 v47, v106, v46
	s_waitcnt lgkmcnt(0)
	v_lshlrev_b32_e32 v3, 16, v3
	v_mul_f32_e32 v48, 0xbfb8aa3b, v3
	v_exp_f32_e32 v48, v48
	s_waitcnt vmcnt(0)
	v_mul_f32_e32 v47, v47, v236
	v_add_f32_e32 v48, 1.0, v48
	v_div_scale_f32 v49, s[0:1], v48, v48, v3
	v_mul_f32_e32 v39, v39, v236
	v_mul_f32_e32 v38, v38, v236
	v_mul_f32_e32 v37, v37, v236
	v_rcp_f32_e32 v49, v48
	s_nop 0
	v_mul_f32_e32 v3, v3, v49
	v_mul_f32_e32 v3, v47, v3
	v_cvt_pk_bf16_f32 v3, v3, s0
	ds_write_b16 v1, v3 offset:128
	ds_read_u16 v3, v1 offset:400
	v_mul_f32_e32 v47, v105, v45
	v_mul_f32_e32 v47, v47, v236
	v_mul_f32_e32 v36, v36, v236
	v_mul_f32_e32 v34, v34, v236
	s_waitcnt lgkmcnt(0)
	v_lshlrev_b32_e32 v3, 16, v3
	v_mul_f32_e32 v48, 0xbfb8aa3b, v3
	v_exp_f32_e32 v48, v48
	v_mul_f32_e32 v33, v33, v236
	v_mul_f32_e32 v32, v32, v236
	v_mul_f32_e32 v30, v30, v236
	v_add_f32_e32 v48, 1.0, v48
	v_div_scale_f32 v49, s[0:1], v48, v48, v3
	v_mul_f32_e32 v29, v29, v236
	v_mul_f32_e32 v28, v28, v236
	v_rcp_f32_e32 v49, v48
	s_nop 0
	v_mul_f32_e32 v3, v3, v49
	v_mul_f32_e32 v3, v47, v3
	v_cvt_pk_bf16_f32 v3, v3, s0
	ds_write_b16 v1, v3 offset:400
	ds_read_u16 v3, v1 offset:672
	v_mul_f32_e32 v47, v104, v44
	v_mul_f32_e32 v47, v47, v236
	s_waitcnt lgkmcnt(0)
	v_lshlrev_b32_e32 v3, 16, v3
	v_mul_f32_e32 v48, 0xbfb8aa3b, v3
	v_exp_f32_e32 v48, v48
	s_nop 0
	v_add_f32_e32 v48, 1.0, v48
	v_rcp_f32_e32 v49, v48
	s_nop 0
	v_mul_f32_e32 v3, v3, v49
	v_mul_f32_e32 v3, v47, v3
	v_cvt_pk_bf16_f32 v3, v3, v3
	ds_write_b16 v1, v3 offset:672
	ds_read_u16 v3, v1 offset:944
	v_mul_f32_e32 v47, v103, v43
	v_mul_f32_e32 v47, v47, v236
	s_waitcnt lgkmcnt(0)
	v_lshlrev_b32_e32 v3, 16, v3
	v_mul_f32_e32 v48, 0xbfb8aa3b, v3
	v_exp_f32_e32 v48, v48
	s_nop 0
	v_add_f32_e32 v48, 1.0, v48
	v_rcp_f32_e32 v49, v48
	s_nop 0
	v_mul_f32_e32 v3, v3, v49
	v_mul_f32_e32 v3, v47, v3
	v_cvt_pk_bf16_f32 v3, v3, v3
	ds_write_b16 v1, v3 offset:944
	ds_read_u16 v3, v1 offset:2304
	v_mul_f32_e32 v47, v102, v42
	v_mul_f32_e32 v47, v47, v236
	v_mul_f32_e32 v2, v26, v236
	s_waitcnt lgkmcnt(0)
	v_lshlrev_b32_e32 v3, 16, v3
	v_mul_f32_e32 v48, 0xbfb8aa3b, v3
	v_exp_f32_e32 v48, v48
	s_nop 0
	v_add_f32_e32 v48, 1.0, v48
	v_rcp_f32_e32 v49, v48
	s_nop 0
	v_mul_f32_e32 v3, v3, v49
	v_mul_f32_e32 v3, v47, v3
	v_cvt_pk_bf16_f32 v3, v3, v3
	ds_write_b16 v1, v3 offset:2304
	ds_read_u16 v3, v1 offset:2576
	s_waitcnt lgkmcnt(0)
	v_lshlrev_b32_e32 v3, 16, v3
	v_mul_f32_e32 v47, 0xbfb8aa3b, v3
	v_exp_f32_e32 v47, v47
	s_nop 0
	v_add_f32_e32 v47, 1.0, v47
	v_rcp_f32_e32 v48, v47
	s_nop 0
	v_mul_f32_e32 v3, v3, v48
	v_mul_f32_e32 v3, v39, v3
	v_cvt_pk_bf16_f32 v3, v3, v3
	ds_write_b16 v1, v3 offset:2576
	ds_read_u16 v3, v1 offset:2848
	s_waitcnt lgkmcnt(0)
	v_lshlrev_b32_e32 v3, 16, v3
	v_mul_f32_e32 v39, 0xbfb8aa3b, v3
	v_exp_f32_e32 v39, v39
	s_nop 0
	v_add_f32_e32 v39, 1.0, v39
	v_rcp_f32_e32 v47, v39
	s_nop 0
	v_mul_f32_e32 v3, v3, v47
	v_mul_f32_e32 v3, v38, v3
	v_cvt_pk_bf16_f32 v3, v3, v3
	ds_write_b16 v1, v3 offset:2848
	ds_read_u16 v3, v1 offset:3120
	s_waitcnt lgkmcnt(0)
	v_lshlrev_b32_e32 v3, 16, v3
	v_mul_f32_e32 v38, 0xbfb8aa3b, v3
	v_exp_f32_e32 v38, v38
	s_nop 0
	v_add_f32_e32 v38, 1.0, v38
	v_rcp_f32_e32 v39, v38
	s_nop 0
	v_mul_f32_e32 v3, v3, v39
	v_mul_f32_e32 v3, v37, v3
	v_cvt_pk_bf16_f32 v3, v3, v3
	ds_write_b16 v1, v3 offset:3120
	ds_read_u16 v3, v1 offset:4480
	s_waitcnt lgkmcnt(0)
	v_lshlrev_b32_e32 v3, 16, v3
	v_mul_f32_e32 v37, 0xbfb8aa3b, v3
	v_exp_f32_e32 v37, v37
	s_nop 0
	v_add_f32_e32 v37, 1.0, v37
	v_rcp_f32_e32 v38, v37
	s_nop 0
	v_mul_f32_e32 v3, v3, v38
	v_mul_f32_e32 v3, v36, v3
	v_cvt_pk_bf16_f32 v3, v3, v3
	ds_write_b16 v1, v3 offset:4480
	ds_read_u16 v3, v1 offset:4752
	s_waitcnt lgkmcnt(0)
	v_lshlrev_b32_e32 v3, 16, v3
	v_mul_f32_e32 v36, 0xbfb8aa3b, v3
	v_exp_f32_e32 v36, v36
	s_nop 0
	v_add_f32_e32 v36, 1.0, v36
	v_rcp_f32_e32 v37, v36
	s_nop 0
	v_mul_f32_e32 v3, v3, v37
	v_mul_f32_e32 v3, v34, v3
	v_cvt_pk_bf16_f32 v3, v3, v3
	ds_write_b16 v1, v3 offset:4752
	ds_read_u16 v3, v1 offset:5024
	s_waitcnt lgkmcnt(0)
	v_lshlrev_b32_e32 v3, 16, v3
	v_mul_f32_e32 v34, 0xbfb8aa3b, v3
	v_exp_f32_e32 v34, v34
	s_nop 0
	v_add_f32_e32 v34, 1.0, v34
	v_rcp_f32_e32 v36, v34
	s_nop 0
	v_mul_f32_e32 v3, v3, v36
	v_mul_f32_e32 v3, v33, v3
	v_cvt_pk_bf16_f32 v3, v3, v3
	ds_write_b16 v1, v3 offset:5024
	ds_read_u16 v3, v1 offset:5296
	s_waitcnt lgkmcnt(0)
; #define LAS __attribute__((address_space(3)))
; DI unsigned cvtpk(float lo, float hi) { f32x2 v = {lo, hi}; bf16x2_t b = __builtin_convertvector(v, bf16x2_t); return __builtin_bit_cast(unsigned, b); }
; DI float bf2f(bf16 b) { return __uint_as_float(((unsigned)b) << 16); }
; DI float siluf_(float x) { return x / (1.f + __expf(-x)); }
; DI void gla_stage3(const Ctx& c0, int layer, int unit, int cb, LAS unsigned char* lds) {
;     ...
;     for (int vb = 0; vb < 4; ++vb) { const float g = gn[32 * vb + r];
; #pragma unroll
;         for (int rg = 0; rg < 16; ++rg) { LAS bf16* e = (LAS bf16*)(R + (4 * hi) * G3_PITCH + r * 2 + ((rg & 3) + 8 * (rg >> 2)) * G3_PITCH + 64 * vb);
;             const float z = bf2f(*e);
;             *e = (bf16)(cvtpk(o[vb][rg] * rs[rg] * g * siluf_(z), 0.f) & 0xffffu); }
	v_lshlrev_b32_e32 v3, 16, v3
	v_mul_f32_e32 v33, 0xbfb8aa3b, v3
	v_exp_f32_e32 v33, v33
	s_nop 0
	v_add_f32_e32 v33, 1.0, v33
	v_rcp_f32_e32 v34, v33
	s_nop 0
	v_mul_f32_e32 v3, v3, v34
	v_mul_f32_e32 v3, v32, v3
	v_cvt_pk_bf16_f32 v3, v3, v3
	ds_write_b16 v1, v3 offset:5296
	ds_read_u16 v3, v1 offset:6656
	s_waitcnt lgkmcnt(0)
	v_lshlrev_b32_e32 v3, 16, v3
	v_mul_f32_e32 v32, 0xbfb8aa3b, v3
	v_exp_f32_e32 v32, v32
	s_nop 0
	v_add_f32_e32 v32, 1.0, v32
	v_rcp_f32_e32 v33, v32
	s_nop 0
	v_mul_f32_e32 v3, v3, v33
	v_mul_f32_e32 v3, v30, v3
	v_cvt_pk_bf16_f32 v3, v3, v3
	ds_write_b16 v1, v3 offset:6656
	ds_read_u16 v3, v1 offset:6928
	s_waitcnt lgkmcnt(0)
	v_lshlrev_b32_e32 v3, 16, v3
	v_mul_f32_e32 v30, 0xbfb8aa3b, v3
	v_exp_f32_e32 v30, v30
	s_nop 0
	v_add_f32_e32 v30, 1.0, v30
	v_rcp_f32_e32 v32, v30
	s_nop 0
	v_mul_f32_e32 v3, v3, v32
	v_mul_f32_e32 v3, v29, v3
	v_cvt_pk_bf16_f32 v3, v3, v3
	ds_write_b16 v1, v3 offset:6928
	ds_read_u16 v3, v1 offset:7200
	s_waitcnt lgkmcnt(0)
	v_lshlrev_b32_e32 v3, 16, v3
	v_mul_f32_e32 v29, 0xbfb8aa3b, v3
	v_exp_f32_e32 v29, v29
	s_nop 0
	v_add_f32_e32 v29, 1.0, v29
	v_rcp_f32_e32 v30, v29
	s_nop 0
	v_mul_f32_e32 v3, v3, v30
	v_mul_f32_e32 v3, v28, v3
	v_cvt_pk_bf16_f32 v3, v3, v3
	ds_write_b16 v1, v3 offset:7200
	ds_read_u16 v3, v1 offset:7472
	s_waitcnt lgkmcnt(0)
	v_lshlrev_b32_e32 v3, 16, v3
	v_mul_f32_e32 v26, 0xbfb8aa3b, v3
	v_exp_f32_e32 v26, v26
	s_nop 0
	v_add_f32_e32 v26, 1.0, v26
	v_div_scale_f32 v28, s[0:1], v26, v26, v3
	s_nop 0
	v_rcp_f32_e32 v28, v26
	s_nop 0
	v_mul_f32_e32 v3, v3, v28
	v_mul_f32_e32 v2, v2, v3
	v_cvt_pk_bf16_f32 v2, v2, s0
	ds_write_b16 v1, v2 offset:7472
	ds_read_u16 v3, v1 offset:192
	s_waitcnt lgkmcnt(0)
	v_lshlrev_b32_e32 v3, 16, v3
	v_mul_f32_e32 v26, 0xbfb8aa3b, v3
	v_exp_f32_e32 v26, v26
	s_waitcnt vmcnt(31)
	v_mul_f32_e32 v19, v19, v238
	v_add_f32_e32 v26, 1.0, v26
	v_div_scale_f32 v28, s[0:1], v26, v26, v3
	v_mul_f32_e32 v18, v18, v238
	v_mul_f32_e32 v17, v17, v238
	v_mul_f32_e32 v16, v16, v238
	v_rcp_f32_e32 v28, v26
	s_nop 0
	v_mul_f32_e32 v3, v3, v28
	v_mul_f32_e32 v3, v19, v3
	v_cvt_pk_bf16_f32 v3, v3, s0
	ds_write_b16 v1, v3 offset:192
	ds_read_u16 v3, v1 offset:464
	v_mul_f32_e32 v15, v15, v238
	v_mul_f32_e32 v14, v14, v238
	v_mul_f32_e32 v13, v13, v238
	v_mul_f32_e32 v12, v12, v238
	s_waitcnt lgkmcnt(0)
	v_lshlrev_b32_e32 v3, 16, v3
	v_mul_f32_e32 v19, 0xbfb8aa3b, v3
	v_exp_f32_e32 v19, v19
	v_mul_f32_e32 v11, v11, v238
	v_mul_f32_e32 v10, v10, v238
	v_mul_f32_e32 v9, v9, v238
	v_add_f32_e32 v19, 1.0, v19
	v_div_scale_f32 v26, s[0:1], v19, v19, v3
	v_mul_f32_e32 v8, v8, v238
	v_mul_f32_e32 v7, v7, v238
	v_mul_f32_e32 v6, v6, v238
	v_rcp_f32_e32 v26, v19
	s_nop 0
	v_mul_f32_e32 v3, v3, v26
	v_mul_f32_e32 v3, v18, v3
	v_cvt_pk_bf16_f32 v3, v3, s0
	ds_write_b16 v1, v3 offset:464
	ds_read_u16 v3, v1 offset:736
	v_mul_f32_e32 v5, v5, v238
	v_mul_f32_e32 v2, v4, v238
	s_waitcnt lgkmcnt(0)
	v_lshlrev_b32_e32 v3, 16, v3
	v_mul_f32_e32 v18, 0xbfb8aa3b, v3
	v_exp_f32_e32 v18, v18
	s_nop 0
	v_add_f32_e32 v18, 1.0, v18
	v_rcp_f32_e32 v19, v18
	s_nop 0
	v_mul_f32_e32 v3, v3, v19
	v_mul_f32_e32 v3, v17, v3
	v_cvt_pk_bf16_f32 v3, v3, v3
	ds_write_b16 v1, v3 offset:736
	ds_read_u16 v3, v1 offset:1008
	s_waitcnt lgkmcnt(0)
	v_lshlrev_b32_e32 v3, 16, v3
	v_mul_f32_e32 v17, 0xbfb8aa3b, v3
	v_exp_f32_e32 v17, v17
	s_nop 0
	v_add_f32_e32 v17, 1.0, v17
	v_rcp_f32_e32 v18, v17
	s_nop 0
	v_mul_f32_e32 v3, v3, v18
	v_mul_f32_e32 v3, v16, v3
	v_cvt_pk_bf16_f32 v3, v3, v3
	ds_write_b16 v1, v3 offset:1008
	ds_read_u16 v3, v1 offset:2368
	s_waitcnt lgkmcnt(0)
	v_lshlrev_b32_e32 v3, 16, v3
	v_mul_f32_e32 v16, 0xbfb8aa3b, v3
	v_exp_f32_e32 v16, v16
	s_nop 0
	v_add_f32_e32 v16, 1.0, v16
	v_rcp_f32_e32 v17, v16
	s_nop 0
	v_mul_f32_e32 v3, v3, v17
	v_mul_f32_e32 v3, v15, v3
	v_cvt_pk_bf16_f32 v3, v3, v3
	ds_write_b16 v1, v3 offset:2368
	ds_read_u16 v3, v1 offset:2640
	s_waitcnt lgkmcnt(0)
	v_lshlrev_b32_e32 v3, 16, v3
	v_mul_f32_e32 v15, 0xbfb8aa3b, v3
	v_exp_f32_e32 v15, v15
	s_nop 0
	v_add_f32_e32 v15, 1.0, v15
	v_rcp_f32_e32 v16, v15
	s_nop 0
	v_mul_f32_e32 v3, v3, v16
	v_mul_f32_e32 v3, v14, v3
	v_cvt_pk_bf16_f32 v3, v3, v3
	ds_write_b16 v1, v3 offset:2640
	ds_read_u16 v3, v1 offset:2912
	s_waitcnt lgkmcnt(0)
; #define LAS __attribute__((address_space(3)))
; #define LDS_WAIT() asm volatile("s_waitcnt lgkmcnt(0)" ::: "memory")
; DI unsigned cvtpk(float lo, float hi) { f32x2 v = {lo, hi}; bf16x2_t b = __builtin_convertvector(v, bf16x2_t); return __builtin_bit_cast(unsigned, b); }
; DI float bf2f(bf16 b) { return __uint_as_float(((unsigned)b) << 16); }
; DI float siluf_(float x) { return x / (1.f + __expf(-x)); }
; DI void g3_tile_out(bf16* g, const LAS unsigned char* R, int lane) {
;     LDS_WAIT();
; #pragma unroll
;     for (int it = 0; it < 8; ++it) { const int row = 4 * it + (lane >> 4), ch = lane & 15;
;         *(u32x4*)(g + (size_t)row * 512 + ch * 8) = *(const LAS u32x4*)(R + row * G3_PITCH + ch * 16); }
;     LDS_WAIT();
; DI void gla_stage3(const Ctx& c0, int layer, int unit, int cb, LAS unsigned char* lds) {
;     ...
;     for (int vb = 0; vb < 4; ++vb) { const float g = gn[32 * vb + r];
; #pragma unroll
;         for (int rg = 0; rg < 16; ++rg) { LAS bf16* e = (LAS bf16*)(R + (4 * hi) * G3_PITCH + r * 2 + ((rg & 3) + 8 * (rg >> 2)) * G3_PITCH + 64 * vb);
;             const float z = bf2f(*e);
;             *e = (bf16)(cvtpk(o[vb][rg] * rs[rg] * g * siluf_(z), 0.f) & 0xffffu); }
;         asm volatile("" ::: "memory"); }
;     g3_tile_out((bf16*)(c.ws + O_OGLA) + row0 * 512 + h * 128, R, lane);
	v_lshlrev_b32_e32 v3, 16, v3
	v_mul_f32_e32 v14, 0xbfb8aa3b, v3
	v_exp_f32_e32 v14, v14
	s_nop 0
	v_add_f32_e32 v14, 1.0, v14
	v_rcp_f32_e32 v15, v14
	s_nop 0
	v_mul_f32_e32 v3, v3, v15
	v_mul_f32_e32 v3, v13, v3
	v_cvt_pk_bf16_f32 v3, v3, v3
	ds_write_b16 v1, v3 offset:2912
	ds_read_u16 v3, v1 offset:3184
	s_waitcnt lgkmcnt(0)
	v_lshlrev_b32_e32 v3, 16, v3
	v_mul_f32_e32 v13, 0xbfb8aa3b, v3
	v_exp_f32_e32 v13, v13
	s_nop 0
	v_add_f32_e32 v13, 1.0, v13
	v_rcp_f32_e32 v14, v13
	s_nop 0
	v_mul_f32_e32 v3, v3, v14
	v_mul_f32_e32 v3, v12, v3
	v_cvt_pk_bf16_f32 v3, v3, v3
	ds_write_b16 v1, v3 offset:3184
	ds_read_u16 v3, v1 offset:4544
	s_waitcnt lgkmcnt(0)
	v_lshlrev_b32_e32 v3, 16, v3
	v_mul_f32_e32 v12, 0xbfb8aa3b, v3
	v_exp_f32_e32 v12, v12
	s_nop 0
	v_add_f32_e32 v12, 1.0, v12
	v_rcp_f32_e32 v13, v12
	s_nop 0
	v_mul_f32_e32 v3, v3, v13
	v_mul_f32_e32 v3, v11, v3
	v_cvt_pk_bf16_f32 v3, v3, v3
	ds_write_b16 v1, v3 offset:4544
	ds_read_u16 v3, v1 offset:4816
	s_waitcnt lgkmcnt(0)
	v_lshlrev_b32_e32 v3, 16, v3
	v_mul_f32_e32 v11, 0xbfb8aa3b, v3
	v_exp_f32_e32 v11, v11
	s_nop 0
	v_add_f32_e32 v11, 1.0, v11
	v_rcp_f32_e32 v12, v11
	s_nop 0
	v_mul_f32_e32 v3, v3, v12
	v_mul_f32_e32 v3, v10, v3
	v_cvt_pk_bf16_f32 v3, v3, v3
	ds_write_b16 v1, v3 offset:4816
	ds_read_u16 v3, v1 offset:5088
	s_waitcnt lgkmcnt(0)
	v_lshlrev_b32_e32 v3, 16, v3
	v_mul_f32_e32 v10, 0xbfb8aa3b, v3
	v_exp_f32_e32 v10, v10
	s_nop 0
	v_add_f32_e32 v10, 1.0, v10
	v_rcp_f32_e32 v11, v10
	s_nop 0
	v_mul_f32_e32 v3, v3, v11
	v_mul_f32_e32 v3, v9, v3
	v_cvt_pk_bf16_f32 v3, v3, v3
	ds_write_b16 v1, v3 offset:5088
	ds_read_u16 v3, v1 offset:5360
	s_waitcnt lgkmcnt(0)
	v_lshlrev_b32_e32 v3, 16, v3
	v_mul_f32_e32 v9, 0xbfb8aa3b, v3
	v_exp_f32_e32 v9, v9
	s_nop 0
	v_add_f32_e32 v9, 1.0, v9
	v_rcp_f32_e32 v10, v9
	s_nop 0
	v_mul_f32_e32 v3, v3, v10
	v_mul_f32_e32 v3, v8, v3
	v_cvt_pk_bf16_f32 v3, v3, v3
	ds_write_b16 v1, v3 offset:5360
	ds_read_u16 v3, v1 offset:6720
	s_waitcnt lgkmcnt(0)
	v_lshlrev_b32_e32 v3, 16, v3
	v_mul_f32_e32 v8, 0xbfb8aa3b, v3
	v_exp_f32_e32 v8, v8
	s_nop 0
	v_add_f32_e32 v8, 1.0, v8
	v_rcp_f32_e32 v9, v8
	s_nop 0
	v_mul_f32_e32 v3, v3, v9
	v_mul_f32_e32 v3, v7, v3
	v_cvt_pk_bf16_f32 v3, v3, v3
	ds_write_b16 v1, v3 offset:6720
	ds_read_u16 v3, v1 offset:6992
	s_waitcnt lgkmcnt(0)
	v_lshlrev_b32_e32 v3, 16, v3
	v_mul_f32_e32 v7, 0xbfb8aa3b, v3
	v_exp_f32_e32 v7, v7
	s_nop 0
	v_add_f32_e32 v7, 1.0, v7
	v_rcp_f32_e32 v8, v7
	s_nop 0
	v_mul_f32_e32 v3, v3, v8
	v_mul_f32_e32 v3, v6, v3
	v_cvt_pk_bf16_f32 v3, v3, v3
	ds_write_b16 v1, v3 offset:6992
	ds_read_u16 v3, v1 offset:7264
	s_waitcnt lgkmcnt(0)
	v_lshlrev_b32_e32 v3, 16, v3
	v_mul_f32_e32 v6, 0xbfb8aa3b, v3
	v_exp_f32_e32 v6, v6
	s_nop 0
	v_add_f32_e32 v6, 1.0, v6
	v_rcp_f32_e32 v7, v6
	s_nop 0
	v_mul_f32_e32 v3, v3, v7
	v_mul_f32_e32 v3, v5, v3
	v_cvt_pk_bf16_f32 v3, v3, v3
	ds_write_b16 v1, v3 offset:7264
	ds_read_u16 v3, v1 offset:7536
	s_waitcnt lgkmcnt(0)
	v_lshlrev_b32_e32 v3, 16, v3
	v_mul_f32_e32 v4, 0xbfb8aa3b, v3
	v_exp_f32_e32 v4, v4
	s_nop 0
	v_add_f32_e32 v4, 1.0, v4
	v_div_scale_f32 v5, s[0:1], v4, v4, v3
	s_nop 0
	v_rcp_f32_e32 v5, v4
	s_nop 0
	v_mul_f32_e32 v3, v3, v5
	v_mul_f32_e32 v2, v2, v3
	v_cvt_pk_bf16_f32 v2, v2, s0
	ds_write_b16 v1, v2 offset:7536
	s_waitcnt lgkmcnt(0)
	ds_read_b128 v[2:5], v92
	v_lshl_add_u64 v[6:7], v[90:91], 0, s[22:23]
	v_lshl_add_u64 v[8:9], v[6:7], 0, v[66:67]
	s_waitcnt lgkmcnt(0)
	global_store_dwordx4 v[8:9], v[2:5], off
	ds_read_b128 v[2:5], v92 offset:1088
	v_lshl_add_u64 v[8:9], v[6:7], 0, v[68:69]
	s_waitcnt lgkmcnt(0)
	global_store_dwordx4 v[8:9], v[2:5], off
	ds_read_b128 v[2:5], v92 offset:2176
	v_lshl_add_u64 v[8:9], v[6:7], 0, v[70:71]
	s_waitcnt lgkmcnt(0)
	global_store_dwordx4 v[8:9], v[2:5], off
	ds_read_b128 v[2:5], v92 offset:3264
	v_lshl_add_u64 v[8:9], v[6:7], 0, v[72:73]
	s_waitcnt lgkmcnt(0)
	global_store_dwordx4 v[8:9], v[2:5], off
	ds_read_b128 v[2:5], v92 offset:4352
	v_lshl_add_u64 v[8:9], v[6:7], 0, v[74:75]
	s_waitcnt lgkmcnt(0)
	global_store_dwordx4 v[8:9], v[2:5], off
	ds_read_b128 v[2:5], v92 offset:5440
	v_lshl_add_u64 v[8:9], v[6:7], 0, v[76:77]
	s_waitcnt lgkmcnt(0)
	global_store_dwordx4 v[8:9], v[2:5], off
	ds_read_b128 v[2:5], v92 offset:6528
	v_lshl_add_u64 v[8:9], v[6:7], 0, v[78:79]
	v_lshl_add_u64 v[6:7], v[6:7], 0, v[80:81]
	s_waitcnt lgkmcnt(0)
	global_store_dwordx4 v[8:9], v[2:5], off
	ds_read_b128 v[2:5], v92 offset:7616
	s_waitcnt lgkmcnt(0)
	global_store_dwordx4 v[6:7], v[2:5], off
	s_waitcnt lgkmcnt(0)
	s_cbranch_scc1 .LBB0_604

; #define LAS __attribute__((address_space(3)))
; DI float bflo(unsigned w) { return __uint_as_float(w << 16); }
; DI float bfhi(unsigned w) { return __uint_as_float(w & 0xffff0000u); }
; DI void nsa_unit(const Ctx& c0, int b, int g, int i, LAS unsigned char* lds) {
;     ...
;         branch_fold(st, g_w2, false, wsf, lane);
; #pragma unroll
;         for (int rg = 0; rg < 16; ++rg) { const unsigned w = OC[rg * 64]; ca0[rg] = (OACC[rg * 64] + st.o0[rg]) + bflo(w); ca1[rg] = (OACC[(16 + rg) * 64] + st.o1[rg]) + bfhi(w); }
;         __syncthreads();
;     }
;     ...
;     { const size_t g0 = ((size_t)b * SEQ + i * 64 + 32 * qh) * 512 + head * 64;
;       const bf16* nzg = (const bf16*)(c.ws + O_NZ) + g0; bf16* ong = (bf16*)(c.ws + O_ONSA) + g0;
;       LAS unsigned char* S = lds + A_OC + wid * 4096;
; #pragma unroll
;       for (int it = 0; it < 4; ++it) { const int rw = 8 * it + (lane >> 3), ch = lane & 7;
;           *(LAS u32x4*)(S + rw * 128 + ch * 16) = *(const u32x4*)(nzg + (size_t)rw * 512 + ch * 8); }
.LBB0_1153:
	s_or_b64 exec, exec, s[14:15]
	s_or_b32 s6, s26, s33
	s_add_u32 s14, s4, s6
	s_addc_u32 s15, s5, 0
	s_lshl_b64 s[14:15], s[14:15], 9
	s_add_u32 s14, s14, s22
	s_addc_u32 s15, s15, 0
	s_lshl_b64 s[14:15], s[14:15], 1
	s_add_u32 s0, s0, s14
	s_addc_u32 s1, s1, s15
	v_mov_b32_e32 v135, v3
	v_lshl_add_u64 v[246:247], s[0:1], 0, v[134:135]
	s_mov_b64 s[98:99], 0xb500000
	v_lshl_add_u64 v[246:247], v[246:247], 0, s[98:99]
	v_lshl_add_u64 v[248:249], v[246:247], 0, v[126:127]
	global_load_dwordx4 v[230:233], v[248:249], off
	v_lshl_add_u64 v[248:249], v[246:247], 0, v[128:129]
	global_load_dwordx4 v[234:237], v[248:249], off
	v_lshl_add_u64 v[248:249], v[246:247], 0, v[130:131]
	global_load_dwordx4 v[238:241], v[248:249], off
	v_lshl_add_u64 v[248:249], v[246:247], 0, v[132:133]
	global_load_dwordx4 v[242:245], v[248:249], off
	s_waitcnt lgkmcnt(0)
	ds_read_b128 v[48:51], v192 offset:32768
	ds_read_b128 v[44:47], v192 offset:32800
	ds_read_b128 v[40:43], v192 offset:32832
	ds_read_b128 v[36:39], v192 offset:32864
	ds_read2st64_b32 v[52:53], v203 offset1:1
	ds_read2st64_b32 v[54:55], v190 offset0:144 offset1:145
	ds_read2st64_b32 v[56:57], v190 offset0:160 offset1:161
	s_waitcnt lgkmcnt(0)
	v_lshlrev_b32_e32 v2, 16, v52
	v_fma_f32 v1, v20, v48, v54
	v_add_f32_e32 v60, v1, v2
	v_fma_f32 v1, v4, v48, v56
	v_fmac_f32_e32 v55, v21, v49
	v_fmac_f32_e32 v57, v5, v49
	ds_read2st64_b32 v[4:5], v203 offset0:2 offset1:3
	ds_read2st64_b32 v[20:21], v190 offset0:146 offset1:147
	ds_read2st64_b32 v[48:49], v190 offset0:162 offset1:163
	v_and_b32_e32 v2, 0xffff0000, v52
	v_add_f32_e32 v59, v1, v2
	v_lshlrev_b32_e32 v1, 16, v53
	v_add_f32_e32 v58, v55, v1
	v_and_b32_e32 v1, 0xffff0000, v53
	v_add_f32_e32 v57, v57, v1
	s_waitcnt lgkmcnt(0)
	v_fma_f32 v1, v22, v50, v20
	v_lshlrev_b32_e32 v2, 16, v4
	v_add_f32_e32 v56, v1, v2
	v_fma_f32 v1, v6, v50, v48
	v_and_b32_e32 v2, 0xffff0000, v4
	v_add_f32_e32 v55, v1, v2
	v_fmac_f32_e32 v21, v23, v51
	v_lshlrev_b32_e32 v1, 16, v5
	v_add_f32_e32 v54, v21, v1
	v_fmac_f32_e32 v49, v7, v51
	v_and_b32_e32 v1, 0xffff0000, v5
	ds_read2st64_b32 v[4:5], v203 offset0:4 offset1:5
	ds_read2st64_b32 v[6:7], v190 offset0:148 offset1:149
	ds_read2st64_b32 v[20:21], v190 offset0:164 offset1:165
	v_add_f32_e32 v53, v49, v1
	s_waitcnt lgkmcnt(0)
	v_lshlrev_b32_e32 v2, 16, v4
	v_fma_f32 v1, v24, v44, v6
	v_add_f32_e32 v52, v1, v2
	v_fma_f32 v1, v8, v44, v20
	v_and_b32_e32 v2, 0xffff0000, v4
	v_add_f32_e32 v51, v1, v2
	v_fmac_f32_e32 v7, v25, v45
	v_lshlrev_b32_e32 v1, 16, v5
	v_add_f32_e32 v50, v7, v1
	v_and_b32_e32 v1, 0xffff0000, v5
	ds_read2st64_b32 v[4:5], v203 offset0:6 offset1:7
	ds_read2st64_b32 v[6:7], v190 offset0:150 offset1:151
	v_fmac_f32_e32 v21, v9, v45
	ds_read2st64_b32 v[8:9], v190 offset0:166 offset1:167
	v_add_f32_e32 v49, v21, v1
	s_waitcnt lgkmcnt(0)
	v_lshlrev_b32_e32 v2, 16, v4
	v_fma_f32 v1, v26, v46, v6
	v_add_f32_e32 v48, v1, v2
	v_fma_f32 v1, v10, v46, v8
	v_and_b32_e32 v2, 0xffff0000, v4
	v_add_f32_e32 v46, v1, v2
	v_fmac_f32_e32 v7, v27, v47
	v_lshlrev_b32_e32 v1, 16, v5
	v_add_f32_e32 v45, v7, v1
	v_fmac_f32_e32 v9, v11, v47
	v_and_b32_e32 v1, 0xffff0000, v5
	ds_read2st64_b32 v[4:5], v203 offset0:8 offset1:9
	ds_read2st64_b32 v[6:7], v190 offset0:152 offset1:153
	v_add_f32_e32 v44, v9, v1
	ds_read2st64_b32 v[8:9], v190 offset0:168 offset1:169
	s_waitcnt lgkmcnt(0)
	v_lshlrev_b32_e32 v2, 16, v4
	v_fma_f32 v1, v28, v40, v6
	v_add_f32_e32 v27, v1, v2
	v_fma_f32 v1, v12, v40, v8
	v_and_b32_e32 v2, 0xffff0000, v4
	v_add_f32_e32 v26, v1, v2
	v_fmac_f32_e32 v7, v29, v41
	v_lshlrev_b32_e32 v1, 16, v5
	v_add_f32_e32 v25, v7, v1
	v_fmac_f32_e32 v9, v13, v41
	v_and_b32_e32 v1, 0xffff0000, v5
	ds_read2st64_b32 v[4:5], v203 offset0:10 offset1:11
	ds_read2st64_b32 v[6:7], v190 offset0:154 offset1:155
	v_add_f32_e32 v24, v9, v1
	ds_read2st64_b32 v[8:9], v190 offset0:170 offset1:171
	s_waitcnt lgkmcnt(0)
	v_lshlrev_b32_e32 v2, 16, v4
	v_fma_f32 v1, v30, v42, v6
	v_add_f32_e32 v23, v1, v2
	v_fma_f32 v1, v14, v42, v8
	v_and_b32_e32 v2, 0xffff0000, v4
	v_add_f32_e32 v22, v1, v2
	v_fmac_f32_e32 v7, v31, v43
	v_lshlrev_b32_e32 v1, 16, v5
	v_add_f32_e32 v21, v7, v1
	v_fmac_f32_e32 v9, v15, v43
	v_and_b32_e32 v1, 0xffff0000, v5
	ds_read2st64_b32 v[4:5], v203 offset0:12 offset1:13
	ds_read2st64_b32 v[6:7], v190 offset0:156 offset1:157
	v_add_f32_e32 v15, v9, v1
	ds_read2st64_b32 v[8:9], v190 offset0:172 offset1:173
	s_waitcnt lgkmcnt(0)
	v_lshlrev_b32_e32 v2, 16, v4
	v_fma_f32 v1, v32, v36, v6
	v_add_f32_e32 v20, v1, v2
	v_fma_f32 v1, v16, v36, v8
	v_and_b32_e32 v2, 0xffff0000, v4
	v_add_f32_e32 v14, v1, v2
	v_fmac_f32_e32 v7, v33, v37
	v_lshlrev_b32_e32 v1, 16, v5
	v_add_f32_e32 v13, v7, v1
	v_fmac_f32_e32 v9, v17, v37
	v_and_b32_e32 v1, 0xffff0000, v5
	ds_read2st64_b32 v[4:5], v203 offset0:14 offset1:15
	ds_read2st64_b32 v[6:7], v190 offset0:158 offset1:159
	v_add_f32_e32 v12, v9, v1
	ds_read2st64_b32 v[8:9], v190 offset0:174 offset1:175
	s_waitcnt lgkmcnt(0)
	v_lshlrev_b32_e32 v2, 16, v4
	v_fma_f32 v1, v34, v38, v6
	v_add_f32_e32 v10, v1, v2
	v_fma_f32 v1, v18, v38, v8
	v_and_b32_e32 v2, 0xffff0000, v4
	v_add_f32_e32 v11, v1, v2
	v_fmac_f32_e32 v7, v35, v39
	v_lshlrev_b32_e32 v1, 16, v5
	v_add_f32_e32 v2, v7, v1
	v_fmac_f32_e32 v9, v19, v39
	v_and_b32_e32 v1, 0xffff0000, v5
	v_mov_b32_e32 v135, v3
	v_add_f32_e32 v1, v9, v1
	v_lshl_add_u64 v[8:9], s[0:1], 0, v[134:135]
	s_mov_b64 s[0:1], 0xb500000
	v_lshl_add_u64 v[16:17], v[8:9], 0, s[0:1]
	v_lshl_add_u64 v[4:5], v[16:17], 0, v[126:127]
	s_barrier
; #define LAS __attribute__((address_space(3)))
; #define LDS_WAIT() asm volatile("s_waitcnt lgkmcnt(0)" ::: "memory")
; DI unsigned cvtpk(float lo, float hi) { f32x2 v = {lo, hi}; bf16x2_t b = __builtin_convertvector(v, bf16x2_t); return __builtin_bit_cast(unsigned, b); }
; DI float bf2f(bf16 b) { return __uint_as_float(((unsigned)b) << 16); }
; DI float siluf_(float x) { return x / (1.f + __expf(-x)); }
; DI void nsa_unit(const Ctx& c0, int b, int g, int i, LAS unsigned char* lds) {
;     ...
;       for (int it = 0; it < 4; ++it) { const int rw = 8 * it + (lane >> 3), ch = lane & 7;
;           *(LAS u32x4*)(S + rw * 128 + ch * 16) = *(const u32x4*)(nzg + (size_t)rw * 512 + ch * 8); }
;       LDS_WAIT();
; #pragma unroll
;       for (int rg = 0; rg < 16; ++rg) { LAS bf16* e = (LAS bf16*)(S + ((rg & 3) + 8 * (rg >> 2) + 4 * hi) * 128 + r * 2);
;           const float z0 = bf2f(e[0]), z1 = bf2f(e[32]);
;           e[0] = (bf16)(cvtpk(ca0[rg] * siluf_(z0), 0.f) & 0xffffu);
;           e[32] = (bf16)(cvtpk(ca1[rg] * siluf_(z1), 0.f) & 0xffffu); }
	s_add_i32 s25, s25, 1
	s_cmp_eq_u32 s25, 4
	s_waitcnt vmcnt(0) lgkmcnt(0)
	ds_write_b128 v211, v[230:233]
	ds_write_b128 v212, v[234:237]
	ds_write_b128 v213, v[238:241]
	ds_write_b128 v214, v[242:245]
	s_waitcnt lgkmcnt(0)
	ds_read_u16 v4, v215
	ds_read_u16 v5, v215 offset:64
	s_waitcnt lgkmcnt(1)
	v_lshlrev_b32_e32 v4, 16, v4
	v_mul_f32_e32 v6, 0xbfb8aa3b, v4
	v_exp_f32_e32 v6, v6
	s_waitcnt lgkmcnt(0)
	v_lshlrev_b32_e32 v5, 16, v5
	v_add_f32_e32 v6, 1.0, v6
	v_rcp_f32_e32 v7, v6
	s_nop 0
	v_mul_f32_e32 v4, v4, v7
	v_mul_f32_e32 v4, v60, v4
	v_cvt_pk_bf16_f32 v4, v4, v4
	ds_write_b16 v215, v4
	v_mul_f32_e32 v4, 0xbfb8aa3b, v5
	v_exp_f32_e32 v4, v4
	s_nop 0
	v_add_f32_e32 v4, 1.0, v4
	v_div_scale_f32 v6, s[0:1], v4, v4, v5
	s_nop 0
	v_rcp_f32_e32 v4, v4
	s_nop 0
	v_mul_f32_e32 v4, v5, v4
	v_mul_f32_e32 v4, v59, v4
	v_cvt_pk_bf16_f32 v4, v4, s0
	ds_write_b16 v215, v4 offset:64
	ds_read_u16 v4, v215 offset:128
	ds_read_u16 v5, v215 offset:192
	s_waitcnt lgkmcnt(1)
	v_lshlrev_b32_e32 v4, 16, v4
	v_mul_f32_e32 v6, 0xbfb8aa3b, v4
	v_exp_f32_e32 v6, v6
	s_waitcnt lgkmcnt(0)
	v_lshlrev_b32_e32 v5, 16, v5
	v_add_f32_e32 v6, 1.0, v6
	v_rcp_f32_e32 v7, v6
	s_nop 0
	v_mul_f32_e32 v4, v4, v7
	v_mul_f32_e32 v4, v58, v4
	v_cvt_pk_bf16_f32 v4, v4, v4
	ds_write_b16 v215, v4 offset:128
	v_mul_f32_e32 v4, 0xbfb8aa3b, v5
	v_exp_f32_e32 v4, v4
	s_nop 0
	v_add_f32_e32 v4, 1.0, v4
	v_div_scale_f32 v6, s[0:1], v4, v4, v5
	s_nop 0
	v_rcp_f32_e32 v4, v4
	s_nop 0
	v_mul_f32_e32 v4, v5, v4
	v_mul_f32_e32 v4, v57, v4
	v_cvt_pk_bf16_f32 v4, v4, s0
	ds_write_b16 v215, v4 offset:192
	ds_read_u16 v4, v215 offset:256
	ds_read_u16 v5, v215 offset:320
	s_waitcnt lgkmcnt(1)
	v_lshlrev_b32_e32 v4, 16, v4
	v_mul_f32_e32 v6, 0xbfb8aa3b, v4
	v_exp_f32_e32 v6, v6
	s_waitcnt lgkmcnt(0)
	v_lshlrev_b32_e32 v5, 16, v5
	v_add_f32_e32 v6, 1.0, v6
	v_rcp_f32_e32 v7, v6
	s_nop 0
	v_mul_f32_e32 v4, v4, v7
	v_mul_f32_e32 v4, v56, v4
	v_cvt_pk_bf16_f32 v4, v4, v4
	ds_write_b16 v215, v4 offset:256
	v_mul_f32_e32 v4, 0xbfb8aa3b, v5
	v_exp_f32_e32 v4, v4
	s_nop 0
	v_add_f32_e32 v4, 1.0, v4
	v_div_scale_f32 v6, s[0:1], v4, v4, v5
	s_nop 0
	v_rcp_f32_e32 v4, v4
	s_nop 0
	v_mul_f32_e32 v4, v5, v4
	v_mul_f32_e32 v4, v55, v4
	v_cvt_pk_bf16_f32 v4, v4, s0
	ds_write_b16 v215, v4 offset:320
	ds_read_u16 v4, v215 offset:384
	ds_read_u16 v5, v215 offset:448
	s_waitcnt lgkmcnt(1)
	v_lshlrev_b32_e32 v4, 16, v4
	v_mul_f32_e32 v6, 0xbfb8aa3b, v4
	v_exp_f32_e32 v6, v6
	s_waitcnt lgkmcnt(0)
	v_lshlrev_b32_e32 v5, 16, v5
	v_add_f32_e32 v6, 1.0, v6
	v_rcp_f32_e32 v7, v6
	s_nop 0
	v_mul_f32_e32 v4, v4, v7
	v_mul_f32_e32 v4, v54, v4
	v_cvt_pk_bf16_f32 v4, v4, v4
	ds_write_b16 v215, v4 offset:384
	v_mul_f32_e32 v4, 0xbfb8aa3b, v5
	v_exp_f32_e32 v4, v4
	s_nop 0
	v_add_f32_e32 v4, 1.0, v4
	v_div_scale_f32 v6, s[0:1], v4, v4, v5
	s_nop 0
	v_rcp_f32_e32 v4, v4
	s_nop 0
	v_mul_f32_e32 v4, v5, v4
	v_mul_f32_e32 v4, v53, v4
	v_cvt_pk_bf16_f32 v4, v4, s0
	ds_write_b16 v215, v4 offset:448
	ds_read_u16 v4, v215 offset:1024
	ds_read_u16 v5, v215 offset:1088
	s_waitcnt lgkmcnt(1)
	v_lshlrev_b32_e32 v4, 16, v4
	v_mul_f32_e32 v6, 0xbfb8aa3b, v4
	v_exp_f32_e32 v6, v6
	s_waitcnt lgkmcnt(0)
	v_lshlrev_b32_e32 v5, 16, v5
	v_add_f32_e32 v6, 1.0, v6
	v_rcp_f32_e32 v7, v6
	s_nop 0
	v_mul_f32_e32 v4, v4, v7
	v_mul_f32_e32 v4, v52, v4
	v_cvt_pk_bf16_f32 v4, v4, v4
	ds_write_b16 v215, v4 offset:1024
	v_mul_f32_e32 v4, 0xbfb8aa3b, v5
	v_exp_f32_e32 v4, v4
	s_nop 0
	v_add_f32_e32 v4, 1.0, v4
	v_div_scale_f32 v6, s[0:1], v4, v4, v5
	s_nop 0
	v_rcp_f32_e32 v4, v4
	s_nop 0
	v_mul_f32_e32 v4, v5, v4
	v_mul_f32_e32 v4, v51, v4
	v_cvt_pk_bf16_f32 v4, v4, s0
	ds_write_b16 v215, v4 offset:1088
	ds_read_u16 v4, v215 offset:1152
	ds_read_u16 v5, v215 offset:1216
	s_waitcnt lgkmcnt(1)
	v_lshlrev_b32_e32 v4, 16, v4
	v_mul_f32_e32 v6, 0xbfb8aa3b, v4
	v_exp_f32_e32 v6, v6
	s_waitcnt lgkmcnt(0)
	v_lshlrev_b32_e32 v5, 16, v5
	v_add_f32_e32 v6, 1.0, v6
	v_rcp_f32_e32 v7, v6
	s_nop 0
	v_mul_f32_e32 v4, v4, v7
	v_mul_f32_e32 v4, v50, v4
	v_cvt_pk_bf16_f32 v4, v4, v4
	ds_write_b16 v215, v4 offset:1152
	v_mul_f32_e32 v4, 0xbfb8aa3b, v5
	v_exp_f32_e32 v4, v4
	s_nop 0
	v_add_f32_e32 v4, 1.0, v4
	v_div_scale_f32 v6, s[0:1], v4, v4, v5
	s_nop 0
	v_rcp_f32_e32 v4, v4
	s_nop 0
	v_mul_f32_e32 v4, v5, v4
	v_mul_f32_e32 v4, v49, v4
	v_cvt_pk_bf16_f32 v4, v4, s0
	ds_write_b16 v215, v4 offset:1216
	ds_read_u16 v4, v215 offset:1280
	ds_read_u16 v5, v215 offset:1344
	s_waitcnt lgkmcnt(1)
	v_lshlrev_b32_e32 v4, 16, v4
	v_mul_f32_e32 v6, 0xbfb8aa3b, v4
	v_exp_f32_e32 v6, v6
	s_waitcnt lgkmcnt(0)
	v_lshlrev_b32_e32 v5, 16, v5
	v_add_f32_e32 v6, 1.0, v6
	v_rcp_f32_e32 v7, v6
	s_nop 0
	v_mul_f32_e32 v4, v4, v7
	v_mul_f32_e32 v4, v48, v4
	v_cvt_pk_bf16_f32 v4, v4, v4
	ds_write_b16 v215, v4 offset:1280
	v_mul_f32_e32 v4, 0xbfb8aa3b, v5
	v_exp_f32_e32 v4, v4
	s_nop 0
	v_add_f32_e32 v4, 1.0, v4
	v_div_scale_f32 v6, s[0:1], v4, v4, v5
	s_nop 0
	v_rcp_f32_e32 v4, v4
	s_nop 0
	v_mul_f32_e32 v4, v5, v4
	v_mul_f32_e32 v4, v46, v4
	v_cvt_pk_bf16_f32 v4, v4, s0
	ds_write_b16 v215, v4 offset:1344
	ds_read_u16 v4, v215 offset:1408
	s_waitcnt lgkmcnt(0)
	v_lshlrev_b32_e32 v5, 16, v4
	v_mul_f32_e32 v6, 0xbfb8aa3b, v5
	v_exp_f32_e32 v6, v6
	ds_read_u16 v4, v215 offset:1472
	v_add_f32_e32 v6, 1.0, v6
	v_div_scale_f32 v7, s[0:1], v6, v6, v5
	s_waitcnt lgkmcnt(0)
	v_lshlrev_b32_e32 v4, 16, v4
	v_rcp_f32_e32 v7, v6
	s_nop 0
	v_mul_f32_e32 v5, v5, v7
	v_mul_f32_e32 v5, v45, v5
	v_cvt_pk_bf16_f32 v5, v5, s0
	ds_write_b16 v215, v5 offset:1408
	v_mul_f32_e32 v5, 0xbfb8aa3b, v4
	v_exp_f32_e32 v5, v5
	s_nop 0
	v_add_f32_e32 v5, 1.0, v5
	v_rcp_f32_e32 v6, v5
	s_nop 0
	v_mul_f32_e32 v4, v4, v6
	v_mul_f32_e32 v4, v44, v4
	v_cvt_pk_bf16_f32 v4, v4, v4
	ds_write_b16 v215, v4 offset:1472
	ds_read_u16 v4, v215 offset:2048
	ds_read_u16 v5, v215 offset:2112
	s_waitcnt lgkmcnt(1)
; #define LAS __attribute__((address_space(3)))
; #define LDS_WAIT() asm volatile("s_waitcnt lgkmcnt(0)" ::: "memory")
; DI unsigned cvtpk(float lo, float hi) { f32x2 v = {lo, hi}; bf16x2_t b = __builtin_convertvector(v, bf16x2_t); return __builtin_bit_cast(unsigned, b); }
; DI float bf2f(bf16 b) { return __uint_as_float(((unsigned)b) << 16); }
; DI float siluf_(float x) { return x / (1.f + __expf(-x)); }
; DI void nsa_unit(const Ctx& c0, int b, int g, int i, LAS unsigned char* lds) {
;     ...
;       for (int rg = 0; rg < 16; ++rg) { LAS bf16* e = (LAS bf16*)(S + ((rg & 3) + 8 * (rg >> 2) + 4 * hi) * 128 + r * 2);
;           const float z0 = bf2f(e[0]), z1 = bf2f(e[32]);
;           e[0] = (bf16)(cvtpk(ca0[rg] * siluf_(z0), 0.f) & 0xffffu);
;           e[32] = (bf16)(cvtpk(ca1[rg] * siluf_(z1), 0.f) & 0xffffu); }
;       LDS_WAIT();
; #pragma unroll
;       for (int it = 0; it < 4; ++it) { const int rw = 8 * it + (lane >> 3), ch = lane & 7;
;           *(u32x4*)(ong + (size_t)rw * 512 + ch * 8) = *(const LAS u32x4*)(S + rw * 128 + ch * 16); }
	v_lshlrev_b32_e32 v4, 16, v4
	v_mul_f32_e32 v6, 0xbfb8aa3b, v4
	v_exp_f32_e32 v6, v6
	s_waitcnt lgkmcnt(0)
	v_lshlrev_b32_e32 v5, 16, v5
	v_add_f32_e32 v6, 1.0, v6
	v_rcp_f32_e32 v7, v6
	s_nop 0
	v_mul_f32_e32 v4, v4, v7
	v_mul_f32_e32 v4, v27, v4
	v_cvt_pk_bf16_f32 v4, v4, v4
	ds_write_b16 v215, v4 offset:2048
	v_mul_f32_e32 v4, 0xbfb8aa3b, v5
	v_exp_f32_e32 v4, v4
	s_nop 0
	v_add_f32_e32 v4, 1.0, v4
	v_div_scale_f32 v6, s[0:1], v4, v4, v5
	s_nop 0
	v_rcp_f32_e32 v4, v4
	s_nop 0
	v_mul_f32_e32 v4, v5, v4
	v_mul_f32_e32 v4, v26, v4
	v_cvt_pk_bf16_f32 v4, v4, s0
	ds_write_b16 v215, v4 offset:2112
	ds_read_u16 v4, v215 offset:2176
	ds_read_u16 v5, v215 offset:2240
	s_waitcnt lgkmcnt(1)
	v_lshlrev_b32_e32 v4, 16, v4
	v_mul_f32_e32 v6, 0xbfb8aa3b, v4
	v_exp_f32_e32 v6, v6
	s_waitcnt lgkmcnt(0)
	v_lshlrev_b32_e32 v5, 16, v5
	v_add_f32_e32 v6, 1.0, v6
	v_rcp_f32_e32 v7, v6
	s_nop 0
	v_mul_f32_e32 v4, v4, v7
	v_mul_f32_e32 v4, v25, v4
	v_cvt_pk_bf16_f32 v4, v4, v4
	ds_write_b16 v215, v4 offset:2176
	v_mul_f32_e32 v4, 0xbfb8aa3b, v5
	v_exp_f32_e32 v4, v4
	s_nop 0
	v_add_f32_e32 v4, 1.0, v4
	v_div_scale_f32 v6, s[0:1], v4, v4, v5
	s_nop 0
	v_rcp_f32_e32 v4, v4
	s_nop 0
	v_mul_f32_e32 v4, v5, v4
	v_mul_f32_e32 v4, v24, v4
	v_cvt_pk_bf16_f32 v4, v4, s0
	ds_write_b16 v215, v4 offset:2240
	ds_read_u16 v4, v215 offset:2304
	ds_read_u16 v5, v215 offset:2368
	s_waitcnt lgkmcnt(1)
	v_lshlrev_b32_e32 v4, 16, v4
	v_mul_f32_e32 v6, 0xbfb8aa3b, v4
	v_exp_f32_e32 v6, v6
	s_waitcnt lgkmcnt(0)
	v_lshlrev_b32_e32 v5, 16, v5
	v_add_f32_e32 v6, 1.0, v6
	v_rcp_f32_e32 v7, v6
	s_nop 0
	v_mul_f32_e32 v4, v4, v7
	v_mul_f32_e32 v4, v23, v4
	v_cvt_pk_bf16_f32 v4, v4, v4
	ds_write_b16 v215, v4 offset:2304
	v_mul_f32_e32 v4, 0xbfb8aa3b, v5
	v_exp_f32_e32 v4, v4
	s_nop 0
	v_add_f32_e32 v4, 1.0, v4
	v_div_scale_f32 v6, s[0:1], v4, v4, v5
	s_nop 0
	v_rcp_f32_e32 v4, v4
	s_nop 0
	v_mul_f32_e32 v4, v5, v4
	v_mul_f32_e32 v4, v22, v4
	v_cvt_pk_bf16_f32 v4, v4, s0
	ds_write_b16 v215, v4 offset:2368
	ds_read_u16 v4, v215 offset:2432
	ds_read_u16 v5, v215 offset:2496
	s_waitcnt lgkmcnt(1)
	v_lshlrev_b32_e32 v4, 16, v4
	v_mul_f32_e32 v6, 0xbfb8aa3b, v4
	v_exp_f32_e32 v6, v6
	s_waitcnt lgkmcnt(0)
	v_lshlrev_b32_e32 v5, 16, v5
	v_add_f32_e32 v6, 1.0, v6
	v_rcp_f32_e32 v7, v6
	s_nop 0
	v_mul_f32_e32 v4, v4, v7
	v_mul_f32_e32 v4, v21, v4
	v_cvt_pk_bf16_f32 v4, v4, v4
	ds_write_b16 v215, v4 offset:2432
	v_mul_f32_e32 v4, 0xbfb8aa3b, v5
	v_exp_f32_e32 v4, v4
	s_nop 0
	v_add_f32_e32 v4, 1.0, v4
	v_div_scale_f32 v6, s[0:1], v4, v4, v5
	s_nop 0
	v_rcp_f32_e32 v4, v4
	s_nop 0
	v_mul_f32_e32 v4, v5, v4
	v_mul_f32_e32 v4, v15, v4
	v_cvt_pk_bf16_f32 v4, v4, s0
	ds_write_b16 v215, v4 offset:2496
	ds_read_u16 v4, v215 offset:3072
	ds_read_u16 v5, v215 offset:3136
	s_waitcnt lgkmcnt(1)
	v_lshlrev_b32_e32 v4, 16, v4
	v_mul_f32_e32 v6, 0xbfb8aa3b, v4
	v_exp_f32_e32 v6, v6
	s_waitcnt lgkmcnt(0)
	v_lshlrev_b32_e32 v5, 16, v5
	v_add_f32_e32 v6, 1.0, v6
	v_rcp_f32_e32 v7, v6
	s_nop 0
	v_mul_f32_e32 v4, v4, v7
	v_mul_f32_e32 v4, v20, v4
	v_cvt_pk_bf16_f32 v4, v4, v4
	ds_write_b16 v215, v4 offset:3072
	v_mul_f32_e32 v4, 0xbfb8aa3b, v5
	v_exp_f32_e32 v4, v4
	s_nop 0
	v_add_f32_e32 v4, 1.0, v4
	v_div_scale_f32 v6, s[0:1], v4, v4, v5
	s_nop 0
	v_rcp_f32_e32 v4, v4
	s_nop 0
	v_mul_f32_e32 v4, v5, v4
	v_mul_f32_e32 v4, v14, v4
	v_cvt_pk_bf16_f32 v4, v4, s0
	ds_write_b16 v215, v4 offset:3136
	ds_read_u16 v4, v215 offset:3200
	ds_read_u16 v5, v215 offset:3264
	s_waitcnt lgkmcnt(1)
	v_lshlrev_b32_e32 v4, 16, v4
	v_mul_f32_e32 v6, 0xbfb8aa3b, v4
	v_exp_f32_e32 v6, v6
	s_waitcnt lgkmcnt(0)
	v_lshlrev_b32_e32 v5, 16, v5
	v_add_f32_e32 v6, 1.0, v6
	v_rcp_f32_e32 v7, v6
	s_nop 0
	v_mul_f32_e32 v4, v4, v7
	v_mul_f32_e32 v4, v13, v4
	v_cvt_pk_bf16_f32 v4, v4, v4
	ds_write_b16 v215, v4 offset:3200
	v_mul_f32_e32 v4, 0xbfb8aa3b, v5
	v_exp_f32_e32 v4, v4
	s_nop 0
	v_add_f32_e32 v4, 1.0, v4
	v_div_scale_f32 v6, s[0:1], v4, v4, v5
	s_nop 0
	v_rcp_f32_e32 v4, v4
	s_nop 0
	v_mul_f32_e32 v4, v5, v4
	v_mul_f32_e32 v4, v12, v4
	v_cvt_pk_bf16_f32 v4, v4, s0
	ds_write_b16 v215, v4 offset:3264
	ds_read_u16 v4, v215 offset:3328
	ds_read_u16 v5, v215 offset:3392
	s_waitcnt lgkmcnt(1)
	v_lshlrev_b32_e32 v4, 16, v4
	v_mul_f32_e32 v6, 0xbfb8aa3b, v4
	v_exp_f32_e32 v6, v6
	s_waitcnt lgkmcnt(0)
	v_lshlrev_b32_e32 v5, 16, v5
	v_add_f32_e32 v6, 1.0, v6
	v_rcp_f32_e32 v7, v6
	s_nop 0
	v_mul_f32_e32 v4, v4, v7
	v_mul_f32_e32 v4, v10, v4
	v_cvt_pk_bf16_f32 v4, v4, v4
	ds_write_b16 v215, v4 offset:3328
	v_mul_f32_e32 v4, 0xbfb8aa3b, v5
	v_exp_f32_e32 v4, v4
	s_nop 0
	v_add_f32_e32 v4, 1.0, v4
	v_div_scale_f32 v6, s[0:1], v4, v4, v5
	s_nop 0
	v_rcp_f32_e32 v4, v4
	s_nop 0
	v_mul_f32_e32 v4, v5, v4
	v_mul_f32_e32 v4, v11, v4
	v_cvt_pk_bf16_f32 v4, v4, s0
	ds_write_b16 v215, v4 offset:3392
	ds_read_u16 v4, v215 offset:3456
	ds_read_u16 v5, v215 offset:3520
	s_waitcnt lgkmcnt(1)
	v_lshlrev_b32_e32 v4, 16, v4
	v_mul_f32_e32 v6, 0xbfb8aa3b, v4
	v_exp_f32_e32 v6, v6
	s_waitcnt lgkmcnt(0)
	v_lshlrev_b32_e32 v5, 16, v5
	v_add_f32_e32 v6, 1.0, v6
	v_div_scale_f32 v7, s[0:1], v6, v6, v4
	s_nop 0
	v_rcp_f32_e32 v7, v6
	s_nop 0
	v_mul_f32_e32 v4, v4, v7
	v_mul_f32_e32 v2, v2, v4
	v_cvt_pk_bf16_f32 v2, v2, s0
	ds_write_b16 v215, v2 offset:3456
	v_mul_f32_e32 v2, 0xbfb8aa3b, v5
	v_exp_f32_e32 v2, v2
	s_nop 0
	v_add_f32_e32 v2, 1.0, v2
	v_div_scale_f32 v4, s[0:1], v2, v2, v5
	s_nop 0
	v_rcp_f32_e32 v2, v2
	s_nop 0
	v_mul_f32_e32 v2, v5, v2
	v_mul_f32_e32 v1, v1, v2
	v_cvt_pk_bf16_f32 v1, v1, s0
	ds_write_b16 v215, v1 offset:3520
	s_waitcnt lgkmcnt(0)
	ds_read_b128 v[4:7], v211
	s_mov_b64 s[0:1], 0xd500000
	v_lshl_add_u64 v[8:9], v[8:9], 0, s[0:1]
	v_lshl_add_u64 v[10:11], v[8:9], 0, v[126:127]
	s_waitcnt lgkmcnt(0)
	global_store_dwordx4 v[10:11], v[4:7], off
	ds_read_b128 v[4:7], v212
	v_lshl_add_u64 v[10:11], v[8:9], 0, v[128:129]
	s_waitcnt lgkmcnt(0)
	global_store_dwordx4 v[10:11], v[4:7], off
	ds_read_b128 v[4:7], v213
	v_lshl_add_u64 v[10:11], v[8:9], 0, v[130:131]
	v_lshl_add_u64 v[8:9], v[8:9], 0, v[132:133]
	s_waitcnt lgkmcnt(0)
	global_store_dwordx4 v[10:11], v[4:7], off
	ds_read_b128 v[4:7], v214
	s_waitcnt lgkmcnt(0)
	global_store_dwordx4 v[8:9], v[4:7], off
	s_waitcnt lgkmcnt(0)
	s_cbranch_scc1 .LBB0_1151

; #define MFMA32(a, b, c) __builtin_amdgcn_mfma_f32_32x32x16_bf16((a), (b), (c), 0, 0, 0)
; DI void gla_stage3(const Ctx& c0, int layer, int unit, int cb, LAS unsigned char* lds) {
;     ...
;     const bf16* qgp = (const bf16*)(c.ws + O_QG) + (row0 + r) * 256 + h * 64 + 8 * hi;
;     const float* sp = (const float*)(c.ws + O_UPD) + (size_t)unit * 8192;
;     const float* gn = c.a->in[I_GNORM] + (size_t)layer * 128;
;     bf16x8 qf[4];
; #pragma unroll
;     for (int s = 0; s < 4; ++s) qf[s] = *(const bf16x8*)(qgp + 16 * s);
;     f32x16 o[4];
; #pragma unroll
;     for (int vb = 0; vb < 4; ++vb) {
;         o[vb] = f32x16{};
; #pragma unroll
;         for (int s = 0; s < 4; ++s) { const float* s0 = sp + (size_t)(16 * s + 8 * hi) * 128 + 32 * vb + r;
;             const bf16x8 bfv = pack8(s0[0], s0[128], s0[256], s0[384], s0[512], s0[640], s0[768], s0[896]);
;             o[vb] = MFMA32(qf[s], bfv, o[vb]); }
;         asm volatile("" ::: "memory");
;     }
.LBB0_1216:
	s_mov_b64 s[0:1], s[74:75]
	s_mov_b64 s[2:3], s[72:73]
	s_ashr_i32 s2, s34, 8
	s_ashr_i32 s3, s2, 31
	s_lshl_b64 s[2:3], s[2:3], 12
	s_and_b32 s9, s4, 0xfc0
	s_or_b32 s2, s2, s9
	s_or_b64 s[2:3], s[2:3], s[10:11]
	v_mov_b32_e32 v3, s3
	v_or_b32_e32 v2, s2, v152
	s_bfe_u32 s8, s34, 0x20006
	v_lshlrev_b64 v[2:3], 9, v[2:3]
	v_lshl_add_u64 v[2:3], s[0:1], 0, v[2:3]
	s_lshl_b32 s12, s8, 7
	v_lshl_add_u64 v[2:3], v[2:3], 0, s[12:13]
	v_lshl_add_u64 v[2:3], v[2:3], 0, v[86:87]
	v_lshl_add_u64 v[4:5], v[2:3], 0, s[18:19]
	v_add_co_u32_e32 v2, vcc, s6, v2
	v_lshl_add_u64 v[90:91], s[0:1], 0, v[84:85]
	s_nop 0
	v_addc_co_u32_e32 v3, vcc, 0, v3, vcc
	global_load_dwordx4 v[50:53], v[2:3], off
	global_load_dwordx4 v[110:113], v[4:5], off offset:96
	global_load_dwordx4 v[106:109], v[4:5], off offset:64
	global_load_dwordx4 v[102:105], v[4:5], off offset:32
	v_add_co_u32_e32 v2, vcc, s7, v90
	s_lshl_b64 s[2:3], s[2:3], 10
	s_nop 0
	v_addc_co_u32_e32 v3, vcc, -1, v91, vcc
	v_add_co_u32_e32 v58, vcc, s28, v90
	global_load_dword v2, v[2:3], off
	s_nop 0
	v_addc_co_u32_e32 v59, vcc, -1, v91, vcc
	global_load_dword v3, v[58:59], off offset:384
	global_load_dword v4, v[58:59], off offset:896
	global_load_dword v5, v[58:59], off offset:1408
	global_load_dword v6, v[58:59], off offset:1920
	global_load_dword v7, v[58:59], off offset:2432
	global_load_dword v8, v[58:59], off offset:2944
	global_load_dword v9, v[58:59], off offset:3456
	v_add_co_u32_e32 v18, vcc, s15, v90
	s_lshl_b32 s8, s8, 8
	s_nop 0
	v_addc_co_u32_e32 v19, vcc, -1, v91, vcc
	v_add_co_u32_e32 v114, vcc, s29, v90
	global_load_dword v18, v[18:19], off
	s_nop 0
	v_addc_co_u32_e32 v115, vcc, -1, v91, vcc
	global_load_dword v19, v[114:115], off offset:384
	global_load_dword v20, v[114:115], off offset:896
	global_load_dword v21, v[114:115], off offset:1408
	global_load_dword v22, v[114:115], off offset:1920
	global_load_dword v23, v[114:115], off offset:2432
	global_load_dword v24, v[114:115], off offset:2944
	global_load_dword v25, v[114:115], off offset:3456
	s_add_u32 s0, s0, s2
	s_addc_u32 s1, s1, s3
	s_add_u32 s0, s0, s8
	s_addc_u32 s1, s1, 0
	s_add_i32 s34, s34, s14
	s_add_i32 s4, s4, s5
	v_lshl_add_u64 v[84:85], v[84:85], 0, s[16:17]
	s_cmpk_lt_i32 s34, 0x800
	s_waitcnt vmcnt(0) lgkmcnt(0)
	global_load_dword v41, v[114:115], off offset:3584
	global_load_dword v40, v[114:115], off offset:3072
	global_load_dword v39, v[114:115], off offset:2560
	global_load_dword v38, v[114:115], off offset:2048
	global_load_dword v37, v[114:115], off offset:1536
	global_load_dword v36, v[114:115], off offset:1024
	global_load_dword v35, v[114:115], off offset:512
	global_load_dword v34, v[114:115], off
	global_load_dword v145, v[58:59], off offset:3584
	global_load_dword v146, v[58:59], off offset:3072
	global_load_dword v143, v[58:59], off offset:2560
	global_load_dword v144, v[58:59], off offset:2048
	global_load_dword v141, v[58:59], off offset:1536
	global_load_dword v142, v[58:59], off offset:1024
	global_load_dword v139, v[58:59], off offset:512
	global_load_dword v140, v[58:59], off
	v_cvt_pk_bf16_f32 v2, v2, v3
	v_cvt_pk_bf16_f32 v3, v4, v5
	v_cvt_pk_bf16_f32 v4, v6, v7
	v_cvt_pk_bf16_f32 v5, v8, v9
	v_cvt_pk_bf16_f32 v18, v18, v19
	s_nop 0
	v_mfma_f32_32x32x16_bf16 v[2:17], v[50:53], v[2:5], 0
	v_cvt_pk_bf16_f32 v19, v20, v21
	v_cvt_pk_bf16_f32 v20, v22, v23
	v_cvt_pk_bf16_f32 v21, v24, v25
	s_nop 1
	v_mfma_f32_32x32x16_bf16 v[2:17], v[102:105], v[18:21], v[2:17]
	v_add_co_u32_e32 v18, vcc, s26, v90
	s_nop 1
	v_addc_co_u32_e32 v19, vcc, -1, v91, vcc
	v_add_co_u32_e32 v118, vcc, s30, v90
	global_load_dword v18, v[18:19], off
	s_nop 0
	v_addc_co_u32_e32 v119, vcc, -1, v91, vcc
	global_load_dword v19, v[118:119], off offset:384
	global_load_dword v20, v[118:119], off offset:896
	global_load_dword v21, v[118:119], off offset:1408
	global_load_dword v22, v[118:119], off offset:1920
	global_load_dword v23, v[118:119], off offset:2432
	global_load_dword v24, v[118:119], off offset:2944
	global_load_dword v25, v[118:119], off offset:3456
	s_waitcnt vmcnt(0) lgkmcnt(0)
	global_load_dword v63, v[114:115], off offset:3712
	global_load_dword v62, v[114:115], off offset:3200
	global_load_dword v61, v[114:115], off offset:2688
	global_load_dword v60, v[114:115], off offset:2176
	global_load_dword v57, v[114:115], off offset:1664
	global_load_dword v56, v[114:115], off offset:1152
	global_load_dword v55, v[114:115], off offset:640
	global_load_dword v54, v[114:115], off offset:128
	global_load_dword v173, v[58:59], off offset:3712
	global_load_dword v176, v[58:59], off offset:3200
	global_load_dword v171, v[58:59], off offset:2688
	global_load_dword v174, v[58:59], off offset:2176
	global_load_dword v169, v[58:59], off offset:1664
	global_load_dword v172, v[58:59], off offset:1152
	global_load_dword v167, v[58:59], off offset:640
	global_load_dword v170, v[58:59], off offset:128
	global_load_dword v157, v[118:119], off offset:3584
	global_load_dword v160, v[118:119], off offset:3072
	global_load_dword v155, v[118:119], off offset:2560
	global_load_dword v158, v[118:119], off offset:2048
	global_load_dword v149, v[118:119], off offset:1536
	global_load_dword v156, v[118:119], off offset:1024
	global_load_dword v147, v[118:119], off offset:512
	global_load_dword v148, v[118:119], off
	v_cvt_pk_bf16_f32 v18, v18, v19
	v_cvt_pk_bf16_f32 v19, v20, v21
	v_cvt_pk_bf16_f32 v20, v22, v23
	v_cvt_pk_bf16_f32 v21, v24, v25
	s_nop 1
	v_mfma_f32_32x32x16_bf16 v[2:17], v[106:109], v[18:21], v[2:17]
	v_add_co_u32_e32 v18, vcc, s27, v90
	s_nop 1
	v_addc_co_u32_e32 v19, vcc, -1, v91, vcc
	v_add_co_u32_e32 v120, vcc, s31, v90
	global_load_dword v18, v[18:19], off
	s_nop 0
	v_addc_co_u32_e32 v121, vcc, -1, v91, vcc
	global_load_dword v19, v[120:121], off offset:384
	global_load_dword v20, v[120:121], off offset:896
	global_load_dword v21, v[120:121], off offset:1408
	global_load_dword v22, v[120:121], off offset:1920
	global_load_dword v23, v[120:121], off offset:2432
	global_load_dword v24, v[120:121], off offset:2944
	global_load_dword v25, v[120:121], off offset:3456
	v_cmp_lt_i32_e32 vcc, v94, v95
	s_waitcnt vmcnt(0) lgkmcnt(0)
; #define MFMA32(a, b, c) __builtin_amdgcn_mfma_f32_32x32x16_bf16((a), (b), (c), 0, 0, 0)
; DI void gla_stage3(const Ctx& c0, int layer, int unit, int cb, LAS unsigned char* lds) {
;     ...
;     f32x16 o[4];
; #pragma unroll
;     for (int vb = 0; vb < 4; ++vb) {
;         o[vb] = f32x16{};
; #pragma unroll
;         for (int s = 0; s < 4; ++s) { const float* s0 = sp + (size_t)(16 * s + 8 * hi) * 128 + 32 * vb + r;
;             const bf16x8 bfv = pack8(s0[0], s0[128], s0[256], s0[384], s0[512], s0[640], s0[768], s0[896]);
;             o[vb] = MFMA32(qf[s], bfv, o[vb]); }
;         asm volatile("" ::: "memory");
;     }
	global_load_dword v127, v[114:115], off offset:3840
	global_load_dword v126, v[114:115], off offset:3328
	global_load_dword v125, v[114:115], off offset:2816
	global_load_dword v124, v[114:115], off offset:2304
	global_load_dword v123, v[114:115], off offset:1792
	global_load_dword v122, v[114:115], off offset:1280
	global_load_dword v117, v[114:115], off offset:768
	global_load_dword v116, v[114:115], off offset:256
	global_load_dword v214, v[58:59], off offset:3840
	global_load_dword v212, v[58:59], off offset:3328
	global_load_dword v205, v[58:59], off offset:2816
	global_load_dword v210, v[58:59], off offset:2304
	global_load_dword v203, v[58:59], off offset:1792
	global_load_dword v208, v[58:59], off offset:1280
	global_load_dword v201, v[58:59], off offset:768
	global_load_dword v206, v[58:59], off offset:256
	global_load_dword v199, v[120:121], off offset:3712
	global_load_dword v204, v[120:121], off offset:3200
	global_load_dword v197, v[120:121], off offset:2688
	global_load_dword v202, v[120:121], off offset:2176
	global_load_dword v195, v[120:121], off offset:1664
	global_load_dword v200, v[120:121], off offset:1152
	global_load_dword v183, v[120:121], off offset:640
	global_load_dword v198, v[120:121], off offset:128
	global_load_dword v181, v[118:119], off offset:3712
	global_load_dword v196, v[118:119], off offset:3200
	global_load_dword v179, v[118:119], off offset:2688
	global_load_dword v182, v[118:119], off offset:2176
	global_load_dword v177, v[118:119], off offset:1664
	global_load_dword v180, v[118:119], off offset:1152
	global_load_dword v175, v[118:119], off offset:640
	global_load_dword v178, v[118:119], off offset:128
	global_load_dword v165, v[120:121], off offset:3584
	global_load_dword v168, v[120:121], off offset:3072
	global_load_dword v163, v[120:121], off offset:2560
	global_load_dword v166, v[120:121], off offset:2048
	global_load_dword v161, v[120:121], off offset:1536
	global_load_dword v164, v[120:121], off offset:1024
	global_load_dword v159, v[120:121], off offset:512
	global_load_dword v162, v[120:121], off
	v_cvt_pk_bf16_f32 v18, v18, v19
	v_cvt_pk_bf16_f32 v19, v20, v21
	v_cvt_pk_bf16_f32 v20, v22, v23
	v_cvt_pk_bf16_f32 v21, v24, v25
	s_nop 1
	v_mfma_f32_32x32x16_bf16 v[2:17], v[110:113], v[18:21], v[2:17]
	s_waitcnt vmcnt(40) lgkmcnt(0)
	global_load_dword v238, v[82:83], off offset:896
	global_load_dword v236, v[82:83], off offset:768
	global_load_dword v234, v[82:83], off offset:640
	global_load_dword v232, v[82:83], off offset:512
	global_load_dword v90, v[90:91], off
	global_load_dword v230, v[120:121], off offset:3328
	global_load_dword v219, v[120:121], off offset:2816
	global_load_dword v228, v[120:121], off offset:2304
	global_load_dword v217, v[120:121], off offset:1792
	global_load_dword v226, v[120:121], off offset:1280
	global_load_dword v215, v[120:121], off offset:768
	global_load_dword v224, v[120:121], off offset:256
	global_load_dword v213, v[118:119], off offset:3840
	global_load_dword v222, v[118:119], off offset:3328
	global_load_dword v211, v[118:119], off offset:2816
	global_load_dword v220, v[118:119], off offset:2304
	global_load_dword v209, v[118:119], off offset:1792
	global_load_dword v218, v[118:119], off offset:1280
	global_load_dword v207, v[118:119], off offset:768
	global_load_dword v216, v[118:119], off offset:256
	v_cvt_pk_bf16_f32 v18, v140, v139
	v_cvt_pk_bf16_f32 v34, v34, v35
	v_cvt_pk_bf16_f32 v19, v142, v141
	v_cvt_pk_bf16_f32 v35, v36, v37
	v_cvt_pk_bf16_f32 v20, v144, v143
	v_cvt_pk_bf16_f32 v36, v38, v39
	v_cvt_pk_bf16_f32 v21, v146, v145
	v_cvt_pk_bf16_f32 v37, v40, v41
	s_nop 0
	v_mfma_f32_32x32x16_bf16 v[18:33], v[50:53], v[18:21], 0
	v_mfma_f32_32x32x16_bf16 v[18:33], v[102:105], v[34:37], v[18:33]
	s_waitcnt vmcnt(60) lgkmcnt(0)
	v_cvt_pk_bf16_f32 v34, v148, v147
	v_cvt_pk_bf16_f32 v35, v156, v149
	v_cvt_pk_bf16_f32 v36, v158, v155
	v_cvt_pk_bf16_f32 v37, v160, v157
	s_nop 1
	v_mfma_f32_32x32x16_bf16 v[18:33], v[106:109], v[34:37], v[18:33]
	s_waitcnt vmcnt(20) lgkmcnt(0)
	v_cvt_pk_bf16_f32 v34, v162, v159
	v_cvt_pk_bf16_f32 v35, v164, v161
	v_cvt_pk_bf16_f32 v36, v166, v163
	v_cvt_pk_bf16_f32 v37, v168, v165
	s_nop 1
	v_mfma_f32_32x32x16_bf16 v[18:33], v[110:113], v[34:37], v[18:33]
	s_waitcnt vmcnt(62) lgkmcnt(0)
	v_cvt_pk_bf16_f32 v34, v170, v167
	v_cvt_pk_bf16_f32 v54, v54, v55
	v_cvt_pk_bf16_f32 v35, v172, v169
	v_cvt_pk_bf16_f32 v55, v56, v57
	v_cvt_pk_bf16_f32 v36, v174, v171
	v_cvt_pk_bf16_f32 v56, v60, v61
	v_cvt_pk_bf16_f32 v37, v176, v173
	v_cvt_pk_bf16_f32 v57, v62, v63
	s_nop 0
	v_mfma_f32_32x32x16_bf16 v[34:49], v[50:53], v[34:37], 0
	v_mfma_f32_32x32x16_bf16 v[34:49], v[102:105], v[54:57], v[34:49]
	s_waitcnt vmcnt(28) lgkmcnt(0)
	v_cvt_pk_bf16_f32 v54, v178, v175
	v_cvt_pk_bf16_f32 v55, v180, v177
	v_cvt_pk_bf16_f32 v56, v182, v179
	v_cvt_pk_bf16_f32 v57, v196, v181
	s_nop 1
	v_mfma_f32_32x32x16_bf16 v[34:49], v[106:109], v[54:57], v[34:49]
	s_waitcnt vmcnt(36) lgkmcnt(0)
	v_cvt_pk_bf16_f32 v54, v198, v183
	v_cvt_pk_bf16_f32 v55, v200, v195
	v_cvt_pk_bf16_f32 v56, v202, v197
	v_cvt_pk_bf16_f32 v57, v204, v199
	s_nop 1
	v_mfma_f32_32x32x16_bf16 v[34:49], v[110:113], v[54:57], v[34:49]
	s_nop 0
	s_nop 0
	s_waitcnt vmcnt(44) lgkmcnt(0)
	v_cvt_pk_bf16_f32 v54, v206, v201
	v_cvt_pk_bf16_f32 v114, v116, v117
	v_cvt_pk_bf16_f32 v55, v208, v203
	v_cvt_pk_bf16_f32 v115, v122, v123
	v_cvt_pk_bf16_f32 v56, v210, v205
	v_cvt_pk_bf16_f32 v116, v124, v125
	v_cvt_pk_bf16_f32 v57, v212, v214
	v_cvt_pk_bf16_f32 v117, v126, v127
	s_nop 0
	v_mfma_f32_32x32x16_bf16 v[50:65], v[50:53], v[54:57], 0
	v_mfma_f32_32x32x16_bf16 v[50:65], v[102:105], v[114:117], v[50:65]
	s_waitcnt vmcnt(0) lgkmcnt(0)
; #define LAS __attribute__((address_space(3)))
; #define LDS_WAIT() asm volatile("s_waitcnt lgkmcnt(0)" ::: "memory")
; DI float bf2f(bf16 b) { return __uint_as_float(((unsigned)b) << 16); }
; DI void g3_tile_in(const bf16* g, LAS unsigned char* R, int lane) {
; #pragma unroll
;     for (int it = 0; it < 8; ++it) { const int row = 4 * it + (lane >> 4), ch = lane & 15;
;         *(LAS u32x4*)(R + row * G3_PITCH + ch * 16) = *(const u32x4*)(g + (size_t)row * 512 + ch * 8); }
;     LDS_WAIT();
; DI void gla_stage3(const Ctx& c0, int layer, int unit, int cb, LAS unsigned char* lds) {
;     ...
;     g3_tile_in((const bf16*)(c.ws + O_OINTRA) + row0 * 512 + h * 128, R, lane);
; #pragma unroll
;     for (int vb = 0; vb < 4; ++vb) {
; #pragma unroll
;         for (int rg = 0; rg < 16; ++rg) o[vb][rg] += bf2f(*(const LAS bf16*)(Re + ((rg & 3) + 8 * (rg >> 2)) * G3_PITCH + 64 * vb));
;         asm volatile("" ::: "memory");
;     }
	v_cvt_pk_bf16_f32 v102, v216, v207
	v_cvt_pk_bf16_f32 v103, v218, v209
	v_cvt_pk_bf16_f32 v104, v220, v211
	v_cvt_pk_bf16_f32 v105, v222, v213
	s_nop 1
	v_mfma_f32_32x32x16_bf16 v[50:65], v[106:109], v[102:105], v[50:65]
	s_nop 0
	s_waitcnt vmcnt(8) lgkmcnt(0)
	v_cvt_pk_bf16_f32 v102, v224, v215
	v_cvt_pk_bf16_f32 v103, v226, v217
	v_cvt_pk_bf16_f32 v104, v228, v219
	v_cvt_pk_bf16_f32 v105, v230, v90
	v_lshl_add_u64 v[90:91], s[0:1], 0, v[88:89]
	v_lshl_add_u64 v[106:107], v[90:91], 0, s[20:21]
	v_mfma_f32_32x32x16_bf16 v[50:65], v[110:113], v[102:105], v[50:65]
	v_lshl_add_u64 v[102:103], v[106:107], 0, v[66:67]
	global_load_dwordx4 v[102:105], v[102:103], off
	s_waitcnt vmcnt(0) lgkmcnt(0)
	v_lshl_add_u64 v[168:169], v[90:91], 0, s[22:23]
	v_lshl_add_u64 v[140:141], v[168:169], 0, v[70:71]
	global_load_dwordx4 v[174:177], v[140:141], off
	v_lshl_add_u64 v[140:141], v[106:107], 0, v[70:71]
	global_load_dwordx4 v[146:149], v[140:141], off
	v_lshl_add_u64 v[144:145], v[106:107], 0, v[68:69]
	global_load_dwordx4 v[140:143], v[144:145], off
	ds_write_b128 v92, v[102:105]
	s_waitcnt vmcnt(0) lgkmcnt(0)
	v_lshl_add_u64 v[144:145], v[168:169], 0, v[76:77]
	global_load_dwordx4 v[200:203], v[144:145], off
	v_lshl_add_u64 v[144:145], v[168:169], 0, v[74:75]
	global_load_dwordx4 v[196:199], v[144:145], off
	v_lshl_add_u64 v[144:145], v[168:169], 0, v[72:73]
	global_load_dwordx4 v[178:181], v[144:145], off
	v_lshl_add_u64 v[144:145], v[106:107], 0, v[74:75]
	global_load_dwordx4 v[156:159], v[144:145], off
	v_lshl_add_u64 v[102:103], v[106:107], 0, v[72:73]
	global_load_dwordx4 v[102:105], v[102:103], off
	ds_write_b128 v92, v[140:143] offset:1088
	s_waitcnt vmcnt(5) lgkmcnt(0)
	v_lshl_add_u64 v[140:141], v[168:169], 0, v[78:79]
	global_load_dwordx4 v[204:207], v[140:141], off
	v_lshl_add_u64 v[140:141], v[106:107], 0, v[78:79]
	global_load_dwordx4 v[160:163], v[140:141], off
	v_lshl_add_u64 v[144:145], v[106:107], 0, v[76:77]
	global_load_dwordx4 v[140:143], v[144:145], off
	ds_write_b128 v92, v[146:149] offset:2176
	s_waitcnt vmcnt(3) lgkmcnt(0)
	v_lshl_add_u64 v[144:145], v[168:169], 0, v[66:67]
	global_load_dwordx4 v[164:167], v[144:145], off
	v_lshl_add_u64 v[148:149], v[106:107], 0, v[80:81]
	global_load_dwordx4 v[144:147], v[148:149], off
	ds_write_b128 v92, v[102:105] offset:3264
	s_waitcnt vmcnt(6) lgkmcnt(0)
	v_lshl_add_u64 v[148:149], v[168:169], 0, v[68:69]
	global_load_dwordx4 v[170:173], v[148:149], off
	ds_write_b128 v92, v[156:159] offset:4352
	s_waitcnt vmcnt(3) lgkmcnt(0)
	ds_write_b128 v92, v[140:143] offset:5440
	s_waitcnt vmcnt(4) lgkmcnt(0)
	ds_write_b128 v92, v[160:163] offset:6528
	s_waitcnt vmcnt(1) lgkmcnt(0)
	ds_write_b128 v92, v[144:147] offset:7616
	s_waitcnt lgkmcnt(0)
	ds_read_u16 v102, v1
	s_waitcnt lgkmcnt(0)
	v_lshlrev_b32_e32 v102, 16, v102
	v_add_f32_e32 v138, v2, v102
	ds_read_u16 v2, v1 offset:272
	s_waitcnt lgkmcnt(0)
	v_lshlrev_b32_e32 v2, 16, v2
	v_add_f32_e32 v137, v3, v2
	ds_read_u16 v2, v1 offset:544
	s_waitcnt lgkmcnt(0)
	v_lshlrev_b32_e32 v2, 16, v2
	v_add_f32_e32 v136, v4, v2
	ds_read_u16 v2, v1 offset:816
	s_waitcnt lgkmcnt(0)
	v_lshlrev_b32_e32 v2, 16, v2
	v_add_f32_e32 v135, v5, v2
	ds_read_u16 v2, v1 offset:2176
	s_waitcnt lgkmcnt(0)
	v_lshlrev_b32_e32 v2, 16, v2
	v_add_f32_e32 v134, v6, v2
	ds_read_u16 v2, v1 offset:2448
	s_waitcnt lgkmcnt(0)
	v_lshlrev_b32_e32 v2, 16, v2
	v_add_f32_e32 v133, v7, v2
	ds_read_u16 v2, v1 offset:2720
	s_waitcnt lgkmcnt(0)
	v_lshlrev_b32_e32 v2, 16, v2
	v_add_f32_e32 v132, v8, v2
	ds_read_u16 v2, v1 offset:2992
	s_waitcnt lgkmcnt(0)
	v_lshlrev_b32_e32 v2, 16, v2
	v_add_f32_e32 v131, v9, v2
	ds_read_u16 v2, v1 offset:4352
	s_waitcnt lgkmcnt(0)
	v_lshlrev_b32_e32 v2, 16, v2
	v_add_f32_e32 v130, v10, v2
	ds_read_u16 v2, v1 offset:4624
	s_waitcnt lgkmcnt(0)
	v_lshlrev_b32_e32 v2, 16, v2
	v_add_f32_e32 v129, v11, v2
	ds_read_u16 v2, v1 offset:4896
	s_waitcnt lgkmcnt(0)
	v_lshlrev_b32_e32 v2, 16, v2
	v_add_f32_e32 v128, v12, v2
	ds_read_u16 v2, v1 offset:5168
	s_waitcnt lgkmcnt(0)
	v_lshlrev_b32_e32 v2, 16, v2
	v_add_f32_e32 v127, v13, v2
	ds_read_u16 v2, v1 offset:6528
	s_waitcnt lgkmcnt(0)
	v_lshlrev_b32_e32 v2, 16, v2
	v_add_f32_e32 v126, v14, v2
	ds_read_u16 v2, v1 offset:6800
	s_waitcnt lgkmcnt(0)
	v_lshlrev_b32_e32 v2, 16, v2
	v_add_f32_e32 v125, v15, v2
	ds_read_u16 v2, v1 offset:7072
	s_waitcnt lgkmcnt(0)
	v_lshlrev_b32_e32 v2, 16, v2
	v_add_f32_e32 v124, v16, v2
	ds_read_u16 v2, v1 offset:7344
	s_waitcnt lgkmcnt(0)
	v_lshlrev_b32_e32 v2, 16, v2
	v_add_f32_e32 v123, v17, v2
	ds_read_u16 v2, v1 offset:64
	s_waitcnt lgkmcnt(0)
	v_lshlrev_b32_e32 v2, 16, v2
	v_add_f32_e32 v122, v18, v2
	ds_read_u16 v2, v1 offset:336
	s_waitcnt lgkmcnt(0)
	v_lshlrev_b32_e32 v2, 16, v2
	v_add_f32_e32 v121, v19, v2
	ds_read_u16 v2, v1 offset:608
	s_waitcnt lgkmcnt(0)
	v_lshlrev_b32_e32 v2, 16, v2
	v_add_f32_e32 v120, v20, v2
	ds_read_u16 v2, v1 offset:880
	s_waitcnt lgkmcnt(0)
	v_lshlrev_b32_e32 v2, 16, v2
	v_add_f32_e32 v119, v21, v2
	ds_read_u16 v2, v1 offset:2240
	s_waitcnt lgkmcnt(0)
	v_lshlrev_b32_e32 v2, 16, v2
	v_add_f32_e32 v118, v22, v2
	ds_read_u16 v2, v1 offset:2512
	s_waitcnt lgkmcnt(0)
	v_lshlrev_b32_e32 v2, 16, v2
	v_add_f32_e32 v117, v23, v2
	ds_read_u16 v2, v1 offset:2784
	s_waitcnt lgkmcnt(0)
	v_lshlrev_b32_e32 v2, 16, v2
	v_add_f32_e32 v116, v24, v2
	ds_read_u16 v2, v1 offset:3056
	s_waitcnt lgkmcnt(0)
	v_lshlrev_b32_e32 v2, 16, v2
	v_add_f32_e32 v115, v25, v2
	ds_read_u16 v2, v1 offset:4416
	s_waitcnt lgkmcnt(0)
	v_lshlrev_b32_e32 v2, 16, v2
	v_add_f32_e32 v114, v26, v2
	ds_read_u16 v2, v1 offset:4688
	s_waitcnt lgkmcnt(0)
; #define LAS __attribute__((address_space(3)))
; DI float bf2f(bf16 b) { return __uint_as_float(((unsigned)b) << 16); }
; DI void gla_stage3(const Ctx& c0, int layer, int unit, int cb, LAS unsigned char* lds) {
;     ...
;     for (int vb = 0; vb < 4; ++vb) {
; #pragma unroll
;         for (int rg = 0; rg < 16; ++rg) o[vb][rg] += bf2f(*(const LAS bf16*)(Re + ((rg & 3) + 8 * (rg >> 2)) * G3_PITCH + 64 * vb));
;         asm volatile("" ::: "memory");
;     }
	v_lshlrev_b32_e32 v2, 16, v2
	v_add_f32_e32 v113, v27, v2
	ds_read_u16 v2, v1 offset:4960
	s_waitcnt lgkmcnt(0)
	v_lshlrev_b32_e32 v2, 16, v2
	v_add_f32_e32 v112, v28, v2
	ds_read_u16 v2, v1 offset:5232
	s_waitcnt lgkmcnt(0)
	v_lshlrev_b32_e32 v2, 16, v2
	v_add_f32_e32 v111, v29, v2
	ds_read_u16 v2, v1 offset:6592
	s_waitcnt lgkmcnt(0)
	v_lshlrev_b32_e32 v2, 16, v2
	v_add_f32_e32 v110, v30, v2
	ds_read_u16 v2, v1 offset:6864
	s_waitcnt lgkmcnt(0)
	v_lshlrev_b32_e32 v2, 16, v2
	v_add_f32_e32 v109, v31, v2
	ds_read_u16 v2, v1 offset:7136
	s_waitcnt lgkmcnt(0)
	v_lshlrev_b32_e32 v2, 16, v2
	v_add_f32_e32 v108, v32, v2
	ds_read_u16 v2, v1 offset:7408
	s_waitcnt lgkmcnt(0)
	v_lshlrev_b32_e32 v2, 16, v2
	v_add_f32_e32 v107, v33, v2
	ds_read_u16 v2, v1 offset:128
	s_waitcnt lgkmcnt(0)
	v_lshlrev_b32_e32 v2, 16, v2
	v_add_f32_e32 v106, v34, v2
	ds_read_u16 v2, v1 offset:400
	s_waitcnt lgkmcnt(0)
	v_lshlrev_b32_e32 v2, 16, v2
	v_add_f32_e32 v105, v35, v2
	ds_read_u16 v2, v1 offset:672
	s_waitcnt lgkmcnt(0)
	v_lshlrev_b32_e32 v2, 16, v2
	v_add_f32_e32 v104, v36, v2
	ds_read_u16 v2, v1 offset:944
	s_waitcnt lgkmcnt(0)
	v_lshlrev_b32_e32 v2, 16, v2
	v_add_f32_e32 v103, v37, v2
	ds_read_u16 v2, v1 offset:2304
	s_waitcnt lgkmcnt(0)
	v_lshlrev_b32_e32 v2, 16, v2
	v_add_f32_e32 v102, v38, v2
	ds_read_u16 v2, v1 offset:2576
	s_waitcnt lgkmcnt(0)
	v_lshlrev_b32_e32 v2, 16, v2
	v_add_f32_e32 v39, v39, v2
	ds_read_u16 v2, v1 offset:2848
	s_waitcnt lgkmcnt(0)
	v_lshlrev_b32_e32 v2, 16, v2
	v_add_f32_e32 v38, v40, v2
	ds_read_u16 v2, v1 offset:3120
	s_waitcnt lgkmcnt(0)
	v_lshlrev_b32_e32 v2, 16, v2
	v_add_f32_e32 v37, v41, v2
	ds_read_u16 v2, v1 offset:4480
	s_waitcnt lgkmcnt(0)
	v_lshlrev_b32_e32 v2, 16, v2
	v_add_f32_e32 v36, v42, v2
	ds_read_u16 v2, v1 offset:4752
	s_waitcnt lgkmcnt(0)
	v_lshlrev_b32_e32 v2, 16, v2
	v_add_f32_e32 v34, v43, v2
	ds_read_u16 v2, v1 offset:5024
	s_waitcnt lgkmcnt(0)
	v_lshlrev_b32_e32 v2, 16, v2
	v_add_f32_e32 v33, v44, v2
	ds_read_u16 v2, v1 offset:5296
	s_waitcnt lgkmcnt(0)
	v_lshlrev_b32_e32 v2, 16, v2
	v_add_f32_e32 v32, v45, v2
	ds_read_u16 v2, v1 offset:6656
	s_waitcnt lgkmcnt(0)
	v_lshlrev_b32_e32 v2, 16, v2
	v_add_f32_e32 v30, v46, v2
	ds_read_u16 v2, v1 offset:6928
	s_waitcnt lgkmcnt(0)
	v_lshlrev_b32_e32 v2, 16, v2
	v_add_f32_e32 v29, v47, v2
	ds_read_u16 v2, v1 offset:7200
	s_waitcnt lgkmcnt(0)
	v_lshlrev_b32_e32 v2, 16, v2
	v_add_f32_e32 v28, v48, v2
	ds_read_u16 v2, v1 offset:7472
	s_waitcnt lgkmcnt(0)
	v_lshlrev_b32_e32 v2, 16, v2
	v_add_f32_e32 v26, v49, v2
	ds_read_u16 v2, v1 offset:192
	s_waitcnt lgkmcnt(0)
	v_lshlrev_b32_e32 v2, 16, v2
	v_add_f32_e32 v19, v50, v2
	ds_read_u16 v2, v1 offset:464
	s_waitcnt lgkmcnt(0)
	v_lshlrev_b32_e32 v2, 16, v2
	v_add_f32_e32 v18, v51, v2
	ds_read_u16 v2, v1 offset:736
	s_waitcnt lgkmcnt(0)
	v_lshlrev_b32_e32 v2, 16, v2
	v_add_f32_e32 v17, v52, v2
	ds_read_u16 v2, v1 offset:1008
	s_waitcnt lgkmcnt(0)
	v_lshlrev_b32_e32 v2, 16, v2
	v_add_f32_e32 v16, v53, v2
	ds_read_u16 v2, v1 offset:2368
	s_waitcnt lgkmcnt(0)
	v_lshlrev_b32_e32 v2, 16, v2
	v_add_f32_e32 v15, v54, v2
	ds_read_u16 v2, v1 offset:2640
	s_waitcnt lgkmcnt(0)
	v_lshlrev_b32_e32 v2, 16, v2
	v_add_f32_e32 v14, v55, v2
	ds_read_u16 v2, v1 offset:2912
	s_waitcnt lgkmcnt(0)
	v_lshlrev_b32_e32 v2, 16, v2
	v_add_f32_e32 v13, v56, v2
	ds_read_u16 v2, v1 offset:3184
	s_waitcnt lgkmcnt(0)
	v_lshlrev_b32_e32 v2, 16, v2
	v_add_f32_e32 v12, v57, v2
	ds_read_u16 v2, v1 offset:4544
	s_waitcnt lgkmcnt(0)
	v_lshlrev_b32_e32 v2, 16, v2
	v_add_f32_e32 v11, v58, v2
	ds_read_u16 v2, v1 offset:4816
	s_waitcnt lgkmcnt(0)
	v_lshlrev_b32_e32 v2, 16, v2
	v_add_f32_e32 v10, v59, v2
	ds_read_u16 v2, v1 offset:5088
	s_waitcnt lgkmcnt(0)
	v_lshlrev_b32_e32 v2, 16, v2
	v_add_f32_e32 v9, v60, v2
	ds_read_u16 v2, v1 offset:5360
	s_waitcnt lgkmcnt(0)
	v_lshlrev_b32_e32 v2, 16, v2
	v_add_f32_e32 v8, v61, v2
	ds_read_u16 v2, v1 offset:6720
	s_waitcnt lgkmcnt(0)
	v_lshlrev_b32_e32 v2, 16, v2
	v_add_f32_e32 v7, v62, v2
	ds_read_u16 v2, v1 offset:6992
	s_waitcnt lgkmcnt(0)
	v_lshlrev_b32_e32 v2, 16, v2
	v_add_f32_e32 v6, v63, v2
	ds_read_u16 v2, v1 offset:7264
	s_waitcnt lgkmcnt(0)
	v_lshlrev_b32_e32 v2, 16, v2
	v_add_f32_e32 v5, v64, v2
	ds_read_u16 v2, v1 offset:7536
	s_waitcnt lgkmcnt(0)
	s_waitcnt lgkmcnt(0)
; #define LAS __attribute__((address_space(3)))
; DI float bf2f(bf16 b) { return __uint_as_float(((unsigned)b) << 16); }
; DI void gla_stage3(const Ctx& c0, int layer, int unit, int cb, LAS unsigned char* lds) {
;     ...
;         for (int rg = 0; rg < 16; ++rg) o[vb][rg] += bf2f(*(const LAS bf16*)(Re + ((rg & 3) + 8 * (rg >> 2)) * G3_PITCH + 64 * vb));
;         asm volatile("" ::: "memory");
;     }
;     float rs[16];
; #pragma unroll
;     for (int rg = 0; rg < 16; ++rg) { float ss = o[0][rg] * o[0][rg] + o[1][rg] * o[1][rg] + o[2][rg] * o[2][rg] + o[3][rg] * o[3][rg];
;         ss += __shfl_xor(ss, 1); ss += __shfl_xor(ss, 2); ss += __shfl_xor(ss, 4); ss += __shfl_xor(ss, 8); ss += __shfl_xor(ss, 16);
;         rs[rg] = 1.f / sqrtf(ss * (1.f / 128.f) + EPS); }
	v_lshlrev_b32_e32 v2, 16, v2
	v_add_f32_e32 v4, v65, v2
	v_cndmask_b32_e32 v2, v93, v94, vcc
	v_cmp_lt_i32_e32 vcc, v96, v95
	v_lshlrev_b32_e32 v2, 2, v2
	s_nop 0
	v_cndmask_b32_e32 v3, v93, v96, vcc
	v_cmp_lt_i32_e32 vcc, v97, v95
	v_lshlrev_b32_e32 v3, 2, v3
	s_nop 0
	v_cndmask_b32_e32 v20, v93, v97, vcc
	v_cmp_lt_i32_e32 vcc, v98, v95
	v_lshlrev_b32_e32 v20, 2, v20
	s_nop 0
	v_cndmask_b32_e32 v21, v93, v98, vcc
	v_cmp_lt_i32_e32 vcc, v99, v95
	v_lshlrev_b32_e32 v47, 2, v21
	s_nop 0
	v_cndmask_b32_e32 v21, v93, v99, vcc
	v_lshlrev_b32_e32 v48, 2, v21
	v_mul_f32_e32 v21, v122, v122
	v_fmac_f32_e32 v21, v138, v138
	v_fmac_f32_e32 v21, v106, v106
	v_fmac_f32_e32 v21, v19, v19
	s_nop 1
	v_add_f32_dpp v21, v21, v21 quad_perm:[1,0,3,2] row_mask:0xf bank_mask:0xf
	s_nop 1
	v_add_f32_dpp v21, v21, v21 quad_perm:[2,3,0,1] row_mask:0xf bank_mask:0xf
	s_nop 1
	v_add_f32_dpp v21, v21, v21 row_half_mirror row_mask:0xf bank_mask:0xf
	s_nop 1
	v_add_f32_dpp v21, v21, v21 row_mirror row_mask:0xf bank_mask:0xf
	v_mov_b32_e32 v22, v21
	v_mov_b32_e32 v23, v21
	s_nop 1
	v_permlane16_swap_b32_e32 v22, v23
	v_add_f32_e32 v21, v22, v23
	v_fmamk_f32 v21, v21, 0x3c000000, v100
	v_cmp_gt_f32_e32 vcc, s33, v21
	v_mul_f32_e32 v22, 0x4f800000, v21
	s_nop 0
	v_cndmask_b32_e32 v21, v21, v22, vcc
	v_sqrt_f32_e32 v22, v21
	s_nop 0
	v_add_u32_e32 v23, -1, v22
	v_fma_f32 v24, -v23, v22, v21
	v_cmp_ge_f32_e64 s[8:9], 0, v24
	v_add_u32_e32 v24, 1, v22
	s_nop 0
	v_cndmask_b32_e64 v23, v22, v23, s[8:9]
	v_fma_f32 v22, -v24, v22, v21
	v_cmp_lt_f32_e64 s[8:9], 0, v22
	s_nop 1
	v_cndmask_b32_e64 v22, v23, v24, s[8:9]
	v_mul_f32_e32 v23, 0x37800000, v22
	v_cndmask_b32_e32 v22, v22, v23, vcc
	v_cmp_class_f32_e32 vcc, v21, v101
	s_nop 1
	v_cndmask_b32_e32 v21, v22, v21, vcc
	s_nop 0
	v_div_scale_f32 v24, vcc, 1.0, v21, 1.0
	v_rcp_f32_e32 v46, v21
	v_mul_f32_e32 v21, v121, v121
	v_fmac_f32_e32 v21, v137, v137
	v_fmac_f32_e32 v21, v105, v105
	v_fmac_f32_e32 v21, v18, v18
	s_nop 1
	v_add_f32_dpp v21, v21, v21 quad_perm:[1,0,3,2] row_mask:0xf bank_mask:0xf
	v_mul_f32_e32 v19, v19, v46
	s_nop 1
	v_add_f32_dpp v21, v21, v21 quad_perm:[2,3,0,1] row_mask:0xf bank_mask:0xf
	s_nop 1
	v_add_f32_dpp v21, v21, v21 row_half_mirror row_mask:0xf bank_mask:0xf
	s_nop 1
	v_add_f32_dpp v21, v21, v21 row_mirror row_mask:0xf bank_mask:0xf
	v_mov_b32_e32 v22, v21
	v_mov_b32_e32 v23, v21
	s_nop 1
	v_permlane16_swap_b32_e32 v22, v23
	v_add_f32_e32 v21, v22, v23
	v_fmamk_f32 v21, v21, 0x3c000000, v100
	v_cmp_gt_f32_e32 vcc, s33, v21
	v_mul_f32_e32 v22, 0x4f800000, v21
	s_nop 0
	v_cndmask_b32_e32 v21, v21, v22, vcc
	v_sqrt_f32_e32 v22, v21
	s_nop 0
	v_add_u32_e32 v23, -1, v22
	v_fma_f32 v24, -v23, v22, v21
	v_cmp_ge_f32_e64 s[8:9], 0, v24
	v_add_u32_e32 v24, 1, v22
	s_nop 0
	v_cndmask_b32_e64 v23, v22, v23, s[8:9]
	v_fma_f32 v22, -v24, v22, v21
	v_cmp_lt_f32_e64 s[8:9], 0, v22
	s_nop 1
	v_cndmask_b32_e64 v22, v23, v24, s[8:9]
	v_mul_f32_e32 v23, 0x37800000, v22
	v_cndmask_b32_e32 v22, v22, v23, vcc
	v_cmp_class_f32_e32 vcc, v21, v101
	s_nop 1
	v_cndmask_b32_e32 v21, v22, v21, vcc
	s_nop 0
	v_div_scale_f32 v24, vcc, 1.0, v21, 1.0
	v_rcp_f32_e32 v45, v21
	v_mul_f32_e32 v21, v120, v120
	v_fmac_f32_e32 v21, v136, v136
	v_fmac_f32_e32 v21, v104, v104
	v_fmac_f32_e32 v21, v17, v17
	s_nop 1
	v_add_f32_dpp v21, v21, v21 quad_perm:[1,0,3,2] row_mask:0xf bank_mask:0xf
	v_mul_f32_e32 v18, v18, v45
	s_nop 1
	v_add_f32_dpp v21, v21, v21 quad_perm:[2,3,0,1] row_mask:0xf bank_mask:0xf
	s_nop 1
	v_add_f32_dpp v21, v21, v21 row_half_mirror row_mask:0xf bank_mask:0xf
	s_nop 1
	v_add_f32_dpp v21, v21, v21 row_mirror row_mask:0xf bank_mask:0xf
	v_mov_b32_e32 v22, v21
	v_mov_b32_e32 v23, v21
	s_nop 1
	v_permlane16_swap_b32_e32 v22, v23
	v_add_f32_e32 v21, v22, v23
	v_fmamk_f32 v21, v21, 0x3c000000, v100
	v_cmp_gt_f32_e32 vcc, s33, v21
	v_mul_f32_e32 v22, 0x4f800000, v21
	s_nop 0
	v_cndmask_b32_e32 v21, v21, v22, vcc
	v_sqrt_f32_e32 v22, v21
	s_nop 0
	v_add_u32_e32 v23, -1, v22
	v_fma_f32 v24, -v23, v22, v21
	v_cmp_ge_f32_e64 s[8:9], 0, v24
	v_add_u32_e32 v24, 1, v22
	s_nop 0
	v_cndmask_b32_e64 v23, v22, v23, s[8:9]
	v_fma_f32 v22, -v24, v22, v21
	v_cmp_lt_f32_e64 s[8:9], 0, v22
	s_nop 1
	v_cndmask_b32_e64 v22, v23, v24, s[8:9]
	v_mul_f32_e32 v23, 0x37800000, v22
	v_cndmask_b32_e32 v22, v22, v23, vcc
	v_cmp_class_f32_e32 vcc, v21, v101
	s_nop 1
	v_cndmask_b32_e32 v21, v22, v21, vcc
	s_nop 0
	v_div_scale_f32 v24, vcc, 1.0, v21, 1.0
	v_rcp_f32_e32 v44, v21
	v_mul_f32_e32 v21, v119, v119
	v_fmac_f32_e32 v21, v135, v135
	v_fmac_f32_e32 v21, v103, v103
	v_fmac_f32_e32 v21, v16, v16
	s_nop 1
	v_add_f32_dpp v21, v21, v21 quad_perm:[1,0,3,2] row_mask:0xf bank_mask:0xf
	v_mul_f32_e32 v17, v17, v44
	s_nop 1
	v_add_f32_dpp v21, v21, v21 quad_perm:[2,3,0,1] row_mask:0xf bank_mask:0xf
	s_nop 1
	v_add_f32_dpp v21, v21, v21 row_half_mirror row_mask:0xf bank_mask:0xf
	s_nop 1
	v_add_f32_dpp v21, v21, v21 row_mirror row_mask:0xf bank_mask:0xf
	v_mov_b32_e32 v22, v21
	v_mov_b32_e32 v23, v21
	s_nop 1
	v_permlane16_swap_b32_e32 v22, v23
	v_add_f32_e32 v21, v22, v23
	v_fmamk_f32 v21, v21, 0x3c000000, v100
	v_cmp_gt_f32_e32 vcc, s33, v21
	v_mul_f32_e32 v22, 0x4f800000, v21
	s_nop 0
	v_cndmask_b32_e32 v21, v21, v22, vcc
	v_sqrt_f32_e32 v22, v21
	s_nop 0
	v_add_u32_e32 v23, -1, v22
	v_fma_f32 v24, -v23, v22, v21
	v_cmp_ge_f32_e64 s[8:9], 0, v24
	v_add_u32_e32 v24, 1, v22
	s_nop 0
	v_cndmask_b32_e64 v23, v22, v23, s[8:9]
	v_fma_f32 v22, -v24, v22, v21
	v_cmp_lt_f32_e64 s[8:9], 0, v22
	s_nop 1
	v_cndmask_b32_e64 v22, v23, v24, s[8:9]
	v_mul_f32_e32 v23, 0x37800000, v22
	v_cndmask_b32_e32 v22, v22, v23, vcc
	v_cmp_class_f32_e32 vcc, v21, v101
	s_nop 1
; DI void gla_stage3(const Ctx& c0, int layer, int unit, int cb, LAS unsigned char* lds) {
;     ...
;     for (int rg = 0; rg < 16; ++rg) { float ss = o[0][rg] * o[0][rg] + o[1][rg] * o[1][rg] + o[2][rg] * o[2][rg] + o[3][rg] * o[3][rg];
;         ss += __shfl_xor(ss, 1); ss += __shfl_xor(ss, 2); ss += __shfl_xor(ss, 4); ss += __shfl_xor(ss, 8); ss += __shfl_xor(ss, 16);
;         rs[rg] = 1.f / sqrtf(ss * (1.f / 128.f) + EPS); }
	v_cndmask_b32_e32 v21, v22, v21, vcc
	s_nop 0
	v_div_scale_f32 v24, vcc, 1.0, v21, 1.0
	v_rcp_f32_e32 v43, v21
	v_mul_f32_e32 v21, v118, v118
	v_fmac_f32_e32 v21, v134, v134
	v_fmac_f32_e32 v21, v102, v102
	v_fmac_f32_e32 v21, v15, v15
	s_nop 1
	v_add_f32_dpp v21, v21, v21 quad_perm:[1,0,3,2] row_mask:0xf bank_mask:0xf
	v_mul_f32_e32 v16, v16, v43
	s_nop 1
	v_add_f32_dpp v21, v21, v21 quad_perm:[2,3,0,1] row_mask:0xf bank_mask:0xf
	s_nop 1
	v_add_f32_dpp v21, v21, v21 row_half_mirror row_mask:0xf bank_mask:0xf
	s_nop 1
	v_add_f32_dpp v21, v21, v21 row_mirror row_mask:0xf bank_mask:0xf
	v_mov_b32_e32 v22, v21
	v_mov_b32_e32 v23, v21
	s_nop 1
	v_permlane16_swap_b32_e32 v22, v23
	v_add_f32_e32 v21, v22, v23
	v_fmamk_f32 v21, v21, 0x3c000000, v100
	v_cmp_gt_f32_e32 vcc, s33, v21
	v_mul_f32_e32 v22, 0x4f800000, v21
	s_nop 0
	v_cndmask_b32_e32 v21, v21, v22, vcc
	v_sqrt_f32_e32 v22, v21
	s_nop 0
	v_add_u32_e32 v23, -1, v22
	v_fma_f32 v24, -v23, v22, v21
	v_cmp_ge_f32_e64 s[8:9], 0, v24
	v_add_u32_e32 v24, 1, v22
	s_nop 0
	v_cndmask_b32_e64 v23, v22, v23, s[8:9]
	v_fma_f32 v22, -v24, v22, v21
	v_cmp_lt_f32_e64 s[8:9], 0, v22
	s_nop 1
	v_cndmask_b32_e64 v22, v23, v24, s[8:9]
	v_mul_f32_e32 v23, 0x37800000, v22
	v_cndmask_b32_e32 v22, v22, v23, vcc
	v_cmp_class_f32_e32 vcc, v21, v101
	s_nop 1
	v_cndmask_b32_e32 v21, v22, v21, vcc
	s_nop 0
	v_div_scale_f32 v24, vcc, 1.0, v21, 1.0
	v_rcp_f32_e32 v42, v21
	v_mul_f32_e32 v21, v117, v117
	v_fmac_f32_e32 v21, v133, v133
	v_fmac_f32_e32 v21, v39, v39
	v_fmac_f32_e32 v21, v14, v14
	s_nop 1
	v_add_f32_dpp v21, v21, v21 quad_perm:[1,0,3,2] row_mask:0xf bank_mask:0xf
	v_mul_f32_e32 v15, v15, v42
	s_nop 1
	v_add_f32_dpp v21, v21, v21 quad_perm:[2,3,0,1] row_mask:0xf bank_mask:0xf
	s_nop 1
	v_add_f32_dpp v21, v21, v21 row_half_mirror row_mask:0xf bank_mask:0xf
	s_nop 1
	v_add_f32_dpp v21, v21, v21 row_mirror row_mask:0xf bank_mask:0xf
	v_mov_b32_e32 v22, v21
	v_mov_b32_e32 v23, v21
	s_nop 1
	v_permlane16_swap_b32_e32 v22, v23
	v_add_f32_e32 v21, v22, v23
	v_fmamk_f32 v21, v21, 0x3c000000, v100
	v_cmp_gt_f32_e32 vcc, s33, v21
	v_mul_f32_e32 v22, 0x4f800000, v21
	s_nop 0
	v_cndmask_b32_e32 v21, v21, v22, vcc
	v_sqrt_f32_e32 v22, v21
	s_nop 0
	v_add_u32_e32 v23, -1, v22
	v_fma_f32 v24, -v23, v22, v21
	v_cmp_ge_f32_e64 s[8:9], 0, v24
	v_add_u32_e32 v24, 1, v22
	s_nop 0
	v_cndmask_b32_e64 v23, v22, v23, s[8:9]
	v_fma_f32 v22, -v24, v22, v21
	v_cmp_lt_f32_e64 s[8:9], 0, v22
	s_nop 1
	v_cndmask_b32_e64 v22, v23, v24, s[8:9]
	v_mul_f32_e32 v23, 0x37800000, v22
	v_cndmask_b32_e32 v22, v22, v23, vcc
	v_cmp_class_f32_e32 vcc, v21, v101
	s_nop 1
	v_cndmask_b32_e32 v21, v22, v21, vcc
	s_nop 0
	v_div_scale_f32 v24, vcc, 1.0, v21, 1.0
	v_rcp_f32_e32 v41, v21
	v_mul_f32_e32 v21, v116, v116
	v_fmac_f32_e32 v21, v132, v132
	v_fmac_f32_e32 v21, v38, v38
	v_fmac_f32_e32 v21, v13, v13
	s_nop 1
	v_add_f32_dpp v21, v21, v21 quad_perm:[1,0,3,2] row_mask:0xf bank_mask:0xf
	v_mul_f32_e32 v39, v39, v41
	v_mul_f32_e32 v14, v14, v41
	s_nop 1
	v_add_f32_dpp v21, v21, v21 quad_perm:[2,3,0,1] row_mask:0xf bank_mask:0xf
	s_nop 1
	v_add_f32_dpp v21, v21, v21 row_half_mirror row_mask:0xf bank_mask:0xf
	s_nop 1
	v_add_f32_dpp v21, v21, v21 row_mirror row_mask:0xf bank_mask:0xf
	v_mov_b32_e32 v22, v21
	v_mov_b32_e32 v23, v21
	s_nop 1
	v_permlane16_swap_b32_e32 v22, v23
	v_add_f32_e32 v21, v22, v23
	v_fmamk_f32 v21, v21, 0x3c000000, v100
	v_cmp_gt_f32_e32 vcc, s33, v21
	v_mul_f32_e32 v22, 0x4f800000, v21
	s_nop 0
	v_cndmask_b32_e32 v21, v21, v22, vcc
	v_sqrt_f32_e32 v22, v21
	s_nop 0
	v_add_u32_e32 v23, -1, v22
	v_fma_f32 v24, -v23, v22, v21
	v_cmp_ge_f32_e64 s[8:9], 0, v24
	v_add_u32_e32 v24, 1, v22
	s_nop 0
	v_cndmask_b32_e64 v23, v22, v23, s[8:9]
	v_fma_f32 v22, -v24, v22, v21
	v_cmp_lt_f32_e64 s[8:9], 0, v22
	s_nop 1
	v_cndmask_b32_e64 v22, v23, v24, s[8:9]
	v_mul_f32_e32 v23, 0x37800000, v22
	v_cndmask_b32_e32 v22, v22, v23, vcc
	v_cmp_class_f32_e32 vcc, v21, v101
	s_nop 1
	v_cndmask_b32_e32 v21, v22, v21, vcc
	s_nop 0
	v_div_scale_f32 v24, vcc, 1.0, v21, 1.0
	v_rcp_f32_e32 v40, v21
	v_mul_f32_e32 v21, v115, v115
	v_fmac_f32_e32 v21, v131, v131
	v_fmac_f32_e32 v21, v37, v37
	v_fmac_f32_e32 v21, v12, v12
	s_nop 1
	v_add_f32_dpp v21, v21, v21 quad_perm:[1,0,3,2] row_mask:0xf bank_mask:0xf
	v_mul_f32_e32 v38, v38, v40
	v_mul_f32_e32 v13, v13, v40
	s_nop 1
	v_add_f32_dpp v21, v21, v21 quad_perm:[2,3,0,1] row_mask:0xf bank_mask:0xf
	s_nop 1
	v_add_f32_dpp v21, v21, v21 row_half_mirror row_mask:0xf bank_mask:0xf
	s_nop 1
	v_add_f32_dpp v21, v21, v21 row_mirror row_mask:0xf bank_mask:0xf
	v_mov_b32_e32 v22, v21
	v_mov_b32_e32 v23, v21
	s_nop 1
	v_permlane16_swap_b32_e32 v22, v23
	v_add_f32_e32 v21, v22, v23
	v_fmamk_f32 v21, v21, 0x3c000000, v100
	v_cmp_gt_f32_e32 vcc, s33, v21
	v_mul_f32_e32 v22, 0x4f800000, v21
	s_nop 0
	v_cndmask_b32_e32 v21, v21, v22, vcc
	v_sqrt_f32_e32 v22, v21
	s_nop 0
	v_add_u32_e32 v23, -1, v22
	v_fma_f32 v24, -v23, v22, v21
	v_cmp_ge_f32_e64 s[8:9], 0, v24
	v_add_u32_e32 v24, 1, v22
	s_nop 0
	v_cndmask_b32_e64 v23, v22, v23, s[8:9]
	v_fma_f32 v22, -v24, v22, v21
	v_cmp_lt_f32_e64 s[8:9], 0, v22
	s_nop 1
	v_cndmask_b32_e64 v22, v23, v24, s[8:9]
	v_mul_f32_e32 v23, 0x37800000, v22
	v_cndmask_b32_e32 v22, v22, v23, vcc
	v_cmp_class_f32_e32 vcc, v21, v101
	s_nop 1
	v_cndmask_b32_e32 v21, v22, v21, vcc
	s_nop 0
	v_div_scale_f32 v24, vcc, 1.0, v21, 1.0
	v_rcp_f32_e32 v35, v21
	v_mul_f32_e32 v21, v114, v114
	v_fmac_f32_e32 v21, v130, v130
	v_fmac_f32_e32 v21, v36, v36
	v_fmac_f32_e32 v21, v11, v11
	s_nop 1
	v_add_f32_dpp v21, v21, v21 quad_perm:[1,0,3,2] row_mask:0xf bank_mask:0xf
	v_mul_f32_e32 v37, v37, v35
	v_mul_f32_e32 v12, v12, v35
; DI void gla_stage3(const Ctx& c0, int layer, int unit, int cb, LAS unsigned char* lds) {
;     ...
;     for (int rg = 0; rg < 16; ++rg) { float ss = o[0][rg] * o[0][rg] + o[1][rg] * o[1][rg] + o[2][rg] * o[2][rg] + o[3][rg] * o[3][rg];
;         ss += __shfl_xor(ss, 1); ss += __shfl_xor(ss, 2); ss += __shfl_xor(ss, 4); ss += __shfl_xor(ss, 8); ss += __shfl_xor(ss, 16);
;         rs[rg] = 1.f / sqrtf(ss * (1.f / 128.f) + EPS); }
	s_nop 1
	v_add_f32_dpp v21, v21, v21 quad_perm:[2,3,0,1] row_mask:0xf bank_mask:0xf
	s_nop 1
	v_add_f32_dpp v21, v21, v21 row_half_mirror row_mask:0xf bank_mask:0xf
	s_nop 1
	v_add_f32_dpp v21, v21, v21 row_mirror row_mask:0xf bank_mask:0xf
	v_mov_b32_e32 v22, v21
	v_mov_b32_e32 v23, v21
	s_nop 1
	v_permlane16_swap_b32_e32 v22, v23
	v_add_f32_e32 v21, v22, v23
	v_fmamk_f32 v21, v21, 0x3c000000, v100
	v_cmp_gt_f32_e32 vcc, s33, v21
	v_mul_f32_e32 v22, 0x4f800000, v21
	s_nop 0
	v_cndmask_b32_e32 v21, v21, v22, vcc
	v_sqrt_f32_e32 v22, v21
	s_nop 0
	v_add_u32_e32 v23, -1, v22
	v_fma_f32 v24, -v23, v22, v21
	v_cmp_ge_f32_e64 s[8:9], 0, v24
	v_add_u32_e32 v24, 1, v22
	s_nop 0
	v_cndmask_b32_e64 v23, v22, v23, s[8:9]
	v_fma_f32 v22, -v24, v22, v21
	v_cmp_lt_f32_e64 s[8:9], 0, v22
	s_nop 1
	v_cndmask_b32_e64 v22, v23, v24, s[8:9]
	v_mul_f32_e32 v23, 0x37800000, v22
	v_cndmask_b32_e32 v22, v22, v23, vcc
	v_cmp_class_f32_e32 vcc, v21, v101
	s_nop 1
	v_cndmask_b32_e32 v21, v22, v21, vcc
	s_nop 0
	v_div_scale_f32 v24, vcc, 1.0, v21, 1.0
	v_rcp_f32_e32 v31, v21
	v_mul_f32_e32 v21, v113, v113
	v_fmac_f32_e32 v21, v129, v129
	v_fmac_f32_e32 v21, v34, v34
	v_fmac_f32_e32 v21, v10, v10
	s_nop 1
	v_add_f32_dpp v21, v21, v21 quad_perm:[1,0,3,2] row_mask:0xf bank_mask:0xf
	v_mul_f32_e32 v36, v36, v31
	v_mul_f32_e32 v11, v11, v31
	s_nop 1
	v_add_f32_dpp v21, v21, v21 quad_perm:[2,3,0,1] row_mask:0xf bank_mask:0xf
	s_nop 1
	v_add_f32_dpp v21, v21, v21 row_half_mirror row_mask:0xf bank_mask:0xf
	s_nop 1
	v_add_f32_dpp v21, v21, v21 row_mirror row_mask:0xf bank_mask:0xf
	v_mov_b32_e32 v22, v21
	v_mov_b32_e32 v23, v21
	s_nop 1
	v_permlane16_swap_b32_e32 v22, v23
	v_add_f32_e32 v21, v22, v23
	v_fmamk_f32 v21, v21, 0x3c000000, v100
	v_cmp_gt_f32_e32 vcc, s33, v21
	v_mul_f32_e32 v22, 0x4f800000, v21
	s_nop 0
	v_cndmask_b32_e32 v21, v21, v22, vcc
	v_sqrt_f32_e32 v22, v21
	s_nop 0
	v_add_u32_e32 v23, -1, v22
	v_fma_f32 v24, -v23, v22, v21
	v_cmp_ge_f32_e64 s[8:9], 0, v24
	v_add_u32_e32 v24, 1, v22
	s_nop 0
	v_cndmask_b32_e64 v23, v22, v23, s[8:9]
	v_fma_f32 v22, -v24, v22, v21
	v_cmp_lt_f32_e64 s[8:9], 0, v22
	s_nop 1
	v_cndmask_b32_e64 v22, v23, v24, s[8:9]
	v_mul_f32_e32 v23, 0x37800000, v22
	v_cndmask_b32_e32 v22, v22, v23, vcc
	v_cmp_class_f32_e32 vcc, v21, v101
	s_nop 1
	v_cndmask_b32_e32 v21, v22, v21, vcc
	s_nop 0
	v_div_scale_f32 v24, vcc, 1.0, v21, 1.0
	v_rcp_f32_e32 v27, v21
	v_mul_f32_e32 v21, v112, v112
	v_fmac_f32_e32 v21, v128, v128
	v_fmac_f32_e32 v21, v33, v33
	v_fmac_f32_e32 v21, v9, v9
	s_nop 1
	v_add_f32_dpp v21, v21, v21 quad_perm:[1,0,3,2] row_mask:0xf bank_mask:0xf
	v_mul_f32_e32 v34, v34, v27
	v_mul_f32_e32 v10, v10, v27
	s_nop 1
	v_add_f32_dpp v21, v21, v21 quad_perm:[2,3,0,1] row_mask:0xf bank_mask:0xf
	s_nop 1
	v_add_f32_dpp v21, v21, v21 row_half_mirror row_mask:0xf bank_mask:0xf
	s_nop 1
	v_add_f32_dpp v21, v21, v21 row_mirror row_mask:0xf bank_mask:0xf
	v_mov_b32_e32 v22, v21
	v_mov_b32_e32 v23, v21
	s_nop 1
	v_permlane16_swap_b32_e32 v22, v23
	v_add_f32_e32 v21, v22, v23
	v_fmamk_f32 v21, v21, 0x3c000000, v100
	v_cmp_gt_f32_e32 vcc, s33, v21
	v_mul_f32_e32 v22, 0x4f800000, v21
	s_nop 0
	v_cndmask_b32_e32 v21, v21, v22, vcc
	v_sqrt_f32_e32 v22, v21
	s_nop 0
	v_add_u32_e32 v23, -1, v22
	v_fma_f32 v24, -v23, v22, v21
	v_cmp_ge_f32_e64 s[8:9], 0, v24
	v_add_u32_e32 v24, 1, v22
	s_nop 0
	v_cndmask_b32_e64 v23, v22, v23, s[8:9]
	v_fma_f32 v22, -v24, v22, v21
	v_cmp_lt_f32_e64 s[8:9], 0, v22
	s_nop 1
	v_cndmask_b32_e64 v22, v23, v24, s[8:9]
	v_mul_f32_e32 v23, 0x37800000, v22
	v_cndmask_b32_e32 v22, v22, v23, vcc
	v_cmp_class_f32_e32 vcc, v21, v101
	s_nop 1
	v_cndmask_b32_e32 v21, v22, v21, vcc
	s_nop 0
	v_div_scale_f32 v24, vcc, 1.0, v21, 1.0
	v_rcp_f32_e32 v25, v21
	v_mul_f32_e32 v21, v111, v111
	v_fmac_f32_e32 v21, v127, v127
	v_fmac_f32_e32 v21, v32, v32
	v_fmac_f32_e32 v21, v8, v8
	s_nop 1
	v_add_f32_dpp v21, v21, v21 quad_perm:[1,0,3,2] row_mask:0xf bank_mask:0xf
	v_mul_f32_e32 v33, v33, v25
	v_mul_f32_e32 v9, v9, v25
	s_nop 1
	v_add_f32_dpp v21, v21, v21 quad_perm:[2,3,0,1] row_mask:0xf bank_mask:0xf
	s_nop 1
	v_add_f32_dpp v21, v21, v21 row_half_mirror row_mask:0xf bank_mask:0xf
	s_nop 1
	v_add_f32_dpp v21, v21, v21 row_mirror row_mask:0xf bank_mask:0xf
	v_mov_b32_e32 v22, v21
	v_mov_b32_e32 v23, v21
	s_nop 1
	v_permlane16_swap_b32_e32 v22, v23
	v_add_f32_e32 v21, v22, v23
	v_fmamk_f32 v21, v21, 0x3c000000, v100
	v_cmp_gt_f32_e32 vcc, s33, v21
	v_mul_f32_e32 v22, 0x4f800000, v21
	s_nop 0
	v_cndmask_b32_e32 v21, v21, v22, vcc
	v_sqrt_f32_e32 v22, v21
	s_nop 0
	v_add_u32_e32 v23, -1, v22
	v_fma_f32 v24, -v23, v22, v21
	v_cmp_ge_f32_e64 s[8:9], 0, v24
	v_add_u32_e32 v24, 1, v22
	s_nop 0
	v_cndmask_b32_e64 v23, v22, v23, s[8:9]
	v_fma_f32 v22, -v24, v22, v21
	v_cmp_lt_f32_e64 s[8:9], 0, v22
	s_nop 1
	v_cndmask_b32_e64 v22, v23, v24, s[8:9]
	v_mul_f32_e32 v23, 0x37800000, v22
	v_cndmask_b32_e32 v22, v22, v23, vcc
	v_cmp_class_f32_e32 vcc, v21, v101
	s_nop 1
	v_cndmask_b32_e32 v21, v22, v21, vcc
	s_nop 0
	v_div_scale_f32 v24, vcc, 1.0, v21, 1.0
	v_rcp_f32_e32 v24, v21
	v_mul_f32_e32 v21, v110, v110
	v_fmac_f32_e32 v21, v126, v126
	v_fmac_f32_e32 v21, v30, v30
	v_fmac_f32_e32 v21, v7, v7
	s_nop 1
	v_add_f32_dpp v21, v21, v21 quad_perm:[1,0,3,2] row_mask:0xf bank_mask:0xf
	v_mul_f32_e32 v32, v32, v24
	v_mul_f32_e32 v8, v8, v24
	s_nop 1
	v_add_f32_dpp v21, v21, v21 quad_perm:[2,3,0,1] row_mask:0xf bank_mask:0xf
	s_nop 1
	v_add_f32_dpp v21, v21, v21 row_half_mirror row_mask:0xf bank_mask:0xf
	s_nop 1
	v_add_f32_dpp v21, v21, v21 row_mirror row_mask:0xf bank_mask:0xf
	v_mov_b32_e32 v22, v21
	v_mov_b32_e32 v23, v21
	s_nop 1
	v_permlane16_swap_b32_e32 v22, v23
; #define LAS __attribute__((address_space(3)))
; #define LDS_WAIT() asm volatile("s_waitcnt lgkmcnt(0)" ::: "memory")
; DI unsigned cvtpk(float lo, float hi) { f32x2 v = {lo, hi}; bf16x2_t b = __builtin_convertvector(v, bf16x2_t); return __builtin_bit_cast(unsigned, b); }
; DI float bf2f(bf16 b) { return __uint_as_float(((unsigned)b) << 16); }
; DI float siluf_(float x) { return x / (1.f + __expf(-x)); }
; DI void gla_stage3(const Ctx& c0, int layer, int unit, int cb, LAS unsigned char* lds) {
;     ...
;     for (int rg = 0; rg < 16; ++rg) { float ss = o[0][rg] * o[0][rg] + o[1][rg] * o[1][rg] + o[2][rg] * o[2][rg] + o[3][rg] * o[3][rg];
;         ss += __shfl_xor(ss, 1); ss += __shfl_xor(ss, 2); ss += __shfl_xor(ss, 4); ss += __shfl_xor(ss, 8); ss += __shfl_xor(ss, 16);
;         rs[rg] = 1.f / sqrtf(ss * (1.f / 128.f) + EPS); }
;     LDS_WAIT();
;     g3_tile_in((const bf16*)(c.ws + O_GR) + row0 * 512 + h * 128, R, lane);
; #pragma unroll
;     for (int vb = 0; vb < 4; ++vb) { const float g = gn[32 * vb + r];
; #pragma unroll
;         for (int rg = 0; rg < 16; ++rg) { LAS bf16* e = (LAS bf16*)(R + (4 * hi) * G3_PITCH + r * 2 + ((rg & 3) + 8 * (rg >> 2)) * G3_PITCH + 64 * vb);
;             const float z = bf2f(*e);
;             *e = (bf16)(cvtpk(o[vb][rg] * rs[rg] * g * siluf_(z), 0.f) & 0xffffu); }
	v_add_f32_e32 v21, v22, v23
	v_fmamk_f32 v21, v21, 0x3c000000, v100
	v_cmp_gt_f32_e32 vcc, s33, v21
	v_mul_f32_e32 v22, 0x4f800000, v21
	s_nop 0
	v_cndmask_b32_e32 v21, v21, v22, vcc
	v_sqrt_f32_e32 v22, v21
	s_nop 0
	v_add_u32_e32 v23, -1, v22
	v_fma_f32 v49, -v23, v22, v21
	v_cmp_ge_f32_e64 s[8:9], 0, v49
	v_add_u32_e32 v49, 1, v22
	s_nop 0
	v_cndmask_b32_e64 v23, v22, v23, s[8:9]
	v_fma_f32 v22, -v49, v22, v21
	v_cmp_lt_f32_e64 s[8:9], 0, v22
	s_nop 1
	v_cndmask_b32_e64 v22, v23, v49, s[8:9]
	v_mul_f32_e32 v23, 0x37800000, v22
	v_cndmask_b32_e32 v22, v22, v23, vcc
	v_cmp_class_f32_e32 vcc, v21, v101
	s_nop 1
	v_cndmask_b32_e32 v21, v22, v21, vcc
	s_nop 0
	v_div_scale_f32 v49, vcc, 1.0, v21, 1.0
	v_rcp_f32_e32 v23, v21
	v_mul_f32_e32 v21, v109, v109
	v_fmac_f32_e32 v21, v125, v125
	v_fmac_f32_e32 v21, v29, v29
	v_fmac_f32_e32 v21, v6, v6
	s_nop 1
	v_add_f32_dpp v21, v21, v21 quad_perm:[1,0,3,2] row_mask:0xf bank_mask:0xf
	v_mul_f32_e32 v30, v30, v23
	v_mul_f32_e32 v7, v7, v23
	s_nop 1
	v_add_f32_dpp v21, v21, v21 quad_perm:[2,3,0,1] row_mask:0xf bank_mask:0xf
	s_nop 1
	v_add_f32_dpp v21, v21, v21 row_half_mirror row_mask:0xf bank_mask:0xf
	s_nop 1
	v_add_f32_dpp v21, v21, v21 row_mirror row_mask:0xf bank_mask:0xf
	v_mov_b32_e32 v22, v21
	v_mov_b32_e32 v49, v21
	s_nop 1
	v_permlane16_swap_b32_e32 v22, v49
	v_add_f32_e32 v21, v22, v49
	v_fmamk_f32 v21, v21, 0x3c000000, v100
	v_cmp_gt_f32_e32 vcc, s33, v21
	v_mul_f32_e32 v22, 0x4f800000, v21
	s_nop 0
	v_cndmask_b32_e32 v21, v21, v22, vcc
	v_sqrt_f32_e32 v22, v21
	s_nop 0
	v_add_u32_e32 v49, -1, v22
	v_fma_f32 v50, -v49, v22, v21
	v_cmp_ge_f32_e64 s[8:9], 0, v50
	v_add_u32_e32 v50, 1, v22
	s_nop 0
	v_cndmask_b32_e64 v49, v22, v49, s[8:9]
	v_fma_f32 v22, -v50, v22, v21
	v_cmp_lt_f32_e64 s[8:9], 0, v22
	s_nop 1
	v_cndmask_b32_e64 v22, v49, v50, s[8:9]
	v_mul_f32_e32 v49, 0x37800000, v22
	v_cndmask_b32_e32 v22, v22, v49, vcc
	v_cmp_class_f32_e32 vcc, v21, v101
	s_nop 1
	v_cndmask_b32_e32 v21, v22, v21, vcc
	s_nop 0
	v_div_scale_f32 v50, vcc, 1.0, v21, 1.0
	v_rcp_f32_e32 v22, v21
	v_mul_f32_e32 v21, v108, v108
	v_fmac_f32_e32 v21, v124, v124
	v_fmac_f32_e32 v21, v28, v28
	v_fmac_f32_e32 v21, v5, v5
	s_nop 1
	v_add_f32_dpp v21, v21, v21 quad_perm:[1,0,3,2] row_mask:0xf bank_mask:0xf
	v_mul_f32_e32 v29, v29, v22
	v_mul_f32_e32 v6, v6, v22
	s_nop 1
	v_add_f32_dpp v21, v21, v21 quad_perm:[2,3,0,1] row_mask:0xf bank_mask:0xf
	s_nop 1
	v_add_f32_dpp v21, v21, v21 row_half_mirror row_mask:0xf bank_mask:0xf
	s_nop 1
	v_add_f32_dpp v21, v21, v21 row_mirror row_mask:0xf bank_mask:0xf
	v_mov_b32_e32 v49, v21
	v_mov_b32_e32 v50, v21
	s_nop 1
	v_permlane16_swap_b32_e32 v49, v50
	v_add_f32_e32 v21, v49, v50
	v_fmamk_f32 v21, v21, 0x3c000000, v100
	v_cmp_gt_f32_e32 vcc, s33, v21
	v_mul_f32_e32 v49, 0x4f800000, v21
	s_nop 0
	v_cndmask_b32_e32 v21, v21, v49, vcc
	v_sqrt_f32_e32 v49, v21
	s_nop 0
	v_add_u32_e32 v50, -1, v49
	v_fma_f32 v51, -v50, v49, v21
	v_cmp_ge_f32_e64 s[8:9], 0, v51
	v_add_u32_e32 v51, 1, v49
	s_nop 0
	v_cndmask_b32_e64 v50, v49, v50, s[8:9]
	v_fma_f32 v49, -v51, v49, v21
	v_cmp_lt_f32_e64 s[8:9], 0, v49
	s_nop 1
	v_cndmask_b32_e64 v49, v50, v51, s[8:9]
	v_mul_f32_e32 v50, 0x37800000, v49
	v_cndmask_b32_e32 v49, v49, v50, vcc
	v_cmp_class_f32_e32 vcc, v21, v101
	s_nop 1
	v_cndmask_b32_e32 v21, v49, v21, vcc
	s_nop 0
	v_div_scale_f32 v51, vcc, 1.0, v21, 1.0
	v_rcp_f32_e32 v21, v21
	v_mul_f32_e32 v49, v107, v107
	v_fmac_f32_e32 v49, v123, v123
	v_fmac_f32_e32 v49, v26, v26
	v_fmac_f32_e32 v49, v4, v4
	ds_bpermute_b32 v2, v2, v49
	v_mul_f32_e32 v28, v28, v21
	v_mul_f32_e32 v5, v5, v21
	s_waitcnt lgkmcnt(0)
	v_add_f32_e32 v2, v49, v2
	ds_bpermute_b32 v3, v3, v2
	s_waitcnt lgkmcnt(0)
	v_add_f32_e32 v2, v2, v3
	ds_bpermute_b32 v3, v20, v2
	s_waitcnt lgkmcnt(0)
	v_add_f32_e32 v2, v2, v3
	ds_bpermute_b32 v3, v47, v2
	s_waitcnt lgkmcnt(0)
	v_add_f32_e32 v2, v2, v3
	ds_bpermute_b32 v3, v48, v2
	s_waitcnt lgkmcnt(0)
	v_add_f32_e32 v2, v2, v3
	v_fmamk_f32 v2, v2, 0x3c000000, v100
	v_cmp_gt_f32_e32 vcc, s33, v2
	v_mul_f32_e32 v3, 0x4f800000, v2
	s_nop 0
	v_cndmask_b32_e32 v2, v2, v3, vcc
	v_sqrt_f32_e32 v3, v2
	s_nop 0
	v_add_u32_e32 v20, -1, v3
	v_fma_f32 v47, -v20, v3, v2
	v_cmp_ge_f32_e64 s[8:9], 0, v47
	v_add_u32_e32 v47, 1, v3
	s_nop 0
	v_cndmask_b32_e64 v20, v3, v20, s[8:9]
	v_fma_f32 v3, -v47, v3, v2
	v_cmp_lt_f32_e64 s[8:9], 0, v3
	s_nop 1
	v_cndmask_b32_e64 v3, v20, v47, s[8:9]
	v_mul_f32_e32 v20, 0x37800000, v3
	v_cndmask_b32_e32 v3, v3, v20, vcc
	v_cmp_class_f32_e32 vcc, v2, v101
	s_nop 1
	v_cndmask_b32_e32 v2, v3, v2, vcc
	s_nop 0
	v_rcp_f32_e32 v20, v2
	v_mul_f32_e32 v47, v138, v46
	v_mul_f32_e32 v26, v26, v20
	v_mul_f32_e32 v4, v4, v20
	s_waitcnt vmcnt(2) lgkmcnt(0)
	ds_write_b128 v92, v[164:167]
	s_waitcnt vmcnt(0) lgkmcnt(0)
	ds_write_b128 v92, v[170:173] offset:1088
	s_waitcnt vmcnt(13) lgkmcnt(0)
	ds_write_b128 v92, v[174:177] offset:2176
	s_waitcnt vmcnt(8) lgkmcnt(0)
	ds_write_b128 v92, v[178:181] offset:3264
	s_waitcnt vmcnt(9) lgkmcnt(0)
	ds_write_b128 v92, v[196:199] offset:4352
	s_waitcnt vmcnt(10) lgkmcnt(0)
	ds_write_b128 v92, v[200:203] offset:5440
	v_lshl_add_u64 v[2:3], v[168:169], 0, v[80:81]
	s_waitcnt vmcnt(5) lgkmcnt(0)
	ds_write_b128 v92, v[204:207] offset:6528
	global_load_dwordx4 v[48:51], v[2:3], off
	s_waitcnt vmcnt(0) lgkmcnt(0)
	ds_write_b128 v92, v[48:51] offset:7616
	s_waitcnt lgkmcnt(0)
	ds_read_u16 v3, v1
	s_waitcnt lgkmcnt(0)
	v_lshlrev_b32_e32 v3, 16, v3
	v_mul_f32_e32 v48, 0xbfb8aa3b, v3
	v_exp_f32_e32 v48, v48
	s_waitcnt vmcnt(0)
; #define LAS __attribute__((address_space(3)))
; DI unsigned cvtpk(float lo, float hi) { f32x2 v = {lo, hi}; bf16x2_t b = __builtin_convertvector(v, bf16x2_t); return __builtin_bit_cast(unsigned, b); }
; DI float bf2f(bf16 b) { return __uint_as_float(((unsigned)b) << 16); }
; DI float siluf_(float x) { return x / (1.f + __expf(-x)); }
; DI void gla_stage3(const Ctx& c0, int layer, int unit, int cb, LAS unsigned char* lds) {
;     ...
;     for (int vb = 0; vb < 4; ++vb) { const float g = gn[32 * vb + r];
; #pragma unroll
;         for (int rg = 0; rg < 16; ++rg) { LAS bf16* e = (LAS bf16*)(R + (4 * hi) * G3_PITCH + r * 2 + ((rg & 3) + 8 * (rg >> 2)) * G3_PITCH + 64 * vb);
;             const float z = bf2f(*e);
;             *e = (bf16)(cvtpk(o[vb][rg] * rs[rg] * g * siluf_(z), 0.f) & 0xffffu); }
	v_mul_f32_e32 v47, v47, v232
	v_add_f32_e32 v48, 1.0, v48
	v_rcp_f32_e32 v49, v48
	s_nop 0
	v_mul_f32_e32 v3, v3, v49
	v_mul_f32_e32 v3, v47, v3
	v_cvt_pk_bf16_f32 v3, v3, v3
	ds_write_b16 v1, v3
	ds_read_u16 v3, v1 offset:272
	v_mul_f32_e32 v47, v137, v45
	v_mul_f32_e32 v47, v47, v232
	s_waitcnt lgkmcnt(0)
	v_lshlrev_b32_e32 v3, 16, v3
	v_mul_f32_e32 v48, 0xbfb8aa3b, v3
	v_exp_f32_e32 v48, v48
	s_nop 0
	v_add_f32_e32 v48, 1.0, v48
	v_rcp_f32_e32 v49, v48
	s_nop 0
	v_mul_f32_e32 v3, v3, v49
	v_mul_f32_e32 v3, v47, v3
	v_cvt_pk_bf16_f32 v3, v3, v3
	ds_write_b16 v1, v3 offset:272
	ds_read_u16 v3, v1 offset:544
	v_mul_f32_e32 v47, v136, v44
	v_mul_f32_e32 v47, v47, v232
	s_waitcnt lgkmcnt(0)
	v_lshlrev_b32_e32 v3, 16, v3
	v_mul_f32_e32 v48, 0xbfb8aa3b, v3
	v_exp_f32_e32 v48, v48
	s_nop 0
	v_add_f32_e32 v48, 1.0, v48
	v_rcp_f32_e32 v49, v48
	s_nop 0
	v_mul_f32_e32 v3, v3, v49
	v_mul_f32_e32 v3, v47, v3
	v_cvt_pk_bf16_f32 v3, v3, v3
	ds_write_b16 v1, v3 offset:544
	ds_read_u16 v3, v1 offset:816
	v_mul_f32_e32 v47, v135, v43
	v_mul_f32_e32 v47, v47, v232
	s_waitcnt lgkmcnt(0)
	v_lshlrev_b32_e32 v3, 16, v3
	v_mul_f32_e32 v48, 0xbfb8aa3b, v3
	v_exp_f32_e32 v48, v48
	s_nop 0
	v_add_f32_e32 v48, 1.0, v48
	v_rcp_f32_e32 v49, v48
	s_nop 0
	v_mul_f32_e32 v3, v3, v49
	v_mul_f32_e32 v3, v47, v3
	v_cvt_pk_bf16_f32 v3, v3, v3
	ds_write_b16 v1, v3 offset:816
	ds_read_u16 v3, v1 offset:2176
	v_mul_f32_e32 v47, v134, v42
	v_mul_f32_e32 v47, v47, v232
	s_waitcnt lgkmcnt(0)
	v_lshlrev_b32_e32 v3, 16, v3
	v_mul_f32_e32 v48, 0xbfb8aa3b, v3
	v_exp_f32_e32 v48, v48
	s_nop 0
	v_add_f32_e32 v48, 1.0, v48
	v_rcp_f32_e32 v49, v48
	s_nop 0
	v_mul_f32_e32 v3, v3, v49
	v_mul_f32_e32 v3, v47, v3
	v_cvt_pk_bf16_f32 v3, v3, v3
	ds_write_b16 v1, v3 offset:2176
	ds_read_u16 v3, v1 offset:2448
	v_mul_f32_e32 v47, v133, v41
	v_mul_f32_e32 v47, v47, v232
	s_waitcnt lgkmcnt(0)
	v_lshlrev_b32_e32 v3, 16, v3
	v_mul_f32_e32 v48, 0xbfb8aa3b, v3
	v_exp_f32_e32 v48, v48
	s_nop 0
	v_add_f32_e32 v48, 1.0, v48
	v_rcp_f32_e32 v49, v48
	s_nop 0
	v_mul_f32_e32 v3, v3, v49
	v_mul_f32_e32 v3, v47, v3
	v_cvt_pk_bf16_f32 v3, v3, v3
	ds_write_b16 v1, v3 offset:2448
	ds_read_u16 v3, v1 offset:2720
	v_mul_f32_e32 v47, v132, v40
	v_mul_f32_e32 v47, v47, v232
	s_waitcnt lgkmcnt(0)
	v_lshlrev_b32_e32 v3, 16, v3
	v_mul_f32_e32 v48, 0xbfb8aa3b, v3
	v_exp_f32_e32 v48, v48
	s_nop 0
	v_add_f32_e32 v48, 1.0, v48
	v_rcp_f32_e32 v49, v48
	s_nop 0
	v_mul_f32_e32 v3, v3, v49
	v_mul_f32_e32 v3, v47, v3
	v_cvt_pk_bf16_f32 v3, v3, v3
	ds_write_b16 v1, v3 offset:2720
	ds_read_u16 v3, v1 offset:2992
	v_mul_f32_e32 v47, v131, v35
	v_mul_f32_e32 v47, v47, v232
	s_waitcnt lgkmcnt(0)
	v_lshlrev_b32_e32 v3, 16, v3
	v_mul_f32_e32 v48, 0xbfb8aa3b, v3
	v_exp_f32_e32 v48, v48
	s_nop 0
	v_add_f32_e32 v48, 1.0, v48
	v_rcp_f32_e32 v49, v48
	s_nop 0
	v_mul_f32_e32 v3, v3, v49
	v_mul_f32_e32 v3, v47, v3
	v_cvt_pk_bf16_f32 v3, v3, v3
	ds_write_b16 v1, v3 offset:2992
	ds_read_u16 v3, v1 offset:4352
	v_mul_f32_e32 v47, v130, v31
	v_mul_f32_e32 v47, v47, v232
	s_waitcnt lgkmcnt(0)
	v_lshlrev_b32_e32 v3, 16, v3
	v_mul_f32_e32 v48, 0xbfb8aa3b, v3
	v_exp_f32_e32 v48, v48
	s_nop 0
	v_add_f32_e32 v48, 1.0, v48
	v_rcp_f32_e32 v49, v48
	s_nop 0
	v_mul_f32_e32 v3, v3, v49
	v_mul_f32_e32 v3, v47, v3
	v_cvt_pk_bf16_f32 v3, v3, v3
	ds_write_b16 v1, v3 offset:4352
	ds_read_u16 v3, v1 offset:4624
	v_mul_f32_e32 v47, v129, v27
	v_mul_f32_e32 v47, v47, v232
	s_waitcnt lgkmcnt(0)
	v_lshlrev_b32_e32 v3, 16, v3
	v_mul_f32_e32 v48, 0xbfb8aa3b, v3
	v_exp_f32_e32 v48, v48
	s_nop 0
	v_add_f32_e32 v48, 1.0, v48
	v_rcp_f32_e32 v49, v48
	s_nop 0
	v_mul_f32_e32 v3, v3, v49
	v_mul_f32_e32 v3, v47, v3
	v_cvt_pk_bf16_f32 v3, v3, v3
	ds_write_b16 v1, v3 offset:4624
	ds_read_u16 v3, v1 offset:4896
	v_mul_f32_e32 v47, v128, v25
	v_mul_f32_e32 v47, v47, v232
	s_waitcnt lgkmcnt(0)
	v_lshlrev_b32_e32 v3, 16, v3
	v_mul_f32_e32 v48, 0xbfb8aa3b, v3
	v_exp_f32_e32 v48, v48
	s_nop 0
	v_add_f32_e32 v48, 1.0, v48
	v_rcp_f32_e32 v49, v48
	s_nop 0
	v_mul_f32_e32 v3, v3, v49
	v_mul_f32_e32 v3, v47, v3
	v_cvt_pk_bf16_f32 v3, v3, v3
	ds_write_b16 v1, v3 offset:4896
	ds_read_u16 v3, v1 offset:5168
	v_mul_f32_e32 v47, v127, v24
	v_mul_f32_e32 v47, v47, v232
	s_waitcnt lgkmcnt(0)
	v_lshlrev_b32_e32 v3, 16, v3
	v_mul_f32_e32 v48, 0xbfb8aa3b, v3
	v_exp_f32_e32 v48, v48
	s_nop 0
	v_add_f32_e32 v48, 1.0, v48
	v_rcp_f32_e32 v49, v48
	s_nop 0
	v_mul_f32_e32 v3, v3, v49
	v_mul_f32_e32 v3, v47, v3
	v_cvt_pk_bf16_f32 v3, v3, v3
	ds_write_b16 v1, v3 offset:5168
	ds_read_u16 v3, v1 offset:6528
	v_mul_f32_e32 v47, v126, v23
	v_mul_f32_e32 v47, v47, v232
	s_waitcnt lgkmcnt(0)
	v_lshlrev_b32_e32 v3, 16, v3
	v_mul_f32_e32 v48, 0xbfb8aa3b, v3
	v_exp_f32_e32 v48, v48
	s_nop 0
	v_add_f32_e32 v48, 1.0, v48
	v_rcp_f32_e32 v49, v48
	s_nop 0
	v_mul_f32_e32 v3, v3, v49
	v_mul_f32_e32 v3, v47, v3
	v_cvt_pk_bf16_f32 v3, v3, v3
	ds_write_b16 v1, v3 offset:6528
	ds_read_u16 v3, v1 offset:6800
	v_mul_f32_e32 v47, v125, v22
	v_mul_f32_e32 v47, v47, v232
	s_waitcnt lgkmcnt(0)
	v_lshlrev_b32_e32 v3, 16, v3
	v_mul_f32_e32 v48, 0xbfb8aa3b, v3
	v_exp_f32_e32 v48, v48
	s_nop 0
	v_add_f32_e32 v48, 1.0, v48
	v_rcp_f32_e32 v49, v48
	s_nop 0
	v_mul_f32_e32 v3, v3, v49
	v_mul_f32_e32 v3, v47, v3
	v_cvt_pk_bf16_f32 v3, v3, v3
	ds_write_b16 v1, v3 offset:6800
	ds_read_u16 v3, v1 offset:7072
	v_mul_f32_e32 v47, v124, v21
	v_mul_f32_e32 v47, v47, v232
	s_waitcnt lgkmcnt(0)
	v_lshlrev_b32_e32 v3, 16, v3
	v_mul_f32_e32 v48, 0xbfb8aa3b, v3
	v_exp_f32_e32 v48, v48
	s_nop 0
	v_add_f32_e32 v48, 1.0, v48
	v_rcp_f32_e32 v49, v48
	s_nop 0
	v_mul_f32_e32 v3, v3, v49
	v_mul_f32_e32 v3, v47, v3
	v_cvt_pk_bf16_f32 v3, v3, v3
	ds_write_b16 v1, v3 offset:7072
	ds_read_u16 v3, v1 offset:7344
	v_mul_f32_e32 v47, v123, v20
	v_mul_f32_e32 v2, v47, v232
	s_waitcnt lgkmcnt(0)
; #define LAS __attribute__((address_space(3)))
; DI unsigned cvtpk(float lo, float hi) { f32x2 v = {lo, hi}; bf16x2_t b = __builtin_convertvector(v, bf16x2_t); return __builtin_bit_cast(unsigned, b); }
; DI float bf2f(bf16 b) { return __uint_as_float(((unsigned)b) << 16); }
; DI float siluf_(float x) { return x / (1.f + __expf(-x)); }
; DI void gla_stage3(const Ctx& c0, int layer, int unit, int cb, LAS unsigned char* lds) {
;     ...
;     for (int vb = 0; vb < 4; ++vb) { const float g = gn[32 * vb + r];
; #pragma unroll
;         for (int rg = 0; rg < 16; ++rg) { LAS bf16* e = (LAS bf16*)(R + (4 * hi) * G3_PITCH + r * 2 + ((rg & 3) + 8 * (rg >> 2)) * G3_PITCH + 64 * vb);
;             const float z = bf2f(*e);
;             *e = (bf16)(cvtpk(o[vb][rg] * rs[rg] * g * siluf_(z), 0.f) & 0xffffu); }
;         asm volatile("" ::: "memory"); }
	v_lshlrev_b32_e32 v3, 16, v3
	v_mul_f32_e32 v47, 0xbfb8aa3b, v3
	v_exp_f32_e32 v47, v47
	s_nop 0
	v_add_f32_e32 v47, 1.0, v47
	v_div_scale_f32 v48, s[0:1], v47, v47, v3
	s_nop 0
	v_rcp_f32_e32 v48, v47
	s_nop 0
	v_mul_f32_e32 v3, v3, v48
	v_mul_f32_e32 v2, v2, v3
	v_cvt_pk_bf16_f32 v2, v2, s0
	ds_write_b16 v1, v2 offset:7344
	ds_read_u16 v3, v1 offset:64
	v_mul_f32_e32 v47, v122, v46
	s_waitcnt lgkmcnt(0)
	v_lshlrev_b32_e32 v3, 16, v3
	v_mul_f32_e32 v48, 0xbfb8aa3b, v3
	v_exp_f32_e32 v48, v48
	s_waitcnt vmcnt(0)
	v_mul_f32_e32 v47, v47, v234
	v_add_f32_e32 v48, 1.0, v48
	v_rcp_f32_e32 v49, v48
	s_nop 0
	v_mul_f32_e32 v3, v3, v49
	v_mul_f32_e32 v3, v47, v3
	v_cvt_pk_bf16_f32 v3, v3, v3
	ds_write_b16 v1, v3 offset:64
	ds_read_u16 v3, v1 offset:336
	v_mul_f32_e32 v47, v121, v45
	v_mul_f32_e32 v47, v47, v234
	s_waitcnt lgkmcnt(0)
	v_lshlrev_b32_e32 v3, 16, v3
	v_mul_f32_e32 v48, 0xbfb8aa3b, v3
	v_exp_f32_e32 v48, v48
	s_nop 0
	v_add_f32_e32 v48, 1.0, v48
	v_rcp_f32_e32 v49, v48
	s_nop 0
	v_mul_f32_e32 v3, v3, v49
	v_mul_f32_e32 v3, v47, v3
	v_cvt_pk_bf16_f32 v3, v3, v3
	ds_write_b16 v1, v3 offset:336
	ds_read_u16 v3, v1 offset:608
	v_mul_f32_e32 v47, v120, v44
	v_mul_f32_e32 v47, v47, v234
	s_waitcnt lgkmcnt(0)
	v_lshlrev_b32_e32 v3, 16, v3
	v_mul_f32_e32 v48, 0xbfb8aa3b, v3
	v_exp_f32_e32 v48, v48
	s_nop 0
	v_add_f32_e32 v48, 1.0, v48
	v_rcp_f32_e32 v49, v48
	s_nop 0
	v_mul_f32_e32 v3, v3, v49
	v_mul_f32_e32 v3, v47, v3
	v_cvt_pk_bf16_f32 v3, v3, v3
	ds_write_b16 v1, v3 offset:608
	ds_read_u16 v3, v1 offset:880
	v_mul_f32_e32 v47, v119, v43
	v_mul_f32_e32 v47, v47, v234
	s_waitcnt lgkmcnt(0)
	v_lshlrev_b32_e32 v3, 16, v3
	v_mul_f32_e32 v48, 0xbfb8aa3b, v3
	v_exp_f32_e32 v48, v48
	s_nop 0
	v_add_f32_e32 v48, 1.0, v48
	v_rcp_f32_e32 v49, v48
	s_nop 0
	v_mul_f32_e32 v3, v3, v49
	v_mul_f32_e32 v3, v47, v3
	v_cvt_pk_bf16_f32 v3, v3, v3
	ds_write_b16 v1, v3 offset:880
	ds_read_u16 v3, v1 offset:2240
	v_mul_f32_e32 v47, v118, v42
	v_mul_f32_e32 v47, v47, v234
	s_waitcnt lgkmcnt(0)
	v_lshlrev_b32_e32 v3, 16, v3
	v_mul_f32_e32 v48, 0xbfb8aa3b, v3
	v_exp_f32_e32 v48, v48
	s_nop 0
	v_add_f32_e32 v48, 1.0, v48
	v_rcp_f32_e32 v49, v48
	s_nop 0
	v_mul_f32_e32 v3, v3, v49
	v_mul_f32_e32 v3, v47, v3
	v_cvt_pk_bf16_f32 v3, v3, v3
	ds_write_b16 v1, v3 offset:2240
	ds_read_u16 v3, v1 offset:2512
	v_mul_f32_e32 v47, v117, v41
	v_mul_f32_e32 v47, v47, v234
	s_waitcnt lgkmcnt(0)
	v_lshlrev_b32_e32 v3, 16, v3
	v_mul_f32_e32 v48, 0xbfb8aa3b, v3
	v_exp_f32_e32 v48, v48
	s_nop 0
	v_add_f32_e32 v48, 1.0, v48
	v_rcp_f32_e32 v49, v48
	s_nop 0
	v_mul_f32_e32 v3, v3, v49
	v_mul_f32_e32 v3, v47, v3
	v_cvt_pk_bf16_f32 v3, v3, v3
	ds_write_b16 v1, v3 offset:2512
	ds_read_u16 v3, v1 offset:2784
	v_mul_f32_e32 v47, v116, v40
	v_mul_f32_e32 v47, v47, v234
	s_waitcnt lgkmcnt(0)
	v_lshlrev_b32_e32 v3, 16, v3
	v_mul_f32_e32 v48, 0xbfb8aa3b, v3
	v_exp_f32_e32 v48, v48
	s_nop 0
	v_add_f32_e32 v48, 1.0, v48
	v_rcp_f32_e32 v49, v48
	s_nop 0
	v_mul_f32_e32 v3, v3, v49
	v_mul_f32_e32 v3, v47, v3
	v_cvt_pk_bf16_f32 v3, v3, v3
	ds_write_b16 v1, v3 offset:2784
	ds_read_u16 v3, v1 offset:3056
	v_mul_f32_e32 v47, v115, v35
	v_mul_f32_e32 v47, v47, v234
	s_waitcnt lgkmcnt(0)
	v_lshlrev_b32_e32 v3, 16, v3
	v_mul_f32_e32 v48, 0xbfb8aa3b, v3
	v_exp_f32_e32 v48, v48
	s_nop 0
	v_add_f32_e32 v48, 1.0, v48
	v_rcp_f32_e32 v49, v48
	s_nop 0
	v_mul_f32_e32 v3, v3, v49
	v_mul_f32_e32 v3, v47, v3
	v_cvt_pk_bf16_f32 v3, v3, v3
	ds_write_b16 v1, v3 offset:3056
	ds_read_u16 v3, v1 offset:4416
	v_mul_f32_e32 v47, v114, v31
	v_mul_f32_e32 v47, v47, v234
	s_waitcnt lgkmcnt(0)
	v_lshlrev_b32_e32 v3, 16, v3
	v_mul_f32_e32 v48, 0xbfb8aa3b, v3
	v_exp_f32_e32 v48, v48
	s_nop 0
	v_add_f32_e32 v48, 1.0, v48
	v_rcp_f32_e32 v49, v48
	s_nop 0
	v_mul_f32_e32 v3, v3, v49
	v_mul_f32_e32 v3, v47, v3
	v_cvt_pk_bf16_f32 v3, v3, v3
	ds_write_b16 v1, v3 offset:4416
	ds_read_u16 v3, v1 offset:4688
	v_mul_f32_e32 v47, v113, v27
	v_mul_f32_e32 v47, v47, v234
	s_waitcnt lgkmcnt(0)
	v_lshlrev_b32_e32 v3, 16, v3
	v_mul_f32_e32 v48, 0xbfb8aa3b, v3
	v_exp_f32_e32 v48, v48
	s_nop 0
	v_add_f32_e32 v48, 1.0, v48
	v_rcp_f32_e32 v49, v48
	s_nop 0
	v_mul_f32_e32 v3, v3, v49
	v_mul_f32_e32 v3, v47, v3
	v_cvt_pk_bf16_f32 v3, v3, v3
	ds_write_b16 v1, v3 offset:4688
	ds_read_u16 v3, v1 offset:4960
	v_mul_f32_e32 v47, v112, v25
	v_mul_f32_e32 v47, v47, v234
	s_waitcnt lgkmcnt(0)
	v_lshlrev_b32_e32 v3, 16, v3
	v_mul_f32_e32 v48, 0xbfb8aa3b, v3
	v_exp_f32_e32 v48, v48
	s_nop 0
	v_add_f32_e32 v48, 1.0, v48
	v_rcp_f32_e32 v49, v48
	s_nop 0
	v_mul_f32_e32 v3, v3, v49
	v_mul_f32_e32 v3, v47, v3
	v_cvt_pk_bf16_f32 v3, v3, v3
	ds_write_b16 v1, v3 offset:4960
	ds_read_u16 v3, v1 offset:5232
	v_mul_f32_e32 v47, v111, v24
	v_mul_f32_e32 v47, v47, v234
	s_waitcnt lgkmcnt(0)
	v_lshlrev_b32_e32 v3, 16, v3
	v_mul_f32_e32 v48, 0xbfb8aa3b, v3
	v_exp_f32_e32 v48, v48
	s_nop 0
	v_add_f32_e32 v48, 1.0, v48
	v_rcp_f32_e32 v49, v48
	s_nop 0
	v_mul_f32_e32 v3, v3, v49
	v_mul_f32_e32 v3, v47, v3
	v_cvt_pk_bf16_f32 v3, v3, v3
	ds_write_b16 v1, v3 offset:5232
	ds_read_u16 v3, v1 offset:6592
	v_mul_f32_e32 v47, v110, v23
	v_mul_f32_e32 v47, v47, v234
	s_waitcnt lgkmcnt(0)
	v_lshlrev_b32_e32 v3, 16, v3
	v_mul_f32_e32 v48, 0xbfb8aa3b, v3
	v_exp_f32_e32 v48, v48
	s_nop 0
	v_add_f32_e32 v48, 1.0, v48
	v_rcp_f32_e32 v49, v48
	s_nop 0
	v_mul_f32_e32 v3, v3, v49
	v_mul_f32_e32 v3, v47, v3
	v_cvt_pk_bf16_f32 v3, v3, v3
	ds_write_b16 v1, v3 offset:6592
	ds_read_u16 v3, v1 offset:6864
	v_mul_f32_e32 v47, v109, v22
	v_mul_f32_e32 v47, v47, v234
	s_waitcnt lgkmcnt(0)
; #define LAS __attribute__((address_space(3)))
; DI unsigned cvtpk(float lo, float hi) { f32x2 v = {lo, hi}; bf16x2_t b = __builtin_convertvector(v, bf16x2_t); return __builtin_bit_cast(unsigned, b); }
; DI float bf2f(bf16 b) { return __uint_as_float(((unsigned)b) << 16); }
; DI float siluf_(float x) { return x / (1.f + __expf(-x)); }
; DI void gla_stage3(const Ctx& c0, int layer, int unit, int cb, LAS unsigned char* lds) {
;     ...
;     for (int vb = 0; vb < 4; ++vb) { const float g = gn[32 * vb + r];
; #pragma unroll
;         for (int rg = 0; rg < 16; ++rg) { LAS bf16* e = (LAS bf16*)(R + (4 * hi) * G3_PITCH + r * 2 + ((rg & 3) + 8 * (rg >> 2)) * G3_PITCH + 64 * vb);
;             const float z = bf2f(*e);
;             *e = (bf16)(cvtpk(o[vb][rg] * rs[rg] * g * siluf_(z), 0.f) & 0xffffu); }
;         asm volatile("" ::: "memory"); }
	v_lshlrev_b32_e32 v3, 16, v3
	v_mul_f32_e32 v48, 0xbfb8aa3b, v3
	v_exp_f32_e32 v48, v48
	s_nop 0
	v_add_f32_e32 v48, 1.0, v48
	v_rcp_f32_e32 v49, v48
	s_nop 0
	v_mul_f32_e32 v3, v3, v49
	v_mul_f32_e32 v3, v47, v3
	v_cvt_pk_bf16_f32 v3, v3, v3
	ds_write_b16 v1, v3 offset:6864
	ds_read_u16 v3, v1 offset:7136
	v_mul_f32_e32 v47, v108, v21
	v_mul_f32_e32 v47, v47, v234
	s_waitcnt lgkmcnt(0)
	v_lshlrev_b32_e32 v3, 16, v3
	v_mul_f32_e32 v48, 0xbfb8aa3b, v3
	v_exp_f32_e32 v48, v48
	s_nop 0
	v_add_f32_e32 v48, 1.0, v48
	v_rcp_f32_e32 v49, v48
	s_nop 0
	v_mul_f32_e32 v3, v3, v49
	v_mul_f32_e32 v3, v47, v3
	v_cvt_pk_bf16_f32 v3, v3, v3
	ds_write_b16 v1, v3 offset:7136
	ds_read_u16 v3, v1 offset:7408
	v_mul_f32_e32 v47, v107, v20
	v_mul_f32_e32 v2, v47, v234
	s_waitcnt lgkmcnt(0)
	v_lshlrev_b32_e32 v3, 16, v3
	v_mul_f32_e32 v47, 0xbfb8aa3b, v3
	v_exp_f32_e32 v47, v47
	s_nop 0
	v_add_f32_e32 v47, 1.0, v47
	v_div_scale_f32 v48, s[0:1], v47, v47, v3
	s_nop 0
	v_rcp_f32_e32 v48, v47
	s_nop 0
	v_mul_f32_e32 v3, v3, v48
	v_mul_f32_e32 v2, v2, v3
	v_cvt_pk_bf16_f32 v2, v2, s0
	ds_write_b16 v1, v2 offset:7408
	ds_read_u16 v3, v1 offset:128
	v_mul_f32_e32 v47, v106, v46
	s_waitcnt lgkmcnt(0)
	v_lshlrev_b32_e32 v3, 16, v3
	v_mul_f32_e32 v48, 0xbfb8aa3b, v3
	v_exp_f32_e32 v48, v48
	s_waitcnt vmcnt(0)
	v_mul_f32_e32 v47, v47, v236
	v_add_f32_e32 v48, 1.0, v48
	v_div_scale_f32 v49, s[0:1], v48, v48, v3
	v_mul_f32_e32 v39, v39, v236
	v_mul_f32_e32 v38, v38, v236
	v_mul_f32_e32 v37, v37, v236
	v_rcp_f32_e32 v49, v48
	s_nop 0
	v_mul_f32_e32 v3, v3, v49
	v_mul_f32_e32 v3, v47, v3
	v_cvt_pk_bf16_f32 v3, v3, s0
	ds_write_b16 v1, v3 offset:128
	ds_read_u16 v3, v1 offset:400
	v_mul_f32_e32 v47, v105, v45
	v_mul_f32_e32 v47, v47, v236
	v_mul_f32_e32 v36, v36, v236
	v_mul_f32_e32 v34, v34, v236
	s_waitcnt lgkmcnt(0)
	v_lshlrev_b32_e32 v3, 16, v3
	v_mul_f32_e32 v48, 0xbfb8aa3b, v3
	v_exp_f32_e32 v48, v48
	v_mul_f32_e32 v33, v33, v236
	v_mul_f32_e32 v32, v32, v236
	v_mul_f32_e32 v30, v30, v236
	v_add_f32_e32 v48, 1.0, v48
	v_div_scale_f32 v49, s[0:1], v48, v48, v3
	v_mul_f32_e32 v29, v29, v236
	v_mul_f32_e32 v28, v28, v236
	v_rcp_f32_e32 v49, v48
	s_nop 0
	v_mul_f32_e32 v3, v3, v49
	v_mul_f32_e32 v3, v47, v3
	v_cvt_pk_bf16_f32 v3, v3, s0
	ds_write_b16 v1, v3 offset:400
	ds_read_u16 v3, v1 offset:672
	v_mul_f32_e32 v47, v104, v44
	v_mul_f32_e32 v47, v47, v236
	s_waitcnt lgkmcnt(0)
	v_lshlrev_b32_e32 v3, 16, v3
	v_mul_f32_e32 v48, 0xbfb8aa3b, v3
	v_exp_f32_e32 v48, v48
	s_nop 0
	v_add_f32_e32 v48, 1.0, v48
	v_rcp_f32_e32 v49, v48
	s_nop 0
	v_mul_f32_e32 v3, v3, v49
	v_mul_f32_e32 v3, v47, v3
	v_cvt_pk_bf16_f32 v3, v3, v3
	ds_write_b16 v1, v3 offset:672
	ds_read_u16 v3, v1 offset:944
	v_mul_f32_e32 v47, v103, v43
	v_mul_f32_e32 v47, v47, v236
	s_waitcnt lgkmcnt(0)
	v_lshlrev_b32_e32 v3, 16, v3
	v_mul_f32_e32 v48, 0xbfb8aa3b, v3
	v_exp_f32_e32 v48, v48
	s_nop 0
	v_add_f32_e32 v48, 1.0, v48
	v_rcp_f32_e32 v49, v48
	s_nop 0
	v_mul_f32_e32 v3, v3, v49
	v_mul_f32_e32 v3, v47, v3
	v_cvt_pk_bf16_f32 v3, v3, v3
	ds_write_b16 v1, v3 offset:944
	ds_read_u16 v3, v1 offset:2304
	v_mul_f32_e32 v47, v102, v42
	v_mul_f32_e32 v47, v47, v236
	v_mul_f32_e32 v2, v26, v236
	s_waitcnt lgkmcnt(0)
	v_lshlrev_b32_e32 v3, 16, v3
	v_mul_f32_e32 v48, 0xbfb8aa3b, v3
	v_exp_f32_e32 v48, v48
	s_nop 0
	v_add_f32_e32 v48, 1.0, v48
	v_rcp_f32_e32 v49, v48
	s_nop 0
	v_mul_f32_e32 v3, v3, v49
	v_mul_f32_e32 v3, v47, v3
	v_cvt_pk_bf16_f32 v3, v3, v3
	ds_write_b16 v1, v3 offset:2304
	ds_read_u16 v3, v1 offset:2576
	s_waitcnt lgkmcnt(0)
	v_lshlrev_b32_e32 v3, 16, v3
	v_mul_f32_e32 v47, 0xbfb8aa3b, v3
	v_exp_f32_e32 v47, v47
	s_nop 0
	v_add_f32_e32 v47, 1.0, v47
	v_rcp_f32_e32 v48, v47
	s_nop 0
	v_mul_f32_e32 v3, v3, v48
	v_mul_f32_e32 v3, v39, v3
	v_cvt_pk_bf16_f32 v3, v3, v3
	ds_write_b16 v1, v3 offset:2576
	ds_read_u16 v3, v1 offset:2848
	s_waitcnt lgkmcnt(0)
	v_lshlrev_b32_e32 v3, 16, v3
	v_mul_f32_e32 v39, 0xbfb8aa3b, v3
	v_exp_f32_e32 v39, v39
	s_nop 0
	v_add_f32_e32 v39, 1.0, v39
	v_rcp_f32_e32 v47, v39
	s_nop 0
	v_mul_f32_e32 v3, v3, v47
	v_mul_f32_e32 v3, v38, v3
	v_cvt_pk_bf16_f32 v3, v3, v3
	ds_write_b16 v1, v3 offset:2848
	ds_read_u16 v3, v1 offset:3120
	s_waitcnt lgkmcnt(0)
	v_lshlrev_b32_e32 v3, 16, v3
	v_mul_f32_e32 v38, 0xbfb8aa3b, v3
	v_exp_f32_e32 v38, v38
	s_nop 0
	v_add_f32_e32 v38, 1.0, v38
	v_rcp_f32_e32 v39, v38
	s_nop 0
	v_mul_f32_e32 v3, v3, v39
	v_mul_f32_e32 v3, v37, v3
	v_cvt_pk_bf16_f32 v3, v3, v3
	ds_write_b16 v1, v3 offset:3120
	ds_read_u16 v3, v1 offset:4480
	s_waitcnt lgkmcnt(0)
	v_lshlrev_b32_e32 v3, 16, v3
	v_mul_f32_e32 v37, 0xbfb8aa3b, v3
	v_exp_f32_e32 v37, v37
	s_nop 0
	v_add_f32_e32 v37, 1.0, v37
	v_rcp_f32_e32 v38, v37
	s_nop 0
	v_mul_f32_e32 v3, v3, v38
	v_mul_f32_e32 v3, v36, v3
	v_cvt_pk_bf16_f32 v3, v3, v3
	ds_write_b16 v1, v3 offset:4480
	ds_read_u16 v3, v1 offset:4752
	s_waitcnt lgkmcnt(0)
	v_lshlrev_b32_e32 v3, 16, v3
	v_mul_f32_e32 v36, 0xbfb8aa3b, v3
	v_exp_f32_e32 v36, v36
	s_nop 0
	v_add_f32_e32 v36, 1.0, v36
	v_rcp_f32_e32 v37, v36
	s_nop 0
	v_mul_f32_e32 v3, v3, v37
	v_mul_f32_e32 v3, v34, v3
	v_cvt_pk_bf16_f32 v3, v3, v3
	ds_write_b16 v1, v3 offset:4752
	ds_read_u16 v3, v1 offset:5024
	s_waitcnt lgkmcnt(0)
	v_lshlrev_b32_e32 v3, 16, v3
	v_mul_f32_e32 v34, 0xbfb8aa3b, v3
	v_exp_f32_e32 v34, v34
	s_nop 0
	v_add_f32_e32 v34, 1.0, v34
	v_rcp_f32_e32 v36, v34
	s_nop 0
	v_mul_f32_e32 v3, v3, v36
	v_mul_f32_e32 v3, v33, v3
	v_cvt_pk_bf16_f32 v3, v3, v3
	ds_write_b16 v1, v3 offset:5024
	ds_read_u16 v3, v1 offset:5296
	s_waitcnt lgkmcnt(0)
; #define LAS __attribute__((address_space(3)))
; DI unsigned cvtpk(float lo, float hi) { f32x2 v = {lo, hi}; bf16x2_t b = __builtin_convertvector(v, bf16x2_t); return __builtin_bit_cast(unsigned, b); }
; DI float bf2f(bf16 b) { return __uint_as_float(((unsigned)b) << 16); }
; DI float siluf_(float x) { return x / (1.f + __expf(-x)); }
; DI void gla_stage3(const Ctx& c0, int layer, int unit, int cb, LAS unsigned char* lds) {
;     ...
;     for (int vb = 0; vb < 4; ++vb) { const float g = gn[32 * vb + r];
; #pragma unroll
;         for (int rg = 0; rg < 16; ++rg) { LAS bf16* e = (LAS bf16*)(R + (4 * hi) * G3_PITCH + r * 2 + ((rg & 3) + 8 * (rg >> 2)) * G3_PITCH + 64 * vb);
;             const float z = bf2f(*e);
;             *e = (bf16)(cvtpk(o[vb][rg] * rs[rg] * g * siluf_(z), 0.f) & 0xffffu); }
;         asm volatile("" ::: "memory"); }
	v_lshlrev_b32_e32 v3, 16, v3
	v_mul_f32_e32 v33, 0xbfb8aa3b, v3
	v_exp_f32_e32 v33, v33
	s_nop 0
	v_add_f32_e32 v33, 1.0, v33
	v_rcp_f32_e32 v34, v33
	s_nop 0
	v_mul_f32_e32 v3, v3, v34
	v_mul_f32_e32 v3, v32, v3
	v_cvt_pk_bf16_f32 v3, v3, v3
	ds_write_b16 v1, v3 offset:5296
	ds_read_u16 v3, v1 offset:6656
	s_waitcnt lgkmcnt(0)
	v_lshlrev_b32_e32 v3, 16, v3
	v_mul_f32_e32 v32, 0xbfb8aa3b, v3
	v_exp_f32_e32 v32, v32
	s_nop 0
	v_add_f32_e32 v32, 1.0, v32
	v_rcp_f32_e32 v33, v32
	s_nop 0
	v_mul_f32_e32 v3, v3, v33
	v_mul_f32_e32 v3, v30, v3
	v_cvt_pk_bf16_f32 v3, v3, v3
	ds_write_b16 v1, v3 offset:6656
	ds_read_u16 v3, v1 offset:6928
	s_waitcnt lgkmcnt(0)
	v_lshlrev_b32_e32 v3, 16, v3
	v_mul_f32_e32 v30, 0xbfb8aa3b, v3
	v_exp_f32_e32 v30, v30
	s_nop 0
	v_add_f32_e32 v30, 1.0, v30
	v_rcp_f32_e32 v32, v30
	s_nop 0
	v_mul_f32_e32 v3, v3, v32
	v_mul_f32_e32 v3, v29, v3
	v_cvt_pk_bf16_f32 v3, v3, v3
	ds_write_b16 v1, v3 offset:6928
	ds_read_u16 v3, v1 offset:7200
	s_waitcnt lgkmcnt(0)
	v_lshlrev_b32_e32 v3, 16, v3
	v_mul_f32_e32 v29, 0xbfb8aa3b, v3
	v_exp_f32_e32 v29, v29
	s_nop 0
	v_add_f32_e32 v29, 1.0, v29
	v_rcp_f32_e32 v30, v29
	s_nop 0
	v_mul_f32_e32 v3, v3, v30
	v_mul_f32_e32 v3, v28, v3
	v_cvt_pk_bf16_f32 v3, v3, v3
	ds_write_b16 v1, v3 offset:7200
	ds_read_u16 v3, v1 offset:7472
	s_waitcnt lgkmcnt(0)
	v_lshlrev_b32_e32 v3, 16, v3
	v_mul_f32_e32 v26, 0xbfb8aa3b, v3
	v_exp_f32_e32 v26, v26
	s_nop 0
	v_add_f32_e32 v26, 1.0, v26
	v_div_scale_f32 v28, s[0:1], v26, v26, v3
	s_nop 0
	v_rcp_f32_e32 v28, v26
	s_nop 0
	v_mul_f32_e32 v3, v3, v28
	v_mul_f32_e32 v2, v2, v3
	v_cvt_pk_bf16_f32 v2, v2, s0
	ds_write_b16 v1, v2 offset:7472
	ds_read_u16 v3, v1 offset:192
	s_waitcnt lgkmcnt(0)
	v_lshlrev_b32_e32 v3, 16, v3
	v_mul_f32_e32 v26, 0xbfb8aa3b, v3
	v_exp_f32_e32 v26, v26
	s_waitcnt vmcnt(31)
	v_mul_f32_e32 v19, v19, v238
	v_add_f32_e32 v26, 1.0, v26
	v_div_scale_f32 v28, s[0:1], v26, v26, v3
	v_mul_f32_e32 v18, v18, v238
	v_mul_f32_e32 v17, v17, v238
	v_mul_f32_e32 v16, v16, v238
	v_rcp_f32_e32 v28, v26
	s_nop 0
	v_mul_f32_e32 v3, v3, v28
	v_mul_f32_e32 v3, v19, v3
	v_cvt_pk_bf16_f32 v3, v3, s0
	ds_write_b16 v1, v3 offset:192
	ds_read_u16 v3, v1 offset:464
	v_mul_f32_e32 v15, v15, v238
	v_mul_f32_e32 v14, v14, v238
	v_mul_f32_e32 v13, v13, v238
	v_mul_f32_e32 v12, v12, v238
	s_waitcnt lgkmcnt(0)
	v_lshlrev_b32_e32 v3, 16, v3
	v_mul_f32_e32 v19, 0xbfb8aa3b, v3
	v_exp_f32_e32 v19, v19
	v_mul_f32_e32 v11, v11, v238
	v_mul_f32_e32 v10, v10, v238
	v_mul_f32_e32 v9, v9, v238
	v_add_f32_e32 v19, 1.0, v19
	v_div_scale_f32 v26, s[0:1], v19, v19, v3
	v_mul_f32_e32 v8, v8, v238
	v_mul_f32_e32 v7, v7, v238
	v_mul_f32_e32 v6, v6, v238
	v_rcp_f32_e32 v26, v19
	s_nop 0
	v_mul_f32_e32 v3, v3, v26
	v_mul_f32_e32 v3, v18, v3
	v_cvt_pk_bf16_f32 v3, v3, s0
	ds_write_b16 v1, v3 offset:464
	ds_read_u16 v3, v1 offset:736
	v_mul_f32_e32 v5, v5, v238
	v_mul_f32_e32 v2, v4, v238
	s_waitcnt lgkmcnt(0)
	v_lshlrev_b32_e32 v3, 16, v3
	v_mul_f32_e32 v18, 0xbfb8aa3b, v3
	v_exp_f32_e32 v18, v18
	s_nop 0
	v_add_f32_e32 v18, 1.0, v18
	v_rcp_f32_e32 v19, v18
	s_nop 0
	v_mul_f32_e32 v3, v3, v19
	v_mul_f32_e32 v3, v17, v3
	v_cvt_pk_bf16_f32 v3, v3, v3
	ds_write_b16 v1, v3 offset:736
	ds_read_u16 v3, v1 offset:1008
	s_waitcnt lgkmcnt(0)
	v_lshlrev_b32_e32 v3, 16, v3
	v_mul_f32_e32 v17, 0xbfb8aa3b, v3
	v_exp_f32_e32 v17, v17
	s_nop 0
	v_add_f32_e32 v17, 1.0, v17
	v_rcp_f32_e32 v18, v17
	s_nop 0
	v_mul_f32_e32 v3, v3, v18
	v_mul_f32_e32 v3, v16, v3
	v_cvt_pk_bf16_f32 v3, v3, v3
	ds_write_b16 v1, v3 offset:1008
	ds_read_u16 v3, v1 offset:2368
	s_waitcnt lgkmcnt(0)
	v_lshlrev_b32_e32 v3, 16, v3
	v_mul_f32_e32 v16, 0xbfb8aa3b, v3
	v_exp_f32_e32 v16, v16
	s_nop 0
	v_add_f32_e32 v16, 1.0, v16
	v_rcp_f32_e32 v17, v16
	s_nop 0
	v_mul_f32_e32 v3, v3, v17
	v_mul_f32_e32 v3, v15, v3
	v_cvt_pk_bf16_f32 v3, v3, v3
	ds_write_b16 v1, v3 offset:2368
	ds_read_u16 v3, v1 offset:2640
	s_waitcnt lgkmcnt(0)
	v_lshlrev_b32_e32 v3, 16, v3
	v_mul_f32_e32 v15, 0xbfb8aa3b, v3
	v_exp_f32_e32 v15, v15
	s_nop 0
	v_add_f32_e32 v15, 1.0, v15
	v_rcp_f32_e32 v16, v15
	s_nop 0
	v_mul_f32_e32 v3, v3, v16
	v_mul_f32_e32 v3, v14, v3
	v_cvt_pk_bf16_f32 v3, v3, v3
	ds_write_b16 v1, v3 offset:2640
	ds_read_u16 v3, v1 offset:2912
	s_waitcnt lgkmcnt(0)
; #define LAS __attribute__((address_space(3)))
; #define LDS_WAIT() asm volatile("s_waitcnt lgkmcnt(0)" ::: "memory")
; DI unsigned cvtpk(float lo, float hi) { f32x2 v = {lo, hi}; bf16x2_t b = __builtin_convertvector(v, bf16x2_t); return __builtin_bit_cast(unsigned, b); }
; DI float bf2f(bf16 b) { return __uint_as_float(((unsigned)b) << 16); }
; DI float siluf_(float x) { return x / (1.f + __expf(-x)); }
; DI void g3_tile_out(bf16* g, const LAS unsigned char* R, int lane) {
;     LDS_WAIT();
; #pragma unroll
;     for (int it = 0; it < 8; ++it) { const int row = 4 * it + (lane >> 4), ch = lane & 15;
;         *(u32x4*)(g + (size_t)row * 512 + ch * 8) = *(const LAS u32x4*)(R + row * G3_PITCH + ch * 16); }
;     LDS_WAIT();
; DI void gla_stage3(const Ctx& c0, int layer, int unit, int cb, LAS unsigned char* lds) {
;     ...
;     for (int vb = 0; vb < 4; ++vb) { const float g = gn[32 * vb + r];
; #pragma unroll
;         for (int rg = 0; rg < 16; ++rg) { LAS bf16* e = (LAS bf16*)(R + (4 * hi) * G3_PITCH + r * 2 + ((rg & 3) + 8 * (rg >> 2)) * G3_PITCH + 64 * vb);
;             const float z = bf2f(*e);
;             *e = (bf16)(cvtpk(o[vb][rg] * rs[rg] * g * siluf_(z), 0.f) & 0xffffu); }
;         asm volatile("" ::: "memory"); }
;     g3_tile_out((bf16*)(c.ws + O_OGLA) + row0 * 512 + h * 128, R, lane);
	v_lshlrev_b32_e32 v3, 16, v3
	v_mul_f32_e32 v14, 0xbfb8aa3b, v3
	v_exp_f32_e32 v14, v14
	s_nop 0
	v_add_f32_e32 v14, 1.0, v14
	v_rcp_f32_e32 v15, v14
	s_nop 0
	v_mul_f32_e32 v3, v3, v15
	v_mul_f32_e32 v3, v13, v3
	v_cvt_pk_bf16_f32 v3, v3, v3
	ds_write_b16 v1, v3 offset:2912
	ds_read_u16 v3, v1 offset:3184
	s_waitcnt lgkmcnt(0)
	v_lshlrev_b32_e32 v3, 16, v3
	v_mul_f32_e32 v13, 0xbfb8aa3b, v3
	v_exp_f32_e32 v13, v13
	s_nop 0
	v_add_f32_e32 v13, 1.0, v13
	v_rcp_f32_e32 v14, v13
	s_nop 0
	v_mul_f32_e32 v3, v3, v14
	v_mul_f32_e32 v3, v12, v3
	v_cvt_pk_bf16_f32 v3, v3, v3
	ds_write_b16 v1, v3 offset:3184
	ds_read_u16 v3, v1 offset:4544
	s_waitcnt lgkmcnt(0)
	v_lshlrev_b32_e32 v3, 16, v3
	v_mul_f32_e32 v12, 0xbfb8aa3b, v3
	v_exp_f32_e32 v12, v12
	s_nop 0
	v_add_f32_e32 v12, 1.0, v12
	v_rcp_f32_e32 v13, v12
	s_nop 0
	v_mul_f32_e32 v3, v3, v13
	v_mul_f32_e32 v3, v11, v3
	v_cvt_pk_bf16_f32 v3, v3, v3
	ds_write_b16 v1, v3 offset:4544
	ds_read_u16 v3, v1 offset:4816
	s_waitcnt lgkmcnt(0)
	v_lshlrev_b32_e32 v3, 16, v3
	v_mul_f32_e32 v11, 0xbfb8aa3b, v3
	v_exp_f32_e32 v11, v11
	s_nop 0
	v_add_f32_e32 v11, 1.0, v11
	v_rcp_f32_e32 v12, v11
	s_nop 0
	v_mul_f32_e32 v3, v3, v12
	v_mul_f32_e32 v3, v10, v3
	v_cvt_pk_bf16_f32 v3, v3, v3
	ds_write_b16 v1, v3 offset:4816
	ds_read_u16 v3, v1 offset:5088
	s_waitcnt lgkmcnt(0)
	v_lshlrev_b32_e32 v3, 16, v3
	v_mul_f32_e32 v10, 0xbfb8aa3b, v3
	v_exp_f32_e32 v10, v10
	s_nop 0
	v_add_f32_e32 v10, 1.0, v10
	v_rcp_f32_e32 v11, v10
	s_nop 0
	v_mul_f32_e32 v3, v3, v11
	v_mul_f32_e32 v3, v9, v3
	v_cvt_pk_bf16_f32 v3, v3, v3
	ds_write_b16 v1, v3 offset:5088
	ds_read_u16 v3, v1 offset:5360
	s_waitcnt lgkmcnt(0)
	v_lshlrev_b32_e32 v3, 16, v3
	v_mul_f32_e32 v9, 0xbfb8aa3b, v3
	v_exp_f32_e32 v9, v9
	s_nop 0
	v_add_f32_e32 v9, 1.0, v9
	v_rcp_f32_e32 v10, v9
	s_nop 0
	v_mul_f32_e32 v3, v3, v10
	v_mul_f32_e32 v3, v8, v3
	v_cvt_pk_bf16_f32 v3, v3, v3
	ds_write_b16 v1, v3 offset:5360
	ds_read_u16 v3, v1 offset:6720
	s_waitcnt lgkmcnt(0)
	v_lshlrev_b32_e32 v3, 16, v3
	v_mul_f32_e32 v8, 0xbfb8aa3b, v3
	v_exp_f32_e32 v8, v8
	s_nop 0
	v_add_f32_e32 v8, 1.0, v8
	v_rcp_f32_e32 v9, v8
	s_nop 0
	v_mul_f32_e32 v3, v3, v9
	v_mul_f32_e32 v3, v7, v3
	v_cvt_pk_bf16_f32 v3, v3, v3
	ds_write_b16 v1, v3 offset:6720
	ds_read_u16 v3, v1 offset:6992
	s_waitcnt lgkmcnt(0)
	v_lshlrev_b32_e32 v3, 16, v3
	v_mul_f32_e32 v7, 0xbfb8aa3b, v3
	v_exp_f32_e32 v7, v7
	s_nop 0
	v_add_f32_e32 v7, 1.0, v7
	v_rcp_f32_e32 v8, v7
	s_nop 0
	v_mul_f32_e32 v3, v3, v8
	v_mul_f32_e32 v3, v6, v3
	v_cvt_pk_bf16_f32 v3, v3, v3
	ds_write_b16 v1, v3 offset:6992
	ds_read_u16 v3, v1 offset:7264
	s_waitcnt lgkmcnt(0)
	v_lshlrev_b32_e32 v3, 16, v3
	v_mul_f32_e32 v6, 0xbfb8aa3b, v3
	v_exp_f32_e32 v6, v6
	s_nop 0
	v_add_f32_e32 v6, 1.0, v6
	v_rcp_f32_e32 v7, v6
	s_nop 0
	v_mul_f32_e32 v3, v3, v7
	v_mul_f32_e32 v3, v5, v3
	v_cvt_pk_bf16_f32 v3, v3, v3
	ds_write_b16 v1, v3 offset:7264
	ds_read_u16 v3, v1 offset:7536
	s_waitcnt lgkmcnt(0)
	v_lshlrev_b32_e32 v3, 16, v3
	v_mul_f32_e32 v4, 0xbfb8aa3b, v3
	v_exp_f32_e32 v4, v4
	s_nop 0
	v_add_f32_e32 v4, 1.0, v4
	v_div_scale_f32 v5, s[0:1], v4, v4, v3
	s_nop 0
	v_rcp_f32_e32 v5, v4
	s_nop 0
	v_mul_f32_e32 v3, v3, v5
	v_mul_f32_e32 v2, v2, v3
	v_cvt_pk_bf16_f32 v2, v2, s0
	ds_write_b16 v1, v2 offset:7536
	s_waitcnt lgkmcnt(0)
	ds_read_b128 v[2:5], v92
	v_lshl_add_u64 v[6:7], v[90:91], 0, s[24:25]
	v_lshl_add_u64 v[8:9], v[6:7], 0, v[66:67]
	s_waitcnt lgkmcnt(0)
	global_store_dwordx4 v[8:9], v[2:5], off
	ds_read_b128 v[2:5], v92 offset:1088
	v_lshl_add_u64 v[8:9], v[6:7], 0, v[68:69]
	s_waitcnt lgkmcnt(0)
	global_store_dwordx4 v[8:9], v[2:5], off
	ds_read_b128 v[2:5], v92 offset:2176
	v_lshl_add_u64 v[8:9], v[6:7], 0, v[70:71]
	s_waitcnt lgkmcnt(0)
	global_store_dwordx4 v[8:9], v[2:5], off
	ds_read_b128 v[2:5], v92 offset:3264
	v_lshl_add_u64 v[8:9], v[6:7], 0, v[72:73]
	s_waitcnt lgkmcnt(0)
	global_store_dwordx4 v[8:9], v[2:5], off
	ds_read_b128 v[2:5], v92 offset:4352
	v_lshl_add_u64 v[8:9], v[6:7], 0, v[74:75]
	s_waitcnt lgkmcnt(0)
	global_store_dwordx4 v[8:9], v[2:5], off
	ds_read_b128 v[2:5], v92 offset:5440
	v_lshl_add_u64 v[8:9], v[6:7], 0, v[76:77]
	s_waitcnt lgkmcnt(0)
	global_store_dwordx4 v[8:9], v[2:5], off
	ds_read_b128 v[2:5], v92 offset:6528
	v_lshl_add_u64 v[8:9], v[6:7], 0, v[78:79]
	v_lshl_add_u64 v[6:7], v[6:7], 0, v[80:81]
	s_waitcnt lgkmcnt(0)
	global_store_dwordx4 v[8:9], v[2:5], off
	ds_read_b128 v[2:5], v92 offset:7616
	s_waitcnt lgkmcnt(0)
	global_store_dwordx4 v[6:7], v[2:5], off
	s_waitcnt lgkmcnt(0)
	s_cbranch_scc1 .LBB0_1216
